# v6 = v4 + accumulator zero-init removed: the first k-step MFMAs of each tile take srcC=0 (scalar flag, rare variant out of line) in all six GEMM loops
# speedup vs baseline: 1.0057x; 1.0057x over previous
; #define PG8_STAGE(bufoff, gbase, voff) do { _Pragma("unroll") for (int _i = 0; _i < 2; ++_i) \
;         __builtin_amdgcn_global_load_lds((const unsigned*)((const char*)(gbase) + (voff)[_i]), (PG8_LAS unsigned*)(lds + (bufoff) + ldsw + _i * 8192), 16, 0, 0); } while (0)
; #define PG8_LDA(dst, b, h) do { _Pragma("unroll") for (int m = 0; m < 4; ++m) _Pragma("unroll") for (int k = 0; k < 2; ++k) dst[m][k] = *(const PG8_LAS bf16x8*)(lds + PG8_SA(b, h) + aoff + m * 2048 + k * 1024); } while (0)
; #define PG8_LDB(dst, b, h) do { _Pragma("unroll") for (int n = 0; n < 2; ++n) _Pragma("unroll") for (int k = 0; k < 2; ++k) dst[n][k] = *(const PG8_LAS bf16x8*)(lds + PG8_SB(b, h) + boff + n * 2048 + k * 1024); } while (0)
; #define PG8_WAIT_V(n) asm volatile("s_waitcnt vmcnt(" #n ")" ::: "memory")
; #define PG8_WAIT_L(n) asm volatile("s_waitcnt lgkmcnt(" #n ")" ::: "memory")
; template <class Epi, class Sched, bool ALIGN_EPI = false>
; __device__ __forceinline__ void gemm_phase8(PG8_LAS unsigned char* lds, const Gemm g, const Sched& S, const Epi& E) {
;     ...
;         const bool has_next = S.next(ui + 1, nxt);
;         const size_t nko = (has_next && nxt.kp > 0) ? (size_t)nxt.kp * g.kpiece : 0;
;         const char* nA = has_next ? (const char*)g.A + (size_t)nxt.pm * tstepA + (size_t)nxt.pn * astep + nko : cA; const char* nB = has_next ? (const char*)g.Bt + (size_t)nxt.pn * tstepB + nko : cB;
;         const int nt = (cur.kp < 0 ? g.K : g.kpiece) / 128;
;         for (int t = 0; t < nt; t += 2) {
;             const bool last = (t == nt - 2);
;             const char* a1 = cA + (size_t)(t + 1) * kstep;
;             const char* a2 = last ? nA : cA + (size_t)(t + 2) * kstep; const char* b2 = last ? nB : cB + (size_t)(t + 2) * kstep;
;             const char* a3 = a2 + kstep; const char* b3 = b2 + kstep;
;             if (last && has_next) S.a_ready(nxt);
;             PG8_LDB(B0, 0, 0); PG8_LDB(B1, 0, 1); PG8_SCHED; PG8_LDA(At, 0, 0); PG8_STAGE(PG8_SA(1, 1), a1 + hstepA, voffA);
;             PG8_WAIT_V(8); PG8_WAIT_L(0); PG8_BAR; PG8_MMA(0, 0, At, B0); PG8_MMA(0, 1, At, B1); PG8_BAR; PG8_SCHED;
;             PG8_LDA(At, 0, 1); PG8_STAGE(PG8_SB(0, 0), b2, voffB); PG8_STAGE(PG8_SB(0, 1), b2 + hstepB, voffB); PG8_STAGE(PG8_SA(0, 0), a2, voffA);
;             PG8_WAIT_V(8); PG8_WAIT_L(0); PG8_BAR; PG8_MMA(1, 0, At, B0); PG8_MMA(1, 1, At, B1); PG8_BAR; PG8_SCHED;
.LBB0_324:
	s_ashr_i32 s15, s14, 31
	s_lshl_b64 s[16:17], s[14:15], 19
	s_add_u32 s16, s28, s16
	s_addc_u32 s17, s29, s17
	s_and_b64 s[18:19], s[2:3], exec
	s_cselect_b32 s15, s17, s23
	s_cselect_b32 s61, s16, s22
	s_ashr_i32 s13, s12, 31
	s_lshl_b64 s[18:19], s[12:13], 19
	s_add_u32 s18, s4, s18
	s_addc_u32 s19, s5, s19
	s_and_b64 s[26:27], s[2:3], exec
	s_cselect_b32 s13, s19, s25
	s_cselect_b32 s62, s18, s24
	s_add_u32 s22, s22, 0x40080
	s_addc_u32 s23, s23, 0
	s_add_u32 s63, s24, 0x100
	s_mov_b32 s100, 1
	s_addc_u32 s64, s25, 0
	s_mov_b32 s65, -2
.LBB0_325:
	ds_read_b128 v[18:21], v191
	ds_read_b128 v[26:29], v191 offset:2048
	ds_read_b128 v[22:25], v192
	ds_read_b128 v[30:33], v192 offset:2048
	ds_read_b128 v[2:5], v193
	ds_read_b128 v[10:13], v193 offset:2048
	ds_read_b128 v[6:9], v194
	ds_read_b128 v[14:17], v194 offset:2048
	s_add_u32 s24, s22, 0xfffc0080
	s_addc_u32 s25, s23, -1
	s_cmp_eq_u32 s65, 12
	s_cselect_b32 s27, s15, s25
	s_cselect_b32 s26, s61, s24
	s_cselect_b32 s25, s13, s64
	s_cselect_b32 s24, s62, s63
	v_lshl_add_u64 v[222:223], s[22:23], 0, v[170:171]
	s_add_i32 m0, s21, 0xc000
	ds_read_b128 v[178:181], v195
	ds_read_b128 v[198:201], v195 offset:2048
	ds_read_b128 v[182:185], v196
	ds_read_b128 v[202:205], v196 offset:2048
	ds_read_b128 v[206:209], v195 offset:4096
	ds_read_b128 v[214:217], v195 offset:6144
	ds_read_b128 v[210:213], v196 offset:4096
	ds_read_b128 v[218:221], v196 offset:6144
	global_load_lds_dwordx4 v[222:223], off
	v_lshl_add_u64 v[222:223], s[22:23], 0, v[172:173]
	s_add_i32 m0, s21, 0xe000
	s_nop 0
	global_load_lds_dwordx4 v[222:223], off
	s_waitcnt vmcnt(8)
	s_waitcnt lgkmcnt(0)
	s_barrier
	s_setprio 1
	s_waitcnt lgkmcnt(0)
	s_cmp_eq_u32 s100, 1
	s_cbranch_scc1 .Lcy0_0f
	v_mfma_scale_f32_16x16x128_f8f6f4 v[158:161], v[18:25], v[178:185], v[158:161], v1, v186 op_sel_hi:[0,0,0]
	v_mfma_scale_f32_16x16x128_f8f6f4 v[150:153], v[26:33], v[178:185], v[150:153], v1, v186 op_sel_hi:[0,0,0]
	v_mfma_scale_f32_16x16x128_f8f6f4 v[142:145], v[18:25], v[198:205], v[142:145], v1, v186 op_sel_hi:[0,0,0]
	v_mfma_scale_f32_16x16x128_f8f6f4 v[134:137], v[26:33], v[198:205], v[134:137], v1, v186 op_sel_hi:[0,0,0]
	v_mfma_scale_f32_16x16x128_f8f6f4 v[126:129], v[18:25], v[206:213], v[126:129], v1, v186 op_sel_hi:[0,0,0]
	v_mfma_scale_f32_16x16x128_f8f6f4 v[118:121], v[26:33], v[206:213], v[118:121], v1, v186 op_sel_hi:[0,0,0]
	v_mfma_scale_f32_16x16x128_f8f6f4 v[110:113], v[18:25], v[214:221], v[110:113], v1, v186 op_sel_hi:[0,0,0]
	v_mfma_scale_f32_16x16x128_f8f6f4 v[102:105], v[26:33], v[214:221], v[102:105], v1, v186 op_sel_hi:[0,0,0]
	s_setprio 0
	s_setprio 1
	v_mfma_scale_f32_16x16x128_f8f6f4 v[154:157], v[2:9], v[178:185], v[154:157], v1, v186 op_sel_hi:[0,0,0]
	v_mfma_scale_f32_16x16x128_f8f6f4 v[146:149], v[10:17], v[178:185], v[146:149], v1, v186 op_sel_hi:[0,0,0]
	v_mfma_scale_f32_16x16x128_f8f6f4 v[138:141], v[2:9], v[198:205], v[138:141], v1, v186 op_sel_hi:[0,0,0]
	v_mfma_scale_f32_16x16x128_f8f6f4 v[130:133], v[10:17], v[198:205], v[130:133], v1, v186 op_sel_hi:[0,0,0]
	v_mfma_scale_f32_16x16x128_f8f6f4 v[122:125], v[2:9], v[206:213], v[122:125], v1, v186 op_sel_hi:[0,0,0]
	v_mfma_scale_f32_16x16x128_f8f6f4 v[114:117], v[10:17], v[206:213], v[114:117], v1, v186 op_sel_hi:[0,0,0]
	v_mfma_scale_f32_16x16x128_f8f6f4 v[106:109], v[2:9], v[214:221], v[106:109], v1, v186 op_sel_hi:[0,0,0]
	v_mfma_scale_f32_16x16x128_f8f6f4 v[98:101], v[10:17], v[214:221], v[98:101], v1, v186 op_sel_hi:[0,0,0]
.Lcy0_0j:
	s_setprio 0
	s_barrier
	s_add_i32 s66, s57, s30
	v_lshl_add_u64 v[178:179], s[24:25], 0, v[164:165]
	s_mov_b32 m0, s66
	ds_read_b128 v[198:201], v195 offset:16384
	ds_read_b128 v[206:209], v195 offset:18432
	ds_read_b128 v[202:205], v196 offset:16384
	ds_read_b128 v[210:213], v196 offset:18432
	ds_read_b128 v[214:217], v195 offset:20480
	ds_read_b128 v[222:225], v195 offset:22528
	ds_read_b128 v[218:221], v196 offset:20480
	ds_read_b128 v[226:229], v196 offset:22528
	global_load_lds_dwordx4 v[178:179], off
	s_add_i32 m0, s66, 0x2000
	s_add_u32 s66, s24, 0x40000
	v_lshl_add_u64 v[180:181], s[24:25], 0, v[168:169]
	s_addc_u32 s67, s25, 0
	s_add_i32 s72, s58, s30
	global_load_lds_dwordx4 v[180:181], off
	v_lshl_add_u64 v[182:183], s[66:67], 0, v[164:165]
	s_mov_b32 m0, s72
	v_lshl_add_u64 v[184:185], s[26:27], 0, v[166:167]
	global_load_lds_dwordx4 v[182:183], off
	v_lshl_add_u64 v[182:183], s[66:67], 0, v[168:169]
	s_add_i32 m0, s72, 0x2000
	s_nop 0
	global_load_lds_dwordx4 v[182:183], off
	v_lshl_add_u64 v[182:183], s[26:27], 0, v[162:163]
	s_mov_b32 m0, s21
	s_nop 0
	global_load_lds_dwordx4 v[182:183], off
	s_mov_b32 m0, s34
	s_nop 0
	global_load_lds_dwordx4 v[184:185], off
	s_waitcnt vmcnt(8)
	s_waitcnt lgkmcnt(0)
	s_barrier
	s_setprio 1
	s_waitcnt lgkmcnt(0)
	s_cmp_eq_u32 s100, 1
	s_cbranch_scc1 .Lcy0_1f
	v_mfma_scale_f32_16x16x128_f8f6f4 v[94:97], v[18:25], v[198:205], v[94:97], v1, v186 op_sel_hi:[0,0,0]
	v_mfma_scale_f32_16x16x128_f8f6f4 v[86:89], v[26:33], v[198:205], v[86:89], v1, v186 op_sel_hi:[0,0,0]
	v_mfma_scale_f32_16x16x128_f8f6f4 v[78:81], v[18:25], v[206:213], v[78:81], v1, v186 op_sel_hi:[0,0,0]
	v_mfma_scale_f32_16x16x128_f8f6f4 v[70:73], v[26:33], v[206:213], v[70:73], v1, v186 op_sel_hi:[0,0,0]
	v_mfma_scale_f32_16x16x128_f8f6f4 v[62:65], v[18:25], v[214:221], v[62:65], v1, v186 op_sel_hi:[0,0,0]
	v_mfma_scale_f32_16x16x128_f8f6f4 v[54:57], v[26:33], v[214:221], v[54:57], v1, v186 op_sel_hi:[0,0,0]
	v_mfma_scale_f32_16x16x128_f8f6f4 v[46:49], v[18:25], v[222:229], v[46:49], v1, v186 op_sel_hi:[0,0,0]
	v_mfma_scale_f32_16x16x128_f8f6f4 v[38:41], v[26:33], v[222:229], v[38:41], v1, v186 op_sel_hi:[0,0,0]
	s_setprio 0
	s_setprio 1
	v_mfma_scale_f32_16x16x128_f8f6f4 v[90:93], v[2:9], v[198:205], v[90:93], v1, v186 op_sel_hi:[0,0,0]
	v_mfma_scale_f32_16x16x128_f8f6f4 v[82:85], v[10:17], v[198:205], v[82:85], v1, v186 op_sel_hi:[0,0,0]
	v_mfma_scale_f32_16x16x128_f8f6f4 v[74:77], v[2:9], v[206:213], v[74:77], v1, v186 op_sel_hi:[0,0,0]
	v_mfma_scale_f32_16x16x128_f8f6f4 v[66:69], v[10:17], v[206:213], v[66:69], v1, v186 op_sel_hi:[0,0,0]
	v_mfma_scale_f32_16x16x128_f8f6f4 v[58:61], v[2:9], v[214:221], v[58:61], v1, v186 op_sel_hi:[0,0,0]
	v_mfma_scale_f32_16x16x128_f8f6f4 v[50:53], v[10:17], v[214:221], v[50:53], v1, v186 op_sel_hi:[0,0,0]
	v_mfma_scale_f32_16x16x128_f8f6f4 v[42:45], v[2:9], v[222:229], v[42:45], v1, v186 op_sel_hi:[0,0,0]
	v_mfma_scale_f32_16x16x128_f8f6f4 v[34:37], v[10:17], v[222:229], v[34:37], v1, v186 op_sel_hi:[0,0,0]
; #define PG8_STAGE(bufoff, gbase, voff) do { _Pragma("unroll") for (int _i = 0; _i < 2; ++_i) \
;         __builtin_amdgcn_global_load_lds((const unsigned*)((const char*)(gbase) + (voff)[_i]), (PG8_LAS unsigned*)(lds + (bufoff) + ldsw + _i * 8192), 16, 0, 0); } while (0)
; #define PG8_LDA(dst, b, h) do { _Pragma("unroll") for (int m = 0; m < 4; ++m) _Pragma("unroll") for (int k = 0; k < 2; ++k) dst[m][k] = *(const PG8_LAS bf16x8*)(lds + PG8_SA(b, h) + aoff + m * 2048 + k * 1024); } while (0)
; #define PG8_LDB(dst, b, h) do { _Pragma("unroll") for (int n = 0; n < 2; ++n) _Pragma("unroll") for (int k = 0; k < 2; ++k) dst[n][k] = *(const PG8_LAS bf16x8*)(lds + PG8_SB(b, h) + boff + n * 2048 + k * 1024); } while (0)
; #define PG8_MMA(ai, bj, At, Bt) do { __builtin_amdgcn_s_setprio(1); _Pragma("unroll") for (int m = 0; m < 4; ++m) _Pragma("unroll") for (int n = 0; n < 2; ++n) _Pragma("unroll") for (int k = 0; k < 2; ++k) \
;         acc[ai][bj][m][n] = __builtin_amdgcn_mfma_f32_16x16x32_bf16(Bt[n][k], At[m][k], acc[ai][bj][m][n], 0, 0, 0); __builtin_amdgcn_s_setprio(0); } while (0)
; #define PG8_WAIT_V(n) asm volatile("s_waitcnt vmcnt(" #n ")" ::: "memory")
; #define PG8_WAIT_L(n) asm volatile("s_waitcnt lgkmcnt(" #n ")" ::: "memory")
; #define PG8_BAR __builtin_amdgcn_s_barrier()
; #define PG8_SCHED __builtin_amdgcn_sched_barrier(0)
; #define PG8_STAGE(bufoff, gbase, voff) do { _Pragma("unroll") for (int _i = 0; _i < 2; ++_i) \
;         __builtin_amdgcn_global_load_lds((const unsigned*)((const char*)(gbase) + (voff)[_i]), (PG8_LAS unsigned*)(lds + (bufoff) + ldsw + _i * 8192), 16, 0, 0); } while (0)
; #define PG8_BAR __builtin_amdgcn_s_barrier()
; template <class Epi, class Sched, bool ALIGN_EPI = false>
; __device__ __forceinline__ void gemm_phase8(PG8_LAS unsigned char* lds, const Gemm g, const Sched& S, const Epi& E) {
;     ...
;             PG8_LDB(B0, 1, 0); PG8_LDB(B1, 1, 1); PG8_SCHED; PG8_LDA(At, 1, 0); PG8_STAGE(PG8_SA(0, 1), a2 + hstepA, voffA);
;             PG8_WAIT_V(8); PG8_WAIT_L(0); PG8_BAR; PG8_MMA(0, 0, At, B0); PG8_MMA(0, 1, At, B1); PG8_BAR; PG8_SCHED;
;             PG8_LDA(At, 1, 1); PG8_STAGE(PG8_SB(1, 0), b3, voffB); PG8_STAGE(PG8_SB(1, 1), b3 + hstepB, voffB); PG8_STAGE(PG8_SA(1, 0), a3, voffA);
;             PG8_WAIT_V(8); PG8_WAIT_L(0); PG8_BAR; PG8_MMA(1, 0, At, B0); PG8_MMA(1, 1, At, B1); PG8_BAR; PG8_SCHED;
;         }
.Lcy0_1j:
	s_setprio 0
	s_barrier
	s_add_i32 s66, 0, 0x18000
	s_add_i32 s67, 0, 0x1c000
	v_add_u32_e32 v6, s66, v187
	v_add_u32_e32 v14, s66, v188
	v_add_u32_e32 v22, s67, v187
	v_add_u32_e32 v30, s67, v188
	ds_read_b128 v[2:5], v6
	ds_read_b128 v[10:13], v6 offset:2048
	ds_read_b128 v[6:9], v14
	ds_read_b128 v[14:17], v14 offset:2048
	ds_read_b128 v[18:21], v22
	ds_read_b128 v[26:29], v22 offset:2048
	ds_read_b128 v[22:25], v30
	ds_read_b128 v[30:33], v30 offset:2048
	s_add_u32 s26, s26, 0x40000
	s_addc_u32 s27, s27, 0
	s_mov_b32 m0, s35
	v_lshl_add_u64 v[230:231], s[26:27], 0, v[162:163]
	ds_read_b128 v[198:201], v195 offset:32768
	ds_read_b128 v[206:209], v195 offset:34816
	ds_read_b128 v[202:205], v196 offset:32768
	ds_read_b128 v[210:213], v196 offset:34816
	ds_read_b128 v[214:217], v195 offset:36864
	ds_read_b128 v[222:225], v195 offset:38912
	ds_read_b128 v[218:221], v196 offset:36864
	ds_read_b128 v[226:229], v196 offset:38912
	global_load_lds_dwordx4 v[230:231], off
	v_lshl_add_u64 v[230:231], s[26:27], 0, v[166:167]
	s_mov_b32 m0, s52
	s_nop 0
	global_load_lds_dwordx4 v[230:231], off
	s_waitcnt vmcnt(8)
	s_waitcnt lgkmcnt(0)
	s_barrier
	s_setprio 1
	s_waitcnt lgkmcnt(0)
	v_mfma_scale_f32_16x16x128_f8f6f4 v[158:161], v[2:9], v[198:205], v[158:161], v1, v186 op_sel_hi:[0,0,0]
	v_mfma_scale_f32_16x16x128_f8f6f4 v[150:153], v[10:17], v[198:205], v[150:153], v1, v186 op_sel_hi:[0,0,0]
	v_mfma_scale_f32_16x16x128_f8f6f4 v[142:145], v[2:9], v[206:213], v[142:145], v1, v186 op_sel_hi:[0,0,0]
	v_mfma_scale_f32_16x16x128_f8f6f4 v[134:137], v[10:17], v[206:213], v[134:137], v1, v186 op_sel_hi:[0,0,0]
	v_mfma_scale_f32_16x16x128_f8f6f4 v[126:129], v[2:9], v[214:221], v[126:129], v1, v186 op_sel_hi:[0,0,0]
	v_mfma_scale_f32_16x16x128_f8f6f4 v[118:121], v[10:17], v[214:221], v[118:121], v1, v186 op_sel_hi:[0,0,0]
	v_mfma_scale_f32_16x16x128_f8f6f4 v[110:113], v[2:9], v[222:229], v[110:113], v1, v186 op_sel_hi:[0,0,0]
	v_mfma_scale_f32_16x16x128_f8f6f4 v[102:105], v[10:17], v[222:229], v[102:105], v1, v186 op_sel_hi:[0,0,0]
	s_setprio 0
	s_setprio 1
	v_mfma_scale_f32_16x16x128_f8f6f4 v[154:157], v[18:25], v[198:205], v[154:157], v1, v186 op_sel_hi:[0,0,0]
	v_mfma_scale_f32_16x16x128_f8f6f4 v[146:149], v[26:33], v[198:205], v[146:149], v1, v186 op_sel_hi:[0,0,0]
	v_mfma_scale_f32_16x16x128_f8f6f4 v[138:141], v[18:25], v[206:213], v[138:141], v1, v186 op_sel_hi:[0,0,0]
	v_mfma_scale_f32_16x16x128_f8f6f4 v[130:133], v[26:33], v[206:213], v[130:133], v1, v186 op_sel_hi:[0,0,0]
	v_mfma_scale_f32_16x16x128_f8f6f4 v[122:125], v[18:25], v[214:221], v[122:125], v1, v186 op_sel_hi:[0,0,0]
	v_mfma_scale_f32_16x16x128_f8f6f4 v[114:117], v[26:33], v[214:221], v[114:117], v1, v186 op_sel_hi:[0,0,0]
	v_mfma_scale_f32_16x16x128_f8f6f4 v[106:109], v[18:25], v[222:229], v[106:109], v1, v186 op_sel_hi:[0,0,0]
	v_mfma_scale_f32_16x16x128_f8f6f4 v[98:101], v[26:33], v[222:229], v[98:101], v1, v186 op_sel_hi:[0,0,0]
	s_setprio 0
	s_barrier
	s_add_i32 s26, s66, s30
	v_lshl_add_u64 v[178:179], v[178:179], 0, s[8:9]
	s_mov_b32 m0, s26
	ds_read_b128 v[198:201], v195 offset:49152
	ds_read_b128 v[206:209], v195 offset:51200
	ds_read_b128 v[202:205], v196 offset:49152
	ds_read_b128 v[210:213], v196 offset:51200
	ds_read_b128 v[214:217], v195 offset:53248
	ds_read_b128 v[222:225], v195 offset:55296
	ds_read_b128 v[218:221], v196 offset:53248
	ds_read_b128 v[226:229], v196 offset:55296
	global_load_lds_dwordx4 v[178:179], off
	s_add_i32 m0, s26, 0x2000
	s_add_u32 s24, s24, 0x40080
	v_lshl_add_u64 v[178:179], v[180:181], 0, s[8:9]
	s_addc_u32 s25, s25, 0
	s_add_i32 s26, s67, s30
	global_load_lds_dwordx4 v[178:179], off
	v_lshl_add_u64 v[178:179], s[24:25], 0, v[164:165]
	s_mov_b32 m0, s26
	s_nop 0
	global_load_lds_dwordx4 v[178:179], off
	v_lshl_add_u64 v[178:179], s[24:25], 0, v[168:169]
	s_add_i32 m0, s26, 0x2000
	s_nop 0
	global_load_lds_dwordx4 v[178:179], off
	v_lshl_add_u64 v[178:179], v[182:183], 0, s[8:9]
	s_mov_b32 m0, s55
	s_nop 0
	global_load_lds_dwordx4 v[178:179], off
	v_lshl_add_u64 v[178:179], v[184:185], 0, s[8:9]
	s_mov_b32 m0, s56
	s_nop 0
	global_load_lds_dwordx4 v[178:179], off
	s_waitcnt vmcnt(8)
	s_waitcnt lgkmcnt(0)
	s_barrier
	s_setprio 1
	s_waitcnt lgkmcnt(0)
	v_mfma_scale_f32_16x16x128_f8f6f4 v[94:97], v[2:9], v[198:205], v[94:97], v1, v186 op_sel_hi:[0,0,0]
	v_mfma_scale_f32_16x16x128_f8f6f4 v[86:89], v[10:17], v[198:205], v[86:89], v1, v186 op_sel_hi:[0,0,0]
	v_mfma_scale_f32_16x16x128_f8f6f4 v[78:81], v[2:9], v[206:213], v[78:81], v1, v186 op_sel_hi:[0,0,0]
	v_mfma_scale_f32_16x16x128_f8f6f4 v[70:73], v[10:17], v[206:213], v[70:73], v1, v186 op_sel_hi:[0,0,0]
	v_mfma_scale_f32_16x16x128_f8f6f4 v[62:65], v[2:9], v[214:221], v[62:65], v1, v186 op_sel_hi:[0,0,0]
	v_mfma_scale_f32_16x16x128_f8f6f4 v[54:57], v[10:17], v[214:221], v[54:57], v1, v186 op_sel_hi:[0,0,0]
	v_mfma_scale_f32_16x16x128_f8f6f4 v[46:49], v[2:9], v[222:229], v[46:49], v1, v186 op_sel_hi:[0,0,0]
	v_mfma_scale_f32_16x16x128_f8f6f4 v[38:41], v[10:17], v[222:229], v[38:41], v1, v186 op_sel_hi:[0,0,0]
	s_setprio 0
	s_setprio 1
	v_mfma_scale_f32_16x16x128_f8f6f4 v[90:93], v[18:25], v[198:205], v[90:93], v1, v186 op_sel_hi:[0,0,0]
	v_mfma_scale_f32_16x16x128_f8f6f4 v[82:85], v[26:33], v[198:205], v[82:85], v1, v186 op_sel_hi:[0,0,0]
	v_mfma_scale_f32_16x16x128_f8f6f4 v[74:77], v[18:25], v[206:213], v[74:77], v1, v186 op_sel_hi:[0,0,0]
	v_mfma_scale_f32_16x16x128_f8f6f4 v[66:69], v[26:33], v[206:213], v[66:69], v1, v186 op_sel_hi:[0,0,0]
	v_mfma_scale_f32_16x16x128_f8f6f4 v[58:61], v[18:25], v[214:221], v[58:61], v1, v186 op_sel_hi:[0,0,0]
	v_mfma_scale_f32_16x16x128_f8f6f4 v[50:53], v[26:33], v[214:221], v[50:53], v1, v186 op_sel_hi:[0,0,0]
	v_mfma_scale_f32_16x16x128_f8f6f4 v[42:45], v[18:25], v[222:229], v[42:45], v1, v186 op_sel_hi:[0,0,0]
	v_mfma_scale_f32_16x16x128_f8f6f4 v[34:37], v[26:33], v[222:229], v[34:37], v1, v186 op_sel_hi:[0,0,0]
	s_setprio 0
	s_barrier
	s_add_i32 s65, s65, 2
	s_add_u32 s22, s22, 0x100
	s_addc_u32 s23, s23, 0
	s_add_u32 s63, s63, 0x100
	s_addc_u32 s64, s64, 0
	s_cmp_gt_u32 s65, 13
	s_cbranch_scc0 .LBB0_325
	s_and_b64 vcc, exec, s[10:11]
	s_cbranch_vccz .LBB0_328
	s_barrier

; #define PG8_STAGE(bufoff, gbase, voff) do { _Pragma("unroll") for (int _i = 0; _i < 2; ++_i) \
;         __builtin_amdgcn_global_load_lds((const unsigned*)((const char*)(gbase) + (voff)[_i]), (PG8_LAS unsigned*)(lds + (bufoff) + ldsw + _i * 8192), 16, 0, 0); } while (0)
; #define PG8_LDA(dst, b, h) do { _Pragma("unroll") for (int m = 0; m < 4; ++m) _Pragma("unroll") for (int k = 0; k < 2; ++k) dst[m][k] = *(const PG8_LAS bf16x8*)(lds + PG8_SA(b, h) + aoff + m * 2048 + k * 1024); } while (0)
; #define PG8_MMA(ai, bj, At, Bt) do { __builtin_amdgcn_s_setprio(1); _Pragma("unroll") for (int m = 0; m < 4; ++m) _Pragma("unroll") for (int n = 0; n < 2; ++n) _Pragma("unroll") for (int k = 0; k < 2; ++k) \
;         acc[ai][bj][m][n] = __builtin_amdgcn_mfma_f32_16x16x32_bf16(Bt[n][k], At[m][k], acc[ai][bj][m][n], 0, 0, 0); __builtin_amdgcn_s_setprio(0); } while (0)
; #define PG8_WAIT_V(n) asm volatile("s_waitcnt vmcnt(" #n ")" ::: "memory")
; #define PG8_WAIT_L(n) asm volatile("s_waitcnt lgkmcnt(" #n ")" ::: "memory")
; #define PG8_BAR __builtin_amdgcn_s_barrier()
; #define PG8_SCHED __builtin_amdgcn_sched_barrier(0)
; #define PG8_STAGE(bufoff, gbase, voff) do { _Pragma("unroll") for (int _i = 0; _i < 2; ++_i) \
;         __builtin_amdgcn_global_load_lds((const unsigned*)((const char*)(gbase) + (voff)[_i]), (PG8_LAS unsigned*)(lds + (bufoff) + ldsw + _i * 8192), 16, 0, 0); } while (0)
; #define PG8_LDA(dst, b, h) do { _Pragma("unroll") for (int m = 0; m < 4; ++m) dst[m] = cat8(*(const PG8_LAS bf16x8*)(lds + PG8_SA(b, h) + aoff + m * 2048), *(const PG8_LAS bf16x8*)(lds + PG8_SA(b, h) + (aoff ^ 16) + m * 2048)); } while (0)
; #define PG8_WAIT_V(n) asm volatile("s_waitcnt vmcnt(" #n ")" ::: "memory")
; #define PG8_WAIT_L(n) asm volatile("s_waitcnt lgkmcnt(" #n ")" ::: "memory")
; template <class Epi, class Sched, bool ALIGN_EPI = false>
; __device__ __forceinline__ void gemm_phase8(PG8_LAS unsigned char* lds, const Gemm g, const Sched& S, const Epi& E) {
;     ...
;             PG8_WAIT_V(8); PG8_WAIT_L(0); PG8_BAR; PG8_MMA(0, 0, At, B0); PG8_MMA(0, 1, At, B1); PG8_BAR; PG8_SCHED;
;             PG8_LDA(At, 0, 1); PG8_STAGE(PG8_SB(0, 0), b2, voffB); PG8_STAGE(PG8_SB(0, 1), b2 + hstepB, voffB); PG8_STAGE(PG8_SA(0, 0), a2, voffA);
;             PG8_WAIT_V(8); PG8_WAIT_L(0); PG8_BAR; PG8_MMA(1, 0, At, B0); PG8_MMA(1, 1, At, B1); PG8_BAR; PG8_SCHED;
.Lcy0_0f:
	v_mfma_scale_f32_16x16x128_f8f6f4 v[158:161], v[18:25], v[178:185], 0, v1, v186 op_sel_hi:[0,0,0]
	v_mfma_scale_f32_16x16x128_f8f6f4 v[150:153], v[26:33], v[178:185], 0, v1, v186 op_sel_hi:[0,0,0]
	v_mfma_scale_f32_16x16x128_f8f6f4 v[142:145], v[18:25], v[198:205], 0, v1, v186 op_sel_hi:[0,0,0]
	v_mfma_scale_f32_16x16x128_f8f6f4 v[134:137], v[26:33], v[198:205], 0, v1, v186 op_sel_hi:[0,0,0]
	v_mfma_scale_f32_16x16x128_f8f6f4 v[126:129], v[18:25], v[206:213], 0, v1, v186 op_sel_hi:[0,0,0]
	v_mfma_scale_f32_16x16x128_f8f6f4 v[118:121], v[26:33], v[206:213], 0, v1, v186 op_sel_hi:[0,0,0]
	v_mfma_scale_f32_16x16x128_f8f6f4 v[110:113], v[18:25], v[214:221], 0, v1, v186 op_sel_hi:[0,0,0]
	v_mfma_scale_f32_16x16x128_f8f6f4 v[102:105], v[26:33], v[214:221], 0, v1, v186 op_sel_hi:[0,0,0]
	s_setprio 0
	s_setprio 1
	v_mfma_scale_f32_16x16x128_f8f6f4 v[154:157], v[2:9], v[178:185], 0, v1, v186 op_sel_hi:[0,0,0]
	v_mfma_scale_f32_16x16x128_f8f6f4 v[146:149], v[10:17], v[178:185], 0, v1, v186 op_sel_hi:[0,0,0]
	v_mfma_scale_f32_16x16x128_f8f6f4 v[138:141], v[2:9], v[198:205], 0, v1, v186 op_sel_hi:[0,0,0]
	v_mfma_scale_f32_16x16x128_f8f6f4 v[130:133], v[10:17], v[198:205], 0, v1, v186 op_sel_hi:[0,0,0]
	v_mfma_scale_f32_16x16x128_f8f6f4 v[122:125], v[2:9], v[206:213], 0, v1, v186 op_sel_hi:[0,0,0]
	v_mfma_scale_f32_16x16x128_f8f6f4 v[114:117], v[10:17], v[206:213], 0, v1, v186 op_sel_hi:[0,0,0]
	v_mfma_scale_f32_16x16x128_f8f6f4 v[106:109], v[2:9], v[214:221], 0, v1, v186 op_sel_hi:[0,0,0]
	v_mfma_scale_f32_16x16x128_f8f6f4 v[98:101], v[10:17], v[214:221], 0, v1, v186 op_sel_hi:[0,0,0]
	s_branch .Lcy0_0j
.Lcy0_1f:
	v_mfma_scale_f32_16x16x128_f8f6f4 v[94:97], v[18:25], v[198:205], 0, v1, v186 op_sel_hi:[0,0,0]
	v_mfma_scale_f32_16x16x128_f8f6f4 v[86:89], v[26:33], v[198:205], 0, v1, v186 op_sel_hi:[0,0,0]
	v_mfma_scale_f32_16x16x128_f8f6f4 v[78:81], v[18:25], v[206:213], 0, v1, v186 op_sel_hi:[0,0,0]
	v_mfma_scale_f32_16x16x128_f8f6f4 v[70:73], v[26:33], v[206:213], 0, v1, v186 op_sel_hi:[0,0,0]
	v_mfma_scale_f32_16x16x128_f8f6f4 v[62:65], v[18:25], v[214:221], 0, v1, v186 op_sel_hi:[0,0,0]
	v_mfma_scale_f32_16x16x128_f8f6f4 v[54:57], v[26:33], v[214:221], 0, v1, v186 op_sel_hi:[0,0,0]
	v_mfma_scale_f32_16x16x128_f8f6f4 v[46:49], v[18:25], v[222:229], 0, v1, v186 op_sel_hi:[0,0,0]
	v_mfma_scale_f32_16x16x128_f8f6f4 v[38:41], v[26:33], v[222:229], 0, v1, v186 op_sel_hi:[0,0,0]
	s_setprio 0
	s_setprio 1
	v_mfma_scale_f32_16x16x128_f8f6f4 v[90:93], v[2:9], v[198:205], 0, v1, v186 op_sel_hi:[0,0,0]
	v_mfma_scale_f32_16x16x128_f8f6f4 v[82:85], v[10:17], v[198:205], 0, v1, v186 op_sel_hi:[0,0,0]
	v_mfma_scale_f32_16x16x128_f8f6f4 v[74:77], v[2:9], v[206:213], 0, v1, v186 op_sel_hi:[0,0,0]
	v_mfma_scale_f32_16x16x128_f8f6f4 v[66:69], v[10:17], v[206:213], 0, v1, v186 op_sel_hi:[0,0,0]
	v_mfma_scale_f32_16x16x128_f8f6f4 v[58:61], v[2:9], v[214:221], 0, v1, v186 op_sel_hi:[0,0,0]
	v_mfma_scale_f32_16x16x128_f8f6f4 v[50:53], v[10:17], v[214:221], 0, v1, v186 op_sel_hi:[0,0,0]
	v_mfma_scale_f32_16x16x128_f8f6f4 v[42:45], v[2:9], v[222:229], 0, v1, v186 op_sel_hi:[0,0,0]
	v_mfma_scale_f32_16x16x128_f8f6f4 v[34:37], v[10:17], v[222:229], 0, v1, v186 op_sel_hi:[0,0,0]
	s_mov_b32 s100, 0
	s_branch .Lcy0_1j

; #define PG8_STAGE(bufoff, gbase, voff) do { _Pragma("unroll") for (int _i = 0; _i < 2; ++_i) \
;         __builtin_amdgcn_global_load_lds((const unsigned*)((const char*)(gbase) + (voff)[_i]), (PG8_LAS unsigned*)(lds + (bufoff) + ldsw + _i * 8192), 16, 0, 0); } while (0)
; #define PG8_LDA(dst, b, h) do { _Pragma("unroll") for (int m = 0; m < 4; ++m) _Pragma("unroll") for (int k = 0; k < 2; ++k) dst[m][k] = *(const PG8_LAS bf16x8*)(lds + PG8_SA(b, h) + aoff + m * 2048 + k * 1024); } while (0)
; #define PG8_LDB(dst, b, h) do { _Pragma("unroll") for (int n = 0; n < 2; ++n) _Pragma("unroll") for (int k = 0; k < 2; ++k) dst[n][k] = *(const PG8_LAS bf16x8*)(lds + PG8_SB(b, h) + boff + n * 2048 + k * 1024); } while (0)
; #define PG8_WAIT_V(n) asm volatile("s_waitcnt vmcnt(" #n ")" ::: "memory")
; #define PG8_WAIT_L(n) asm volatile("s_waitcnt lgkmcnt(" #n ")" ::: "memory")
; template <class Epi, class Sched, bool ALIGN_EPI = false>
; __device__ __forceinline__ void gemm_phase8(PG8_LAS unsigned char* lds, const Gemm g, const Sched& S, const Epi& E) {
;     ...
;         const bool has_next = S.next(ui + 1, nxt);
;         const size_t nko = (has_next && nxt.kp > 0) ? (size_t)nxt.kp * g.kpiece : 0;
;         const char* nA = has_next ? (const char*)g.A + (size_t)nxt.pm * tstepA + (size_t)nxt.pn * astep + nko : cA; const char* nB = has_next ? (const char*)g.Bt + (size_t)nxt.pn * tstepB + nko : cB;
;         const int nt = (cur.kp < 0 ? g.K : g.kpiece) / 128;
;         for (int t = 0; t < nt; t += 2) {
;             const bool last = (t == nt - 2);
;             const char* a1 = cA + (size_t)(t + 1) * kstep;
;             const char* a2 = last ? nA : cA + (size_t)(t + 2) * kstep; const char* b2 = last ? nB : cB + (size_t)(t + 2) * kstep;
;             const char* a3 = a2 + kstep; const char* b3 = b2 + kstep;
;             if (last && has_next) S.a_ready(nxt);
;             PG8_LDB(B0, 0, 0); PG8_LDB(B1, 0, 1); PG8_SCHED; PG8_LDA(At, 0, 0); PG8_STAGE(PG8_SA(1, 1), a1 + hstepA, voffA);
;             PG8_WAIT_V(8); PG8_WAIT_L(0); PG8_BAR; PG8_MMA(0, 0, At, B0); PG8_MMA(0, 1, At, B1); PG8_BAR; PG8_SCHED;
;             PG8_LDA(At, 0, 1); PG8_STAGE(PG8_SB(0, 0), b2, voffB); PG8_STAGE(PG8_SB(0, 1), b2 + hstepB, voffB); PG8_STAGE(PG8_SA(0, 0), a2, voffA);
;             PG8_WAIT_V(8); PG8_WAIT_L(0); PG8_BAR; PG8_MMA(1, 0, At, B0); PG8_MMA(1, 1, At, B1); PG8_BAR; PG8_SCHED;
.LBB0_501:
	s_cmp_gt_i32 s24, -1
	s_cselect_b64 s[26:27], -1, 0
	s_cmp_lt_i32 s24, 0
	s_cselect_b32 s25, 44, 4
	s_add_i32 s81, s25, -2
	s_add_u32 s28, s28, 0xb0080
	s_addc_u32 s29, s29, 0
	s_add_u32 s82, s30, 0x100
	s_mov_b32 s100, 1
	s_mov_b32 s34, 0
	s_addc_u32 s83, s31, 0
.LBB0_502:
	ds_read_b128 v[18:21], v187
	ds_read_b128 v[26:29], v187 offset:2048
	ds_read_b128 v[22:25], v188
	ds_read_b128 v[30:33], v188 offset:2048
	ds_read_b128 v[2:5], v189
	ds_read_b128 v[10:13], v189 offset:2048
	ds_read_b128 v[6:9], v190
	ds_read_b128 v[14:17], v190 offset:2048
	s_add_i32 s84, s34, 2
	s_add_u32 s30, s28, 0xfff50080
	s_addc_u32 s31, s29, -1
	s_cmp_eq_u32 s81, s34
	s_cselect_b32 s34, s20, s30
	s_cselect_b32 s35, s21, s31
	s_cselect_b32 s31, s23, s83
	s_cselect_b32 s30, s22, s82
	v_lshl_add_u64 v[218:219], s[28:29], 0, v[170:171]
	s_add_i32 m0, s54, 0xc000
	ds_read_b128 v[174:177], v191
	ds_read_b128 v[194:197], v191 offset:2048
	ds_read_b128 v[178:181], v192
	ds_read_b128 v[198:201], v192 offset:2048
	ds_read_b128 v[202:205], v191 offset:4096
	ds_read_b128 v[210:213], v191 offset:6144
	ds_read_b128 v[206:209], v192 offset:4096
	ds_read_b128 v[214:217], v192 offset:6144
	global_load_lds_dwordx4 v[218:219], off
	v_lshl_add_u64 v[218:219], s[28:29], 0, v[172:173]
	s_add_i32 m0, s54, 0xe000
	s_nop 0
	global_load_lds_dwordx4 v[218:219], off
	s_waitcnt vmcnt(8)
	s_waitcnt lgkmcnt(0)
	s_barrier
	s_setprio 1
	s_waitcnt lgkmcnt(0)
	s_cmp_eq_u32 s100, 1
	s_cbranch_scc1 .Lcy1_0f
	v_mfma_scale_f32_16x16x128_f8f6f4 v[158:161], v[18:25], v[174:181], v[158:161], v1, v182 op_sel_hi:[0,0,0]
	v_mfma_scale_f32_16x16x128_f8f6f4 v[154:157], v[26:33], v[174:181], v[154:157], v1, v182 op_sel_hi:[0,0,0]
	v_mfma_scale_f32_16x16x128_f8f6f4 v[142:145], v[18:25], v[194:201], v[142:145], v1, v182 op_sel_hi:[0,0,0]
	v_mfma_scale_f32_16x16x128_f8f6f4 v[138:141], v[26:33], v[194:201], v[138:141], v1, v182 op_sel_hi:[0,0,0]
	v_mfma_scale_f32_16x16x128_f8f6f4 v[126:129], v[18:25], v[202:209], v[126:129], v1, v182 op_sel_hi:[0,0,0]
	v_mfma_scale_f32_16x16x128_f8f6f4 v[122:125], v[26:33], v[202:209], v[122:125], v1, v182 op_sel_hi:[0,0,0]
	v_mfma_scale_f32_16x16x128_f8f6f4 v[110:113], v[18:25], v[210:217], v[110:113], v1, v182 op_sel_hi:[0,0,0]
	v_mfma_scale_f32_16x16x128_f8f6f4 v[106:109], v[26:33], v[210:217], v[106:109], v1, v182 op_sel_hi:[0,0,0]
	s_setprio 0
	s_setprio 1
	v_mfma_scale_f32_16x16x128_f8f6f4 v[150:153], v[2:9], v[174:181], v[150:153], v1, v182 op_sel_hi:[0,0,0]
	v_mfma_scale_f32_16x16x128_f8f6f4 v[146:149], v[10:17], v[174:181], v[146:149], v1, v182 op_sel_hi:[0,0,0]
	v_mfma_scale_f32_16x16x128_f8f6f4 v[134:137], v[2:9], v[194:201], v[134:137], v1, v182 op_sel_hi:[0,0,0]
	v_mfma_scale_f32_16x16x128_f8f6f4 v[130:133], v[10:17], v[194:201], v[130:133], v1, v182 op_sel_hi:[0,0,0]
	v_mfma_scale_f32_16x16x128_f8f6f4 v[118:121], v[2:9], v[202:209], v[118:121], v1, v182 op_sel_hi:[0,0,0]
	v_mfma_scale_f32_16x16x128_f8f6f4 v[114:117], v[10:17], v[202:209], v[114:117], v1, v182 op_sel_hi:[0,0,0]
	v_mfma_scale_f32_16x16x128_f8f6f4 v[102:105], v[2:9], v[210:217], v[102:105], v1, v182 op_sel_hi:[0,0,0]
	v_mfma_scale_f32_16x16x128_f8f6f4 v[98:101], v[10:17], v[210:217], v[98:101], v1, v182 op_sel_hi:[0,0,0]
.Lcy1_0j:
	s_setprio 0
	s_barrier
	s_add_i32 s85, s65, s53
	v_lshl_add_u64 v[174:175], s[30:31], 0, v[164:165]
	s_mov_b32 m0, s85
	ds_read_b128 v[194:197], v191 offset:16384
	ds_read_b128 v[202:205], v191 offset:18432
	ds_read_b128 v[198:201], v192 offset:16384
	ds_read_b128 v[206:209], v192 offset:18432
	ds_read_b128 v[210:213], v191 offset:20480
	ds_read_b128 v[218:221], v191 offset:22528
	ds_read_b128 v[214:217], v192 offset:20480
	ds_read_b128 v[222:225], v192 offset:22528
	global_load_lds_dwordx4 v[174:175], off
	s_add_i32 m0, s85, 0x2000
	s_add_u32 s88, s30, 0xb0000
	v_lshl_add_u64 v[176:177], s[30:31], 0, v[168:169]
	s_addc_u32 s89, s31, 0
	s_add_i32 s85, s66, s53
	global_load_lds_dwordx4 v[176:177], off
	v_lshl_add_u64 v[178:179], s[88:89], 0, v[164:165]
	s_mov_b32 m0, s85
	v_lshl_add_u64 v[180:181], s[34:35], 0, v[166:167]
	global_load_lds_dwordx4 v[178:179], off
	v_lshl_add_u64 v[178:179], s[88:89], 0, v[168:169]
	s_add_i32 m0, s85, 0x2000
	s_nop 0
	global_load_lds_dwordx4 v[178:179], off
	v_lshl_add_u64 v[178:179], s[34:35], 0, v[162:163]
	s_mov_b32 m0, s54
	s_nop 0
	global_load_lds_dwordx4 v[178:179], off
	s_mov_b32 m0, s55
	s_nop 0
	global_load_lds_dwordx4 v[180:181], off
	s_waitcnt vmcnt(8)
	s_waitcnt lgkmcnt(0)
	s_barrier
	s_setprio 1
	s_waitcnt lgkmcnt(0)
	s_cmp_eq_u32 s100, 1
	s_cbranch_scc1 .Lcy1_1f
	v_mfma_scale_f32_16x16x128_f8f6f4 v[94:97], v[18:25], v[194:201], v[94:97], v1, v182 op_sel_hi:[0,0,0]
	v_mfma_scale_f32_16x16x128_f8f6f4 v[90:93], v[26:33], v[194:201], v[90:93], v1, v182 op_sel_hi:[0,0,0]
	v_mfma_scale_f32_16x16x128_f8f6f4 v[78:81], v[18:25], v[202:209], v[78:81], v1, v182 op_sel_hi:[0,0,0]
	v_mfma_scale_f32_16x16x128_f8f6f4 v[74:77], v[26:33], v[202:209], v[74:77], v1, v182 op_sel_hi:[0,0,0]
	v_mfma_scale_f32_16x16x128_f8f6f4 v[62:65], v[18:25], v[210:217], v[62:65], v1, v182 op_sel_hi:[0,0,0]
	v_mfma_scale_f32_16x16x128_f8f6f4 v[58:61], v[26:33], v[210:217], v[58:61], v1, v182 op_sel_hi:[0,0,0]
	v_mfma_scale_f32_16x16x128_f8f6f4 v[46:49], v[18:25], v[218:225], v[46:49], v1, v182 op_sel_hi:[0,0,0]
	v_mfma_scale_f32_16x16x128_f8f6f4 v[42:45], v[26:33], v[218:225], v[42:45], v1, v182 op_sel_hi:[0,0,0]
	s_setprio 0
	s_setprio 1
	v_mfma_scale_f32_16x16x128_f8f6f4 v[86:89], v[2:9], v[194:201], v[86:89], v1, v182 op_sel_hi:[0,0,0]
	v_mfma_scale_f32_16x16x128_f8f6f4 v[82:85], v[10:17], v[194:201], v[82:85], v1, v182 op_sel_hi:[0,0,0]
	v_mfma_scale_f32_16x16x128_f8f6f4 v[70:73], v[2:9], v[202:209], v[70:73], v1, v182 op_sel_hi:[0,0,0]
	v_mfma_scale_f32_16x16x128_f8f6f4 v[66:69], v[10:17], v[202:209], v[66:69], v1, v182 op_sel_hi:[0,0,0]
	v_mfma_scale_f32_16x16x128_f8f6f4 v[54:57], v[2:9], v[210:217], v[54:57], v1, v182 op_sel_hi:[0,0,0]
	v_mfma_scale_f32_16x16x128_f8f6f4 v[50:53], v[10:17], v[210:217], v[50:53], v1, v182 op_sel_hi:[0,0,0]
	v_mfma_scale_f32_16x16x128_f8f6f4 v[38:41], v[2:9], v[218:225], v[38:41], v1, v182 op_sel_hi:[0,0,0]
	v_mfma_scale_f32_16x16x128_f8f6f4 v[34:37], v[10:17], v[218:225], v[34:37], v1, v182 op_sel_hi:[0,0,0]
; #define PG8_STAGE(bufoff, gbase, voff) do { _Pragma("unroll") for (int _i = 0; _i < 2; ++_i) \
;         __builtin_amdgcn_global_load_lds((const unsigned*)((const char*)(gbase) + (voff)[_i]), (PG8_LAS unsigned*)(lds + (bufoff) + ldsw + _i * 8192), 16, 0, 0); } while (0)
; #define PG8_LDA(dst, b, h) do { _Pragma("unroll") for (int m = 0; m < 4; ++m) _Pragma("unroll") for (int k = 0; k < 2; ++k) dst[m][k] = *(const PG8_LAS bf16x8*)(lds + PG8_SA(b, h) + aoff + m * 2048 + k * 1024); } while (0)
; #define PG8_LDB(dst, b, h) do { _Pragma("unroll") for (int n = 0; n < 2; ++n) _Pragma("unroll") for (int k = 0; k < 2; ++k) dst[n][k] = *(const PG8_LAS bf16x8*)(lds + PG8_SB(b, h) + boff + n * 2048 + k * 1024); } while (0)
; #define PG8_MMA(ai, bj, At, Bt) do { __builtin_amdgcn_s_setprio(1); _Pragma("unroll") for (int m = 0; m < 4; ++m) _Pragma("unroll") for (int n = 0; n < 2; ++n) _Pragma("unroll") for (int k = 0; k < 2; ++k) \
;         acc[ai][bj][m][n] = __builtin_amdgcn_mfma_f32_16x16x32_bf16(Bt[n][k], At[m][k], acc[ai][bj][m][n], 0, 0, 0); __builtin_amdgcn_s_setprio(0); } while (0)
; #define PG8_WAIT_V(n) asm volatile("s_waitcnt vmcnt(" #n ")" ::: "memory")
; #define PG8_WAIT_L(n) asm volatile("s_waitcnt lgkmcnt(" #n ")" ::: "memory")
; #define PG8_BAR __builtin_amdgcn_s_barrier()
; #define PG8_SCHED __builtin_amdgcn_sched_barrier(0)
; #define PG8_STAGE(bufoff, gbase, voff) do { _Pragma("unroll") for (int _i = 0; _i < 2; ++_i) \
;         __builtin_amdgcn_global_load_lds((const unsigned*)((const char*)(gbase) + (voff)[_i]), (PG8_LAS unsigned*)(lds + (bufoff) + ldsw + _i * 8192), 16, 0, 0); } while (0)
; #define PG8_BAR __builtin_amdgcn_s_barrier()
; template <class Epi, class Sched, bool ALIGN_EPI = false>
; __device__ __forceinline__ void gemm_phase8(PG8_LAS unsigned char* lds, const Gemm g, const Sched& S, const Epi& E) {
;     ...
;             PG8_LDB(B0, 1, 0); PG8_LDB(B1, 1, 1); PG8_SCHED; PG8_LDA(At, 1, 0); PG8_STAGE(PG8_SA(0, 1), a2 + hstepA, voffA);
;             PG8_WAIT_V(8); PG8_WAIT_L(0); PG8_BAR; PG8_MMA(0, 0, At, B0); PG8_MMA(0, 1, At, B1); PG8_BAR; PG8_SCHED;
;             PG8_LDA(At, 1, 1); PG8_STAGE(PG8_SB(1, 0), b3, voffB); PG8_STAGE(PG8_SB(1, 1), b3 + hstepB, voffB); PG8_STAGE(PG8_SA(1, 0), a3, voffA);
;             PG8_WAIT_V(8); PG8_WAIT_L(0); PG8_BAR; PG8_MMA(1, 0, At, B0); PG8_MMA(1, 1, At, B1); PG8_BAR; PG8_SCHED;
;         }
.Lcy1_1j:
	s_setprio 0
	s_barrier
	s_add_i32 s85, 0, 0x18000
	s_add_i32 s88, 0, 0x1c000
	v_add_u32_e32 v6, s85, v184
	v_add_u32_e32 v14, s85, v185
	v_add_u32_e32 v22, s88, v184
	v_add_u32_e32 v30, s88, v185
	ds_read_b128 v[2:5], v6
	ds_read_b128 v[10:13], v6 offset:2048
	ds_read_b128 v[6:9], v14
	ds_read_b128 v[14:17], v14 offset:2048
	ds_read_b128 v[18:21], v22
	ds_read_b128 v[26:29], v22 offset:2048
	ds_read_b128 v[22:25], v30
	ds_read_b128 v[30:33], v30 offset:2048
	s_add_u32 s34, s34, 0xb0000
	s_addc_u32 s35, s35, 0
	s_mov_b32 m0, s56
	v_lshl_add_u64 v[226:227], s[34:35], 0, v[162:163]
	ds_read_b128 v[194:197], v191 offset:32768
	ds_read_b128 v[202:205], v191 offset:34816
	ds_read_b128 v[198:201], v192 offset:32768
	ds_read_b128 v[206:209], v192 offset:34816
	ds_read_b128 v[210:213], v191 offset:36864
	ds_read_b128 v[218:221], v191 offset:38912
	ds_read_b128 v[214:217], v192 offset:36864
	ds_read_b128 v[222:225], v192 offset:38912
	global_load_lds_dwordx4 v[226:227], off
	v_lshl_add_u64 v[226:227], s[34:35], 0, v[166:167]
	s_mov_b32 m0, s57
	s_nop 0
	global_load_lds_dwordx4 v[226:227], off
	s_waitcnt vmcnt(8)
	s_waitcnt lgkmcnt(0)
	s_barrier
	s_setprio 1
	s_waitcnt lgkmcnt(0)
	v_mfma_scale_f32_16x16x128_f8f6f4 v[158:161], v[2:9], v[194:201], v[158:161], v1, v182 op_sel_hi:[0,0,0]
	v_mfma_scale_f32_16x16x128_f8f6f4 v[154:157], v[10:17], v[194:201], v[154:157], v1, v182 op_sel_hi:[0,0,0]
	v_mfma_scale_f32_16x16x128_f8f6f4 v[142:145], v[2:9], v[202:209], v[142:145], v1, v182 op_sel_hi:[0,0,0]
	v_mfma_scale_f32_16x16x128_f8f6f4 v[138:141], v[10:17], v[202:209], v[138:141], v1, v182 op_sel_hi:[0,0,0]
	v_mfma_scale_f32_16x16x128_f8f6f4 v[126:129], v[2:9], v[210:217], v[126:129], v1, v182 op_sel_hi:[0,0,0]
	v_mfma_scale_f32_16x16x128_f8f6f4 v[122:125], v[10:17], v[210:217], v[122:125], v1, v182 op_sel_hi:[0,0,0]
	v_mfma_scale_f32_16x16x128_f8f6f4 v[110:113], v[2:9], v[218:225], v[110:113], v1, v182 op_sel_hi:[0,0,0]
	v_mfma_scale_f32_16x16x128_f8f6f4 v[106:109], v[10:17], v[218:225], v[106:109], v1, v182 op_sel_hi:[0,0,0]
	s_setprio 0
	s_setprio 1
	v_mfma_scale_f32_16x16x128_f8f6f4 v[150:153], v[18:25], v[194:201], v[150:153], v1, v182 op_sel_hi:[0,0,0]
	v_mfma_scale_f32_16x16x128_f8f6f4 v[146:149], v[26:33], v[194:201], v[146:149], v1, v182 op_sel_hi:[0,0,0]
	v_mfma_scale_f32_16x16x128_f8f6f4 v[134:137], v[18:25], v[202:209], v[134:137], v1, v182 op_sel_hi:[0,0,0]
	v_mfma_scale_f32_16x16x128_f8f6f4 v[130:133], v[26:33], v[202:209], v[130:133], v1, v182 op_sel_hi:[0,0,0]
	v_mfma_scale_f32_16x16x128_f8f6f4 v[118:121], v[18:25], v[210:217], v[118:121], v1, v182 op_sel_hi:[0,0,0]
	v_mfma_scale_f32_16x16x128_f8f6f4 v[114:117], v[26:33], v[210:217], v[114:117], v1, v182 op_sel_hi:[0,0,0]
	v_mfma_scale_f32_16x16x128_f8f6f4 v[102:105], v[18:25], v[218:225], v[102:105], v1, v182 op_sel_hi:[0,0,0]
	v_mfma_scale_f32_16x16x128_f8f6f4 v[98:101], v[26:33], v[218:225], v[98:101], v1, v182 op_sel_hi:[0,0,0]
	s_setprio 0
	s_barrier
	s_add_i32 s34, s85, s53
	v_lshl_add_u64 v[174:175], v[174:175], 0, s[12:13]
	s_mov_b32 m0, s34
	ds_read_b128 v[194:197], v191 offset:49152
	ds_read_b128 v[202:205], v191 offset:51200
	ds_read_b128 v[198:201], v192 offset:49152
	ds_read_b128 v[206:209], v192 offset:51200
	ds_read_b128 v[210:213], v191 offset:53248
	ds_read_b128 v[218:221], v191 offset:55296
	ds_read_b128 v[214:217], v192 offset:53248
	ds_read_b128 v[222:225], v192 offset:55296
	global_load_lds_dwordx4 v[174:175], off
	s_add_i32 m0, s34, 0x2000
	s_add_u32 s30, s30, 0xb0080
	v_lshl_add_u64 v[174:175], v[176:177], 0, s[12:13]
	s_addc_u32 s31, s31, 0
	s_add_i32 s34, s88, s53
	global_load_lds_dwordx4 v[174:175], off
	v_lshl_add_u64 v[174:175], s[30:31], 0, v[164:165]
	s_mov_b32 m0, s34
	s_nop 0
	global_load_lds_dwordx4 v[174:175], off
	v_lshl_add_u64 v[174:175], s[30:31], 0, v[168:169]
	s_add_i32 m0, s34, 0x2000
	s_nop 0
	global_load_lds_dwordx4 v[174:175], off
	v_lshl_add_u64 v[174:175], v[178:179], 0, s[12:13]
	s_mov_b32 m0, s63
	s_nop 0
	global_load_lds_dwordx4 v[174:175], off
	v_lshl_add_u64 v[174:175], v[180:181], 0, s[12:13]
	s_mov_b32 m0, s64
	s_nop 0
	global_load_lds_dwordx4 v[174:175], off
	s_waitcnt vmcnt(8)
	s_waitcnt lgkmcnt(0)
	s_barrier
	s_setprio 1
	s_waitcnt lgkmcnt(0)
	v_mfma_scale_f32_16x16x128_f8f6f4 v[94:97], v[2:9], v[194:201], v[94:97], v1, v182 op_sel_hi:[0,0,0]
	v_mfma_scale_f32_16x16x128_f8f6f4 v[90:93], v[10:17], v[194:201], v[90:93], v1, v182 op_sel_hi:[0,0,0]
	v_mfma_scale_f32_16x16x128_f8f6f4 v[78:81], v[2:9], v[202:209], v[78:81], v1, v182 op_sel_hi:[0,0,0]
	v_mfma_scale_f32_16x16x128_f8f6f4 v[74:77], v[10:17], v[202:209], v[74:77], v1, v182 op_sel_hi:[0,0,0]
	v_mfma_scale_f32_16x16x128_f8f6f4 v[62:65], v[2:9], v[210:217], v[62:65], v1, v182 op_sel_hi:[0,0,0]
	v_mfma_scale_f32_16x16x128_f8f6f4 v[58:61], v[10:17], v[210:217], v[58:61], v1, v182 op_sel_hi:[0,0,0]
	v_mfma_scale_f32_16x16x128_f8f6f4 v[46:49], v[2:9], v[218:225], v[46:49], v1, v182 op_sel_hi:[0,0,0]
	v_mfma_scale_f32_16x16x128_f8f6f4 v[42:45], v[10:17], v[218:225], v[42:45], v1, v182 op_sel_hi:[0,0,0]
	s_setprio 0
	s_setprio 1
	v_mfma_scale_f32_16x16x128_f8f6f4 v[86:89], v[18:25], v[194:201], v[86:89], v1, v182 op_sel_hi:[0,0,0]
	v_mfma_scale_f32_16x16x128_f8f6f4 v[82:85], v[26:33], v[194:201], v[82:85], v1, v182 op_sel_hi:[0,0,0]
	v_mfma_scale_f32_16x16x128_f8f6f4 v[70:73], v[18:25], v[202:209], v[70:73], v1, v182 op_sel_hi:[0,0,0]
	v_mfma_scale_f32_16x16x128_f8f6f4 v[66:69], v[26:33], v[202:209], v[66:69], v1, v182 op_sel_hi:[0,0,0]
	v_mfma_scale_f32_16x16x128_f8f6f4 v[54:57], v[18:25], v[210:217], v[54:57], v1, v182 op_sel_hi:[0,0,0]
	v_mfma_scale_f32_16x16x128_f8f6f4 v[50:53], v[26:33], v[210:217], v[50:53], v1, v182 op_sel_hi:[0,0,0]
	v_mfma_scale_f32_16x16x128_f8f6f4 v[38:41], v[18:25], v[218:225], v[38:41], v1, v182 op_sel_hi:[0,0,0]
	v_mfma_scale_f32_16x16x128_f8f6f4 v[34:37], v[26:33], v[218:225], v[34:37], v1, v182 op_sel_hi:[0,0,0]
	s_setprio 0
	s_barrier
	s_add_u32 s28, s28, 0x100
	s_addc_u32 s29, s29, 0
	s_add_u32 s82, s82, 0x100
	s_addc_u32 s83, s83, 0
	s_cmp_ge_u32 s84, s25
	s_mov_b32 s34, s84
	s_cbranch_scc0 .LBB0_502
	s_and_b64 vcc, exec, s[14:15]
	s_cbranch_vccz .LBB0_505
	s_barrier

; #define PG8_STAGE(bufoff, gbase, voff) do { _Pragma("unroll") for (int _i = 0; _i < 2; ++_i) \
;         __builtin_amdgcn_global_load_lds((const unsigned*)((const char*)(gbase) + (voff)[_i]), (PG8_LAS unsigned*)(lds + (bufoff) + ldsw + _i * 8192), 16, 0, 0); } while (0)
; #define PG8_LDA(dst, b, h) do { _Pragma("unroll") for (int m = 0; m < 4; ++m) _Pragma("unroll") for (int k = 0; k < 2; ++k) dst[m][k] = *(const PG8_LAS bf16x8*)(lds + PG8_SA(b, h) + aoff + m * 2048 + k * 1024); } while (0)
; #define PG8_MMA(ai, bj, At, Bt) do { __builtin_amdgcn_s_setprio(1); _Pragma("unroll") for (int m = 0; m < 4; ++m) _Pragma("unroll") for (int n = 0; n < 2; ++n) _Pragma("unroll") for (int k = 0; k < 2; ++k) \
;         acc[ai][bj][m][n] = __builtin_amdgcn_mfma_f32_16x16x32_bf16(Bt[n][k], At[m][k], acc[ai][bj][m][n], 0, 0, 0); __builtin_amdgcn_s_setprio(0); } while (0)
; #define PG8_WAIT_V(n) asm volatile("s_waitcnt vmcnt(" #n ")" ::: "memory")
; #define PG8_WAIT_L(n) asm volatile("s_waitcnt lgkmcnt(" #n ")" ::: "memory")
; #define PG8_BAR __builtin_amdgcn_s_barrier()
; #define PG8_SCHED __builtin_amdgcn_sched_barrier(0)
; #define PG8_STAGE(bufoff, gbase, voff) do { _Pragma("unroll") for (int _i = 0; _i < 2; ++_i) \
;         __builtin_amdgcn_global_load_lds((const unsigned*)((const char*)(gbase) + (voff)[_i]), (PG8_LAS unsigned*)(lds + (bufoff) + ldsw + _i * 8192), 16, 0, 0); } while (0)
; #define PG8_LDA(dst, b, h) do { _Pragma("unroll") for (int m = 0; m < 4; ++m) dst[m] = cat8(*(const PG8_LAS bf16x8*)(lds + PG8_SA(b, h) + aoff + m * 2048), *(const PG8_LAS bf16x8*)(lds + PG8_SA(b, h) + (aoff ^ 16) + m * 2048)); } while (0)
; #define PG8_WAIT_V(n) asm volatile("s_waitcnt vmcnt(" #n ")" ::: "memory")
; #define PG8_WAIT_L(n) asm volatile("s_waitcnt lgkmcnt(" #n ")" ::: "memory")
; template <class Epi, class Sched, bool ALIGN_EPI = false>
; __device__ __forceinline__ void gemm_phase8(PG8_LAS unsigned char* lds, const Gemm g, const Sched& S, const Epi& E) {
;     ...
;             PG8_WAIT_V(8); PG8_WAIT_L(0); PG8_BAR; PG8_MMA(0, 0, At, B0); PG8_MMA(0, 1, At, B1); PG8_BAR; PG8_SCHED;
;             PG8_LDA(At, 0, 1); PG8_STAGE(PG8_SB(0, 0), b2, voffB); PG8_STAGE(PG8_SB(0, 1), b2 + hstepB, voffB); PG8_STAGE(PG8_SA(0, 0), a2, voffA);
;             PG8_WAIT_V(8); PG8_WAIT_L(0); PG8_BAR; PG8_MMA(1, 0, At, B0); PG8_MMA(1, 1, At, B1); PG8_BAR; PG8_SCHED;
.Lcy1_0f:
	v_mfma_scale_f32_16x16x128_f8f6f4 v[158:161], v[18:25], v[174:181], 0, v1, v182 op_sel_hi:[0,0,0]
	v_mfma_scale_f32_16x16x128_f8f6f4 v[154:157], v[26:33], v[174:181], 0, v1, v182 op_sel_hi:[0,0,0]
	v_mfma_scale_f32_16x16x128_f8f6f4 v[142:145], v[18:25], v[194:201], 0, v1, v182 op_sel_hi:[0,0,0]
	v_mfma_scale_f32_16x16x128_f8f6f4 v[138:141], v[26:33], v[194:201], 0, v1, v182 op_sel_hi:[0,0,0]
	v_mfma_scale_f32_16x16x128_f8f6f4 v[126:129], v[18:25], v[202:209], 0, v1, v182 op_sel_hi:[0,0,0]
	v_mfma_scale_f32_16x16x128_f8f6f4 v[122:125], v[26:33], v[202:209], 0, v1, v182 op_sel_hi:[0,0,0]
	v_mfma_scale_f32_16x16x128_f8f6f4 v[110:113], v[18:25], v[210:217], 0, v1, v182 op_sel_hi:[0,0,0]
	v_mfma_scale_f32_16x16x128_f8f6f4 v[106:109], v[26:33], v[210:217], 0, v1, v182 op_sel_hi:[0,0,0]
	s_setprio 0
	s_setprio 1
	v_mfma_scale_f32_16x16x128_f8f6f4 v[150:153], v[2:9], v[174:181], 0, v1, v182 op_sel_hi:[0,0,0]
	v_mfma_scale_f32_16x16x128_f8f6f4 v[146:149], v[10:17], v[174:181], 0, v1, v182 op_sel_hi:[0,0,0]
	v_mfma_scale_f32_16x16x128_f8f6f4 v[134:137], v[2:9], v[194:201], 0, v1, v182 op_sel_hi:[0,0,0]
	v_mfma_scale_f32_16x16x128_f8f6f4 v[130:133], v[10:17], v[194:201], 0, v1, v182 op_sel_hi:[0,0,0]
	v_mfma_scale_f32_16x16x128_f8f6f4 v[118:121], v[2:9], v[202:209], 0, v1, v182 op_sel_hi:[0,0,0]
	v_mfma_scale_f32_16x16x128_f8f6f4 v[114:117], v[10:17], v[202:209], 0, v1, v182 op_sel_hi:[0,0,0]
	v_mfma_scale_f32_16x16x128_f8f6f4 v[102:105], v[2:9], v[210:217], 0, v1, v182 op_sel_hi:[0,0,0]
	v_mfma_scale_f32_16x16x128_f8f6f4 v[98:101], v[10:17], v[210:217], 0, v1, v182 op_sel_hi:[0,0,0]
	s_branch .Lcy1_0j
.Lcy1_1f:
	v_mfma_scale_f32_16x16x128_f8f6f4 v[94:97], v[18:25], v[194:201], 0, v1, v182 op_sel_hi:[0,0,0]
	v_mfma_scale_f32_16x16x128_f8f6f4 v[90:93], v[26:33], v[194:201], 0, v1, v182 op_sel_hi:[0,0,0]
	v_mfma_scale_f32_16x16x128_f8f6f4 v[78:81], v[18:25], v[202:209], 0, v1, v182 op_sel_hi:[0,0,0]
	v_mfma_scale_f32_16x16x128_f8f6f4 v[74:77], v[26:33], v[202:209], 0, v1, v182 op_sel_hi:[0,0,0]
	v_mfma_scale_f32_16x16x128_f8f6f4 v[62:65], v[18:25], v[210:217], 0, v1, v182 op_sel_hi:[0,0,0]
	v_mfma_scale_f32_16x16x128_f8f6f4 v[58:61], v[26:33], v[210:217], 0, v1, v182 op_sel_hi:[0,0,0]
	v_mfma_scale_f32_16x16x128_f8f6f4 v[46:49], v[18:25], v[218:225], 0, v1, v182 op_sel_hi:[0,0,0]
	v_mfma_scale_f32_16x16x128_f8f6f4 v[42:45], v[26:33], v[218:225], 0, v1, v182 op_sel_hi:[0,0,0]
	s_setprio 0
	s_setprio 1
	v_mfma_scale_f32_16x16x128_f8f6f4 v[86:89], v[2:9], v[194:201], 0, v1, v182 op_sel_hi:[0,0,0]
	v_mfma_scale_f32_16x16x128_f8f6f4 v[82:85], v[10:17], v[194:201], 0, v1, v182 op_sel_hi:[0,0,0]
	v_mfma_scale_f32_16x16x128_f8f6f4 v[70:73], v[2:9], v[202:209], 0, v1, v182 op_sel_hi:[0,0,0]
	v_mfma_scale_f32_16x16x128_f8f6f4 v[66:69], v[10:17], v[202:209], 0, v1, v182 op_sel_hi:[0,0,0]
	v_mfma_scale_f32_16x16x128_f8f6f4 v[54:57], v[2:9], v[210:217], 0, v1, v182 op_sel_hi:[0,0,0]
	v_mfma_scale_f32_16x16x128_f8f6f4 v[50:53], v[10:17], v[210:217], 0, v1, v182 op_sel_hi:[0,0,0]
	v_mfma_scale_f32_16x16x128_f8f6f4 v[38:41], v[2:9], v[218:225], 0, v1, v182 op_sel_hi:[0,0,0]
	v_mfma_scale_f32_16x16x128_f8f6f4 v[34:37], v[10:17], v[218:225], 0, v1, v182 op_sel_hi:[0,0,0]
	s_mov_b32 s100, 0
	s_branch .Lcy1_1j

; #define PG8_STAGE(bufoff, gbase, voff) do { _Pragma("unroll") for (int _i = 0; _i < 2; ++_i) \
;         __builtin_amdgcn_global_load_lds((const unsigned*)((const char*)(gbase) + (voff)[_i]), (PG8_LAS unsigned*)(lds + (bufoff) + ldsw + _i * 8192), 16, 0, 0); } while (0)
; #define PG8_LDA(dst, b, h) do { _Pragma("unroll") for (int m = 0; m < 4; ++m) _Pragma("unroll") for (int k = 0; k < 2; ++k) dst[m][k] = *(const PG8_LAS bf16x8*)(lds + PG8_SA(b, h) + aoff + m * 2048 + k * 1024); } while (0)
; #define PG8_LDB(dst, b, h) do { _Pragma("unroll") for (int n = 0; n < 2; ++n) _Pragma("unroll") for (int k = 0; k < 2; ++k) dst[n][k] = *(const PG8_LAS bf16x8*)(lds + PG8_SB(b, h) + boff + n * 2048 + k * 1024); } while (0)
; #define PG8_WAIT_V(n) asm volatile("s_waitcnt vmcnt(" #n ")" ::: "memory")
; #define PG8_BAR __builtin_amdgcn_s_barrier()
; template <class Epi, class Sched, bool ALIGN_EPI = false>
; __device__ __forceinline__ void gemm_phase(PG8_LAS unsigned char* lds, const Gemm g, const Sched& S, const Epi& E) {
;     ...
;     for (;;) {
;         const bool has_next = S.next(ui + 1, nxt);
;         const size_t nko = (has_next && nxt.kp > 0) ? (size_t)nxt.kp * g.kpiece * 2 : 0;
;         const char* nA = has_next ? (const char*)g.A + (size_t)nxt.pm * tstepA + (size_t)nxt.pn * astep + nko : cA; const char* nB = has_next ? (const char*)g.Bt + (size_t)nxt.pn * tstepB + nko : cB;
;         const int nt = (cur.kp < 0 ? g.K : g.kpiece) / BK;
;         for (int t = 0; t < nt; t += 2) {
;             const bool last = (t == nt - 2);
;             const char* a1 = cA + (size_t)(t + 1) * kstep;
;             const char* a2 = last ? nA : cA + (size_t)(t + 2) * kstep; const char* b2 = last ? nB : cB + (size_t)(t + 2) * kstep;
;             const char* a3 = a2 + kstep; const char* b3 = b2 + kstep;
;             if (last && has_next) S.a_ready(nxt);
;             PG8_LDB(B0, 0, 0); PG8_LDB(B1, 0, 1); PG8_SCHED; PG8_LDA(At, 0, 0); PG8_STAGE(PG8_SA(1, 1), a1 + hstepA, voffA);
;             PG8_WAIT_V(8); PG8_WAIT_L(0); PG8_BAR; PG8_MMA(0, 0, At, B0); PG8_MMA(0, 1, At, B1); PG8_BAR; PG8_SCHED;
;             PG8_LDA(At, 0, 1); PG8_STAGE(PG8_SB(0, 0), b2, voffB); PG8_STAGE(PG8_SB(0, 1), b2 + hstepB, voffB); PG8_STAGE(PG8_SA(0, 0), a2, voffA);
;             PG8_WAIT_V(8); PG8_WAIT_L(0); PG8_BAR; PG8_MMA(1, 0, At, B0); PG8_MMA(1, 1, At, B1); PG8_BAR; PG8_SCHED;
.LBB0_733:
	s_ashr_i32 s27, s26, 31
	s_lshl_b64 s[28:29], s[26:27], 20
	s_add_u32 s28, s56, s28
	s_addc_u32 s29, s57, s29
	s_and_b64 s[30:31], s[2:3], exec
	s_cselect_b32 s13, s29, s53
	s_cselect_b32 s27, s28, s52
	s_ashr_i32 s25, s24, 31
	s_lshl_b64 s[30:31], s[24:25], 20
	s_add_u32 s30, s4, s30
	s_addc_u32 s31, s5, s31
	s_and_b64 s[54:55], s[2:3], exec
	s_cselect_b32 s25, s31, s35
	s_cselect_b32 s82, s30, s34
	s_add_u32 s52, s52, 0x80080
	s_addc_u32 s53, s53, 0
	s_add_u32 s83, s34, 0x100
	s_mov_b32 s100, 1
	s_addc_u32 s84, s35, 0
	s_mov_b32 s85, -2
.LBB0_734:
	ds_read_b128 v[130:133], v165
	ds_read_b128 v[134:137], v165 offset:1024
	ds_read_b128 v[158:161], v165 offset:2048
	ds_read_b128 v[170:173], v165 offset:3072
	ds_read_b128 v[174:177], v166
	ds_read_b128 v[178:181], v166 offset:1024
	ds_read_b128 v[182:185], v166 offset:2048
	ds_read_b128 v[186:189], v166 offset:3072
	s_add_u32 s34, s52, 0xfff80080
	s_addc_u32 s35, s53, -1
	s_cmp_eq_u32 s85, 28
	s_cselect_b32 s55, s13, s35
	s_cselect_b32 s54, s27, s34
	s_cselect_b32 s35, s25, s84
	s_cselect_b32 s34, s82, s83
	v_lshl_add_u64 v[162:163], s[52:53], 0, v[150:151]
	s_add_i32 m0, s61, 0xc000
	ds_read_b128 v[190:193], v167
	ds_read_b128 v[194:197], v167 offset:1024
	ds_read_b128 v[198:201], v167 offset:2048
	ds_read_b128 v[202:205], v167 offset:3072
	ds_read_b128 v[206:209], v167 offset:4096
	ds_read_b128 v[210:213], v167 offset:5120
	ds_read_b128 v[214:217], v167 offset:6144
	ds_read_b128 v[218:221], v167 offset:7168
	global_load_lds_dwordx4 v[162:163], off
	v_lshl_add_u64 v[162:163], s[52:53], 0, v[152:153]
	s_add_i32 m0, s61, 0xe000
	s_nop 0
	global_load_lds_dwordx4 v[162:163], off
	s_waitcnt vmcnt(8)
	s_waitcnt lgkmcnt(0)
	s_barrier
	s_waitcnt lgkmcnt(0)
	s_cmp_eq_u32 s100, 1
	s_cbranch_scc1 .Lcy2_0f
	v_mfma_f32_16x16x32_bf16 v[126:129], v[130:133], v[190:193], v[126:129]
	v_mfma_f32_16x16x32_bf16 v[122:125], v[158:161], v[190:193], v[122:125]
	v_mfma_f32_16x16x32_bf16 v[114:117], v[130:133], v[198:201], v[114:117]
	v_mfma_f32_16x16x32_bf16 v[106:109], v[158:161], v[198:201], v[106:109]
	v_mfma_f32_16x16x32_bf16 v[98:101], v[130:133], v[206:209], v[98:101]
	v_mfma_f32_16x16x32_bf16 v[90:93], v[158:161], v[206:209], v[90:93]
	v_mfma_f32_16x16x32_bf16 v[82:85], v[130:133], v[214:217], v[82:85]
	v_mfma_f32_16x16x32_bf16 v[74:77], v[158:161], v[214:217], v[74:77]
	v_mfma_f32_16x16x32_bf16 v[126:129], v[134:137], v[194:197], v[126:129]
	v_mfma_f32_16x16x32_bf16 v[122:125], v[170:173], v[194:197], v[122:125]
	v_mfma_f32_16x16x32_bf16 v[114:117], v[134:137], v[202:205], v[114:117]
	v_mfma_f32_16x16x32_bf16 v[106:109], v[170:173], v[202:205], v[106:109]
	v_mfma_f32_16x16x32_bf16 v[98:101], v[134:137], v[210:213], v[98:101]
	v_mfma_f32_16x16x32_bf16 v[90:93], v[170:173], v[210:213], v[90:93]
	v_mfma_f32_16x16x32_bf16 v[82:85], v[134:137], v[218:221], v[82:85]
	v_mfma_f32_16x16x32_bf16 v[74:77], v[170:173], v[218:221], v[74:77]
	v_mfma_f32_16x16x32_bf16 v[118:121], v[174:177], v[190:193], v[118:121]
	v_mfma_f32_16x16x32_bf16 v[110:113], v[182:185], v[190:193], v[110:113]
	v_mfma_f32_16x16x32_bf16 v[102:105], v[174:177], v[198:201], v[102:105]
	v_mfma_f32_16x16x32_bf16 v[94:97], v[182:185], v[198:201], v[94:97]
	v_mfma_f32_16x16x32_bf16 v[86:89], v[174:177], v[206:209], v[86:89]
	v_mfma_f32_16x16x32_bf16 v[78:81], v[182:185], v[206:209], v[78:81]
	v_mfma_f32_16x16x32_bf16 v[70:73], v[174:177], v[214:217], v[70:73]
	v_mfma_f32_16x16x32_bf16 v[66:69], v[182:185], v[214:217], v[66:69]
	v_mfma_f32_16x16x32_bf16 v[118:121], v[178:181], v[194:197], v[118:121]
	v_mfma_f32_16x16x32_bf16 v[110:113], v[186:189], v[194:197], v[110:113]
	v_mfma_f32_16x16x32_bf16 v[102:105], v[178:181], v[202:205], v[102:105]
	v_mfma_f32_16x16x32_bf16 v[94:97], v[186:189], v[202:205], v[94:97]
	v_mfma_f32_16x16x32_bf16 v[86:89], v[178:181], v[210:213], v[86:89]
	v_mfma_f32_16x16x32_bf16 v[78:81], v[186:189], v[210:213], v[78:81]
	v_mfma_f32_16x16x32_bf16 v[70:73], v[178:181], v[218:221], v[70:73]
	v_mfma_f32_16x16x32_bf16 v[66:69], v[186:189], v[218:221], v[66:69]
.Lcy2_0j:
	s_barrier
	s_add_i32 s88, s72, s58
	v_lshl_add_u64 v[162:163], s[34:35], 0, v[140:141]
	s_mov_b32 m0, s88
	ds_read_b128 v[190:193], v167 offset:16384
	ds_read_b128 v[194:197], v167 offset:17408
	ds_read_b128 v[198:201], v167 offset:18432
	ds_read_b128 v[202:205], v167 offset:19456
	ds_read_b128 v[206:209], v167 offset:20480
	ds_read_b128 v[210:213], v167 offset:21504
	ds_read_b128 v[214:217], v167 offset:22528
	ds_read_b128 v[218:221], v167 offset:23552
	global_load_lds_dwordx4 v[162:163], off
	s_add_i32 m0, s88, 0x2000
	s_add_u32 s88, s34, 0x80000
	v_lshl_add_u64 v[222:223], s[34:35], 0, v[144:145]
	s_addc_u32 s89, s35, 0
	s_add_i32 s90, s73, s58
	global_load_lds_dwordx4 v[222:223], off
	v_lshl_add_u64 v[224:225], s[88:89], 0, v[140:141]
	s_mov_b32 m0, s90
	v_lshl_add_u64 v[226:227], s[54:55], 0, v[142:143]
	global_load_lds_dwordx4 v[224:225], off
	v_lshl_add_u64 v[224:225], s[88:89], 0, v[144:145]
	s_add_i32 m0, s90, 0x2000
	s_nop 0
	global_load_lds_dwordx4 v[224:225], off
	v_lshl_add_u64 v[224:225], s[54:55], 0, v[138:139]
	s_mov_b32 m0, s61
	s_nop 0
	global_load_lds_dwordx4 v[224:225], off
	s_mov_b32 m0, s62
	s_nop 0
	global_load_lds_dwordx4 v[226:227], off
	s_waitcnt vmcnt(8)
	s_waitcnt lgkmcnt(0)
	s_barrier
	s_waitcnt lgkmcnt(0)
	s_cmp_eq_u32 s100, 1
	s_cbranch_scc1 .Lcy2_1f
; #define PG8_STAGE(bufoff, gbase, voff) do { _Pragma("unroll") for (int _i = 0; _i < 2; ++_i) \
;         __builtin_amdgcn_global_load_lds((const unsigned*)((const char*)(gbase) + (voff)[_i]), (PG8_LAS unsigned*)(lds + (bufoff) + ldsw + _i * 8192), 16, 0, 0); } while (0)
; #define PG8_LDA(dst, b, h) do { _Pragma("unroll") for (int m = 0; m < 4; ++m) _Pragma("unroll") for (int k = 0; k < 2; ++k) dst[m][k] = *(const PG8_LAS bf16x8*)(lds + PG8_SA(b, h) + aoff + m * 2048 + k * 1024); } while (0)
; #define PG8_LDB(dst, b, h) do { _Pragma("unroll") for (int n = 0; n < 2; ++n) _Pragma("unroll") for (int k = 0; k < 2; ++k) dst[n][k] = *(const PG8_LAS bf16x8*)(lds + PG8_SB(b, h) + boff + n * 2048 + k * 1024); } while (0)
; #define PG8_MMA(ai, bj, At, Bt) do { __builtin_amdgcn_s_setprio(1); _Pragma("unroll") for (int m = 0; m < 4; ++m) _Pragma("unroll") for (int n = 0; n < 2; ++n) _Pragma("unroll") for (int k = 0; k < 2; ++k) \
;         acc[ai][bj][m][n] = __builtin_amdgcn_mfma_f32_16x16x32_bf16(Bt[n][k], At[m][k], acc[ai][bj][m][n], 0, 0, 0); __builtin_amdgcn_s_setprio(0); } while (0)
; #define PG8_WAIT_V(n) asm volatile("s_waitcnt vmcnt(" #n ")" ::: "memory")
; #define PG8_WAIT_L(n) asm volatile("s_waitcnt lgkmcnt(" #n ")" ::: "memory")
; #define PG8_BAR __builtin_amdgcn_s_barrier()
; #define PG8_SCHED __builtin_amdgcn_sched_barrier(0)
; #define PG8_STAGE(bufoff, gbase, voff) do { _Pragma("unroll") for (int _i = 0; _i < 2; ++_i) \
;         __builtin_amdgcn_global_load_lds((const unsigned*)((const char*)(gbase) + (voff)[_i]), (PG8_LAS unsigned*)(lds + (bufoff) + ldsw + _i * 8192), 16, 0, 0); } while (0)
; #define PG8_WAIT_V(n) asm volatile("s_waitcnt vmcnt(" #n ")" ::: "memory")
; template <class Epi, class Sched, bool ALIGN_EPI = false>
; __device__ __forceinline__ void gemm_phase(PG8_LAS unsigned char* lds, const Gemm g, const Sched& S, const Epi& E) {
;     ...
;             PG8_WAIT_V(8); PG8_WAIT_L(0); PG8_BAR; PG8_MMA(1, 0, At, B0); PG8_MMA(1, 1, At, B1); PG8_BAR; PG8_SCHED;
;             PG8_LDB(B0, 1, 0); PG8_LDB(B1, 1, 1); PG8_SCHED; PG8_LDA(At, 1, 0); PG8_STAGE(PG8_SA(0, 1), a2 + hstepA, voffA);
;             PG8_WAIT_V(8); PG8_WAIT_L(0); PG8_BAR; PG8_MMA(0, 0, At, B0); PG8_MMA(0, 1, At, B1); PG8_BAR; PG8_SCHED;
;             PG8_LDA(At, 1, 1); PG8_STAGE(PG8_SB(1, 0), b3, voffB); PG8_STAGE(PG8_SB(1, 1), b3 + hstepB, voffB); PG8_STAGE(PG8_SA(1, 0), a3, voffA);
	v_mfma_f32_16x16x32_bf16 v[62:65], v[130:133], v[190:193], v[62:65]
	v_mfma_f32_16x16x32_bf16 v[58:61], v[158:161], v[190:193], v[58:61]
	v_mfma_f32_16x16x32_bf16 v[54:57], v[130:133], v[198:201], v[54:57]
	v_mfma_f32_16x16x32_bf16 v[46:49], v[158:161], v[198:201], v[46:49]
	v_mfma_f32_16x16x32_bf16 v[38:41], v[130:133], v[206:209], v[38:41]
	v_mfma_f32_16x16x32_bf16 v[30:33], v[158:161], v[206:209], v[30:33]
	v_mfma_f32_16x16x32_bf16 v[22:25], v[130:133], v[214:217], v[22:25]
	v_mfma_f32_16x16x32_bf16 v[14:17], v[158:161], v[214:217], v[14:17]
	v_mfma_f32_16x16x32_bf16 v[62:65], v[134:137], v[194:197], v[62:65]
	v_mfma_f32_16x16x32_bf16 v[58:61], v[170:173], v[194:197], v[58:61]
	v_mfma_f32_16x16x32_bf16 v[54:57], v[134:137], v[202:205], v[54:57]
	v_mfma_f32_16x16x32_bf16 v[46:49], v[170:173], v[202:205], v[46:49]
	v_mfma_f32_16x16x32_bf16 v[38:41], v[134:137], v[210:213], v[38:41]
	v_mfma_f32_16x16x32_bf16 v[30:33], v[170:173], v[210:213], v[30:33]
	v_mfma_f32_16x16x32_bf16 v[22:25], v[134:137], v[218:221], v[22:25]
	v_mfma_f32_16x16x32_bf16 v[14:17], v[170:173], v[218:221], v[14:17]
	v_mfma_f32_16x16x32_bf16 v[50:53], v[174:177], v[190:193], v[50:53]
	v_mfma_f32_16x16x32_bf16 v[42:45], v[182:185], v[190:193], v[42:45]
	v_mfma_f32_16x16x32_bf16 v[34:37], v[174:177], v[198:201], v[34:37]
	v_mfma_f32_16x16x32_bf16 v[26:29], v[182:185], v[198:201], v[26:29]
	v_mfma_f32_16x16x32_bf16 v[18:21], v[174:177], v[206:209], v[18:21]
	v_mfma_f32_16x16x32_bf16 v[10:13], v[182:185], v[206:209], v[10:13]
	v_mfma_f32_16x16x32_bf16 v[6:9], v[174:177], v[214:217], v[6:9]
	v_mfma_f32_16x16x32_bf16 v[2:5], v[182:185], v[214:217], v[2:5]
	v_mfma_f32_16x16x32_bf16 v[50:53], v[178:181], v[194:197], v[50:53]
	v_mfma_f32_16x16x32_bf16 v[42:45], v[186:189], v[194:197], v[42:45]
	v_mfma_f32_16x16x32_bf16 v[34:37], v[178:181], v[202:205], v[34:37]
	v_mfma_f32_16x16x32_bf16 v[26:29], v[186:189], v[202:205], v[26:29]
	v_mfma_f32_16x16x32_bf16 v[18:21], v[178:181], v[210:213], v[18:21]
	v_mfma_f32_16x16x32_bf16 v[10:13], v[186:189], v[210:213], v[10:13]
	v_mfma_f32_16x16x32_bf16 v[6:9], v[178:181], v[218:221], v[6:9]
	v_mfma_f32_16x16x32_bf16 v[2:5], v[186:189], v[218:221], v[2:5]
.Lcy2_1j:
	s_barrier
	s_add_i32 s88, 0, 0x18000
	v_add_u32_e32 v146, s88, v164
	s_add_i32 s89, 0, 0x1c000
	ds_read_b128 v[130:133], v146
	ds_read_b128 v[134:137], v146 offset:1024
	ds_read_b128 v[158:161], v146 offset:2048
	ds_read_b128 v[170:173], v146 offset:3072
	v_add_u32_e32 v146, s89, v164
	ds_read_b128 v[174:177], v146
	ds_read_b128 v[178:181], v146 offset:1024
	ds_read_b128 v[182:185], v146 offset:2048
	ds_read_b128 v[186:189], v146 offset:3072
	s_add_u32 s54, s54, 0x80000
	s_addc_u32 s55, s55, 0
	s_mov_b32 m0, s63
	v_lshl_add_u64 v[228:229], s[54:55], 0, v[138:139]
	ds_read_b128 v[190:193], v167 offset:32768
	ds_read_b128 v[194:197], v167 offset:33792
	ds_read_b128 v[198:201], v167 offset:34816
	ds_read_b128 v[202:205], v167 offset:35840
	ds_read_b128 v[206:209], v167 offset:36864
	ds_read_b128 v[210:213], v167 offset:37888
	ds_read_b128 v[214:217], v167 offset:38912
	ds_read_b128 v[218:221], v167 offset:39936
	global_load_lds_dwordx4 v[228:229], off
	v_lshl_add_u64 v[228:229], s[54:55], 0, v[142:143]
	s_mov_b32 m0, s64
	s_nop 0
	global_load_lds_dwordx4 v[228:229], off
	s_waitcnt vmcnt(8)
	s_waitcnt lgkmcnt(0)
	s_barrier
	s_waitcnt lgkmcnt(0)
	v_mfma_f32_16x16x32_bf16 v[126:129], v[130:133], v[190:193], v[126:129]
	v_mfma_f32_16x16x32_bf16 v[122:125], v[158:161], v[190:193], v[122:125]
	v_mfma_f32_16x16x32_bf16 v[114:117], v[130:133], v[198:201], v[114:117]
	v_mfma_f32_16x16x32_bf16 v[106:109], v[158:161], v[198:201], v[106:109]
	v_mfma_f32_16x16x32_bf16 v[98:101], v[130:133], v[206:209], v[98:101]
	v_mfma_f32_16x16x32_bf16 v[90:93], v[158:161], v[206:209], v[90:93]
	v_mfma_f32_16x16x32_bf16 v[82:85], v[130:133], v[214:217], v[82:85]
	v_mfma_f32_16x16x32_bf16 v[74:77], v[158:161], v[214:217], v[74:77]
	v_mfma_f32_16x16x32_bf16 v[126:129], v[134:137], v[194:197], v[126:129]
	v_mfma_f32_16x16x32_bf16 v[122:125], v[170:173], v[194:197], v[122:125]
	v_mfma_f32_16x16x32_bf16 v[114:117], v[134:137], v[202:205], v[114:117]
	v_mfma_f32_16x16x32_bf16 v[106:109], v[170:173], v[202:205], v[106:109]
	v_mfma_f32_16x16x32_bf16 v[98:101], v[134:137], v[210:213], v[98:101]
	v_mfma_f32_16x16x32_bf16 v[90:93], v[170:173], v[210:213], v[90:93]
	v_mfma_f32_16x16x32_bf16 v[82:85], v[134:137], v[218:221], v[82:85]
	v_mfma_f32_16x16x32_bf16 v[74:77], v[170:173], v[218:221], v[74:77]
	v_mfma_f32_16x16x32_bf16 v[118:121], v[174:177], v[190:193], v[118:121]
	v_mfma_f32_16x16x32_bf16 v[110:113], v[182:185], v[190:193], v[110:113]
	v_mfma_f32_16x16x32_bf16 v[102:105], v[174:177], v[198:201], v[102:105]
	v_mfma_f32_16x16x32_bf16 v[94:97], v[182:185], v[198:201], v[94:97]
	v_mfma_f32_16x16x32_bf16 v[86:89], v[174:177], v[206:209], v[86:89]
	v_mfma_f32_16x16x32_bf16 v[78:81], v[182:185], v[206:209], v[78:81]
	v_mfma_f32_16x16x32_bf16 v[70:73], v[174:177], v[214:217], v[70:73]
	v_mfma_f32_16x16x32_bf16 v[66:69], v[182:185], v[214:217], v[66:69]
	v_mfma_f32_16x16x32_bf16 v[118:121], v[178:181], v[194:197], v[118:121]
	v_mfma_f32_16x16x32_bf16 v[110:113], v[186:189], v[194:197], v[110:113]
	v_mfma_f32_16x16x32_bf16 v[102:105], v[178:181], v[202:205], v[102:105]
	v_mfma_f32_16x16x32_bf16 v[94:97], v[186:189], v[202:205], v[94:97]
	v_mfma_f32_16x16x32_bf16 v[86:89], v[178:181], v[210:213], v[86:89]
	v_mfma_f32_16x16x32_bf16 v[78:81], v[186:189], v[210:213], v[78:81]
	v_mfma_f32_16x16x32_bf16 v[70:73], v[178:181], v[218:221], v[70:73]
	v_mfma_f32_16x16x32_bf16 v[66:69], v[186:189], v[218:221], v[66:69]
	s_barrier
; #define PG8_STAGE(bufoff, gbase, voff) do { _Pragma("unroll") for (int _i = 0; _i < 2; ++_i) \
;         __builtin_amdgcn_global_load_lds((const unsigned*)((const char*)(gbase) + (voff)[_i]), (PG8_LAS unsigned*)(lds + (bufoff) + ldsw + _i * 8192), 16, 0, 0); } while (0)
; #define PG8_LDA(dst, b, h) do { _Pragma("unroll") for (int m = 0; m < 4; ++m) _Pragma("unroll") for (int k = 0; k < 2; ++k) dst[m][k] = *(const PG8_LAS bf16x8*)(lds + PG8_SA(b, h) + aoff + m * 2048 + k * 1024); } while (0)
; #define PG8_MMA(ai, bj, At, Bt) do { __builtin_amdgcn_s_setprio(1); _Pragma("unroll") for (int m = 0; m < 4; ++m) _Pragma("unroll") for (int n = 0; n < 2; ++n) _Pragma("unroll") for (int k = 0; k < 2; ++k) \
;         acc[ai][bj][m][n] = __builtin_amdgcn_mfma_f32_16x16x32_bf16(Bt[n][k], At[m][k], acc[ai][bj][m][n], 0, 0, 0); __builtin_amdgcn_s_setprio(0); } while (0)
; #define PG8_WAIT_V(n) asm volatile("s_waitcnt vmcnt(" #n ")" ::: "memory")
; #define PG8_WAIT_L(n) asm volatile("s_waitcnt lgkmcnt(" #n ")" ::: "memory")
; #define PG8_BAR __builtin_amdgcn_s_barrier()
; #define PG8_SCHED __builtin_amdgcn_sched_barrier(0)
; #define PG8_STAGE(bufoff, gbase, voff) do { _Pragma("unroll") for (int _i = 0; _i < 2; ++_i) \
;         __builtin_amdgcn_global_load_lds((const unsigned*)((const char*)(gbase) + (voff)[_i]), (PG8_LAS unsigned*)(lds + (bufoff) + ldsw + _i * 8192), 16, 0, 0); } while (0)
; #define PG8_LDA(dst, b, h) do { _Pragma("unroll") for (int m = 0; m < 4; ++m) dst[m] = cat8(*(const PG8_LAS bf16x8*)(lds + PG8_SA(b, h) + aoff + m * 2048), *(const PG8_LAS bf16x8*)(lds + PG8_SA(b, h) + (aoff ^ 16) + m * 2048)); } while (0)
; #define PG8_WAIT_V(n) asm volatile("s_waitcnt vmcnt(" #n ")" ::: "memory")
; #define PG8_WAIT_L(n) asm volatile("s_waitcnt lgkmcnt(" #n ")" ::: "memory")
; #define PG8_BAR __builtin_amdgcn_s_barrier()
; #define PG8_SCHED __builtin_amdgcn_sched_barrier(0)
; template <class Epi, class Sched, bool ALIGN_EPI = false>
; __device__ __forceinline__ void gemm_phase(PG8_LAS unsigned char* lds, const Gemm g, const Sched& S, const Epi& E) {
;     ...
;             PG8_LDA(At, 1, 1); PG8_STAGE(PG8_SB(1, 0), b3, voffB); PG8_STAGE(PG8_SB(1, 1), b3 + hstepB, voffB); PG8_STAGE(PG8_SA(1, 0), a3, voffA);
;             PG8_WAIT_V(8); PG8_WAIT_L(0); PG8_BAR; PG8_MMA(1, 0, At, B0); PG8_MMA(1, 1, At, B1); PG8_BAR; PG8_SCHED;
;         }
	s_add_i32 s54, s88, s58
	v_lshl_add_u64 v[162:163], v[162:163], 0, s[10:11]
	s_mov_b32 m0, s54
	ds_read_b128 v[190:193], v167 offset:49152
	ds_read_b128 v[194:197], v167 offset:50176
	ds_read_b128 v[198:201], v167 offset:51200
	ds_read_b128 v[202:205], v167 offset:52224
	ds_read_b128 v[206:209], v167 offset:53248
	ds_read_b128 v[210:213], v167 offset:54272
	ds_read_b128 v[214:217], v167 offset:55296
	ds_read_b128 v[218:221], v167 offset:56320
	global_load_lds_dwordx4 v[162:163], off
	s_add_i32 m0, s54, 0x2000
	s_add_u32 s34, s34, 0x80080
	v_lshl_add_u64 v[162:163], v[222:223], 0, s[10:11]
	s_addc_u32 s35, s35, 0
	s_add_i32 s54, s89, s58
	global_load_lds_dwordx4 v[162:163], off
	v_lshl_add_u64 v[162:163], s[34:35], 0, v[140:141]
	s_mov_b32 m0, s54
	s_nop 0
	global_load_lds_dwordx4 v[162:163], off
	v_lshl_add_u64 v[162:163], s[34:35], 0, v[144:145]
	s_add_i32 m0, s54, 0x2000
	s_nop 0
	global_load_lds_dwordx4 v[162:163], off
	v_lshl_add_u64 v[162:163], v[224:225], 0, s[10:11]
	s_mov_b32 m0, s70
	s_nop 0
	global_load_lds_dwordx4 v[162:163], off
	v_lshl_add_u64 v[162:163], v[226:227], 0, s[10:11]
	s_mov_b32 m0, s71
	s_nop 0
	global_load_lds_dwordx4 v[162:163], off
	s_waitcnt vmcnt(8)
	s_waitcnt lgkmcnt(0)
	s_barrier
	s_waitcnt lgkmcnt(0)
	v_mfma_f32_16x16x32_bf16 v[62:65], v[130:133], v[190:193], v[62:65]
	v_mfma_f32_16x16x32_bf16 v[58:61], v[158:161], v[190:193], v[58:61]
	v_mfma_f32_16x16x32_bf16 v[54:57], v[130:133], v[198:201], v[54:57]
	v_mfma_f32_16x16x32_bf16 v[46:49], v[158:161], v[198:201], v[46:49]
	v_mfma_f32_16x16x32_bf16 v[38:41], v[130:133], v[206:209], v[38:41]
	v_mfma_f32_16x16x32_bf16 v[30:33], v[158:161], v[206:209], v[30:33]
	v_mfma_f32_16x16x32_bf16 v[22:25], v[130:133], v[214:217], v[22:25]
	v_mfma_f32_16x16x32_bf16 v[14:17], v[158:161], v[214:217], v[14:17]
	v_mfma_f32_16x16x32_bf16 v[62:65], v[134:137], v[194:197], v[62:65]
	v_mfma_f32_16x16x32_bf16 v[58:61], v[170:173], v[194:197], v[58:61]
	v_mfma_f32_16x16x32_bf16 v[54:57], v[134:137], v[202:205], v[54:57]
	v_mfma_f32_16x16x32_bf16 v[46:49], v[170:173], v[202:205], v[46:49]
	v_mfma_f32_16x16x32_bf16 v[38:41], v[134:137], v[210:213], v[38:41]
	v_mfma_f32_16x16x32_bf16 v[30:33], v[170:173], v[210:213], v[30:33]
	v_mfma_f32_16x16x32_bf16 v[22:25], v[134:137], v[218:221], v[22:25]
	v_mfma_f32_16x16x32_bf16 v[14:17], v[170:173], v[218:221], v[14:17]
	v_mfma_f32_16x16x32_bf16 v[50:53], v[174:177], v[190:193], v[50:53]
	v_mfma_f32_16x16x32_bf16 v[42:45], v[182:185], v[190:193], v[42:45]
	v_mfma_f32_16x16x32_bf16 v[34:37], v[174:177], v[198:201], v[34:37]
	v_mfma_f32_16x16x32_bf16 v[26:29], v[182:185], v[198:201], v[26:29]
	v_mfma_f32_16x16x32_bf16 v[18:21], v[174:177], v[206:209], v[18:21]
	v_mfma_f32_16x16x32_bf16 v[10:13], v[182:185], v[206:209], v[10:13]
	v_mfma_f32_16x16x32_bf16 v[6:9], v[174:177], v[214:217], v[6:9]
	v_mfma_f32_16x16x32_bf16 v[2:5], v[182:185], v[214:217], v[2:5]
	v_mfma_f32_16x16x32_bf16 v[50:53], v[178:181], v[194:197], v[50:53]
	v_mfma_f32_16x16x32_bf16 v[42:45], v[186:189], v[194:197], v[42:45]
	v_mfma_f32_16x16x32_bf16 v[34:37], v[178:181], v[202:205], v[34:37]
	v_mfma_f32_16x16x32_bf16 v[26:29], v[186:189], v[202:205], v[26:29]
	v_mfma_f32_16x16x32_bf16 v[18:21], v[178:181], v[210:213], v[18:21]
	v_mfma_f32_16x16x32_bf16 v[10:13], v[186:189], v[210:213], v[10:13]
	v_mfma_f32_16x16x32_bf16 v[6:9], v[178:181], v[218:221], v[6:9]
	v_mfma_f32_16x16x32_bf16 v[2:5], v[186:189], v[218:221], v[2:5]
	s_barrier
	s_add_i32 s85, s85, 2
	s_add_u32 s52, s52, 0x100
	s_addc_u32 s53, s53, 0
	s_add_u32 s83, s83, 0x100
	s_addc_u32 s84, s84, 0
	s_cmp_gt_u32 s85, 29
	s_cbranch_scc0 .LBB0_734
	s_and_b64 vcc, exec, s[14:15]
	s_cbranch_vccz .LBB0_737
	s_barrier

; #define PG8_STAGE(bufoff, gbase, voff) do { _Pragma("unroll") for (int _i = 0; _i < 2; ++_i) \
;         __builtin_amdgcn_global_load_lds((const unsigned*)((const char*)(gbase) + (voff)[_i]), (PG8_LAS unsigned*)(lds + (bufoff) + ldsw + _i * 8192), 16, 0, 0); } while (0)
; #define PG8_LDA(dst, b, h) do { _Pragma("unroll") for (int m = 0; m < 4; ++m) _Pragma("unroll") for (int k = 0; k < 2; ++k) dst[m][k] = *(const PG8_LAS bf16x8*)(lds + PG8_SA(b, h) + aoff + m * 2048 + k * 1024); } while (0)
; #define PG8_MMA(ai, bj, At, Bt) do { __builtin_amdgcn_s_setprio(1); _Pragma("unroll") for (int m = 0; m < 4; ++m) _Pragma("unroll") for (int n = 0; n < 2; ++n) _Pragma("unroll") for (int k = 0; k < 2; ++k) \
;         acc[ai][bj][m][n] = __builtin_amdgcn_mfma_f32_16x16x32_bf16(Bt[n][k], At[m][k], acc[ai][bj][m][n], 0, 0, 0); __builtin_amdgcn_s_setprio(0); } while (0)
; #define PG8_WAIT_V(n) asm volatile("s_waitcnt vmcnt(" #n ")" ::: "memory")
; #define PG8_WAIT_L(n) asm volatile("s_waitcnt lgkmcnt(" #n ")" ::: "memory")
; #define PG8_BAR __builtin_amdgcn_s_barrier()
; #define PG8_SCHED __builtin_amdgcn_sched_barrier(0)
; #define PG8_STAGE(bufoff, gbase, voff) do { _Pragma("unroll") for (int _i = 0; _i < 2; ++_i) \
;         __builtin_amdgcn_global_load_lds((const unsigned*)((const char*)(gbase) + (voff)[_i]), (PG8_LAS unsigned*)(lds + (bufoff) + ldsw + _i * 8192), 16, 0, 0); } while (0)
; #define PG8_LDA(dst, b, h) do { _Pragma("unroll") for (int m = 0; m < 4; ++m) dst[m] = cat8(*(const PG8_LAS bf16x8*)(lds + PG8_SA(b, h) + aoff + m * 2048), *(const PG8_LAS bf16x8*)(lds + PG8_SA(b, h) + (aoff ^ 16) + m * 2048)); } while (0)
; #define PG8_WAIT_V(n) asm volatile("s_waitcnt vmcnt(" #n ")" ::: "memory")
; #define PG8_WAIT_L(n) asm volatile("s_waitcnt lgkmcnt(" #n ")" ::: "memory")
; template <class Epi, class Sched, bool ALIGN_EPI = false>
; __device__ __forceinline__ void gemm_phase(PG8_LAS unsigned char* lds, const Gemm g, const Sched& S, const Epi& E) {
;     ...
;             PG8_WAIT_V(8); PG8_WAIT_L(0); PG8_BAR; PG8_MMA(0, 0, At, B0); PG8_MMA(0, 1, At, B1); PG8_BAR; PG8_SCHED;
;             PG8_LDA(At, 0, 1); PG8_STAGE(PG8_SB(0, 0), b2, voffB); PG8_STAGE(PG8_SB(0, 1), b2 + hstepB, voffB); PG8_STAGE(PG8_SA(0, 0), a2, voffA);
;             PG8_WAIT_V(8); PG8_WAIT_L(0); PG8_BAR; PG8_MMA(1, 0, At, B0); PG8_MMA(1, 1, At, B1); PG8_BAR; PG8_SCHED;
.Lcy2_0f:
	v_mfma_f32_16x16x32_bf16 v[126:129], v[130:133], v[190:193], 0
	v_mfma_f32_16x16x32_bf16 v[122:125], v[158:161], v[190:193], 0
	v_mfma_f32_16x16x32_bf16 v[114:117], v[130:133], v[198:201], 0
	v_mfma_f32_16x16x32_bf16 v[106:109], v[158:161], v[198:201], 0
	v_mfma_f32_16x16x32_bf16 v[98:101], v[130:133], v[206:209], 0
	v_mfma_f32_16x16x32_bf16 v[90:93], v[158:161], v[206:209], 0
	v_mfma_f32_16x16x32_bf16 v[82:85], v[130:133], v[214:217], 0
	v_mfma_f32_16x16x32_bf16 v[74:77], v[158:161], v[214:217], 0
	v_mfma_f32_16x16x32_bf16 v[126:129], v[134:137], v[194:197], v[126:129]
	v_mfma_f32_16x16x32_bf16 v[122:125], v[170:173], v[194:197], v[122:125]
	v_mfma_f32_16x16x32_bf16 v[114:117], v[134:137], v[202:205], v[114:117]
	v_mfma_f32_16x16x32_bf16 v[106:109], v[170:173], v[202:205], v[106:109]
	v_mfma_f32_16x16x32_bf16 v[98:101], v[134:137], v[210:213], v[98:101]
	v_mfma_f32_16x16x32_bf16 v[90:93], v[170:173], v[210:213], v[90:93]
	v_mfma_f32_16x16x32_bf16 v[82:85], v[134:137], v[218:221], v[82:85]
	v_mfma_f32_16x16x32_bf16 v[74:77], v[170:173], v[218:221], v[74:77]
	v_mfma_f32_16x16x32_bf16 v[118:121], v[174:177], v[190:193], 0
	v_mfma_f32_16x16x32_bf16 v[110:113], v[182:185], v[190:193], 0
	v_mfma_f32_16x16x32_bf16 v[102:105], v[174:177], v[198:201], 0
	v_mfma_f32_16x16x32_bf16 v[94:97], v[182:185], v[198:201], 0
	v_mfma_f32_16x16x32_bf16 v[86:89], v[174:177], v[206:209], 0
	v_mfma_f32_16x16x32_bf16 v[78:81], v[182:185], v[206:209], 0
	v_mfma_f32_16x16x32_bf16 v[70:73], v[174:177], v[214:217], 0
	v_mfma_f32_16x16x32_bf16 v[66:69], v[182:185], v[214:217], 0
	v_mfma_f32_16x16x32_bf16 v[118:121], v[178:181], v[194:197], v[118:121]
	v_mfma_f32_16x16x32_bf16 v[110:113], v[186:189], v[194:197], v[110:113]
	v_mfma_f32_16x16x32_bf16 v[102:105], v[178:181], v[202:205], v[102:105]
	v_mfma_f32_16x16x32_bf16 v[94:97], v[186:189], v[202:205], v[94:97]
	v_mfma_f32_16x16x32_bf16 v[86:89], v[178:181], v[210:213], v[86:89]
	v_mfma_f32_16x16x32_bf16 v[78:81], v[186:189], v[210:213], v[78:81]
	v_mfma_f32_16x16x32_bf16 v[70:73], v[178:181], v[218:221], v[70:73]
	v_mfma_f32_16x16x32_bf16 v[66:69], v[186:189], v[218:221], v[66:69]
	s_branch .Lcy2_0j
.Lcy2_1f:
	v_mfma_f32_16x16x32_bf16 v[62:65], v[130:133], v[190:193], 0
	v_mfma_f32_16x16x32_bf16 v[58:61], v[158:161], v[190:193], 0
	v_mfma_f32_16x16x32_bf16 v[54:57], v[130:133], v[198:201], 0
	v_mfma_f32_16x16x32_bf16 v[46:49], v[158:161], v[198:201], 0
	v_mfma_f32_16x16x32_bf16 v[38:41], v[130:133], v[206:209], 0
	v_mfma_f32_16x16x32_bf16 v[30:33], v[158:161], v[206:209], 0
	v_mfma_f32_16x16x32_bf16 v[22:25], v[130:133], v[214:217], 0
	v_mfma_f32_16x16x32_bf16 v[14:17], v[158:161], v[214:217], 0
	v_mfma_f32_16x16x32_bf16 v[62:65], v[134:137], v[194:197], v[62:65]
	v_mfma_f32_16x16x32_bf16 v[58:61], v[170:173], v[194:197], v[58:61]
	v_mfma_f32_16x16x32_bf16 v[54:57], v[134:137], v[202:205], v[54:57]
	v_mfma_f32_16x16x32_bf16 v[46:49], v[170:173], v[202:205], v[46:49]
	v_mfma_f32_16x16x32_bf16 v[38:41], v[134:137], v[210:213], v[38:41]
	v_mfma_f32_16x16x32_bf16 v[30:33], v[170:173], v[210:213], v[30:33]
	v_mfma_f32_16x16x32_bf16 v[22:25], v[134:137], v[218:221], v[22:25]
	v_mfma_f32_16x16x32_bf16 v[14:17], v[170:173], v[218:221], v[14:17]
	v_mfma_f32_16x16x32_bf16 v[50:53], v[174:177], v[190:193], 0
	v_mfma_f32_16x16x32_bf16 v[42:45], v[182:185], v[190:193], 0
	v_mfma_f32_16x16x32_bf16 v[34:37], v[174:177], v[198:201], 0
	v_mfma_f32_16x16x32_bf16 v[26:29], v[182:185], v[198:201], 0
	v_mfma_f32_16x16x32_bf16 v[18:21], v[174:177], v[206:209], 0
	v_mfma_f32_16x16x32_bf16 v[10:13], v[182:185], v[206:209], 0
	v_mfma_f32_16x16x32_bf16 v[6:9], v[174:177], v[214:217], 0
	v_mfma_f32_16x16x32_bf16 v[2:5], v[182:185], v[214:217], 0
	v_mfma_f32_16x16x32_bf16 v[50:53], v[178:181], v[194:197], v[50:53]
	v_mfma_f32_16x16x32_bf16 v[42:45], v[186:189], v[194:197], v[42:45]
	v_mfma_f32_16x16x32_bf16 v[34:37], v[178:181], v[202:205], v[34:37]
	v_mfma_f32_16x16x32_bf16 v[26:29], v[186:189], v[202:205], v[26:29]
	v_mfma_f32_16x16x32_bf16 v[18:21], v[178:181], v[210:213], v[18:21]
	v_mfma_f32_16x16x32_bf16 v[10:13], v[186:189], v[210:213], v[10:13]
	v_mfma_f32_16x16x32_bf16 v[6:9], v[178:181], v[218:221], v[6:9]
	v_mfma_f32_16x16x32_bf16 v[2:5], v[186:189], v[218:221], v[2:5]
	s_mov_b32 s100, 0
	s_branch .Lcy2_1j

; #define PG8_STAGE(bufoff, gbase, voff) do { _Pragma("unroll") for (int _i = 0; _i < 2; ++_i) \
;         __builtin_amdgcn_global_load_lds((const unsigned*)((const char*)(gbase) + (voff)[_i]), (PG8_LAS unsigned*)(lds + (bufoff) + ldsw + _i * 8192), 16, 0, 0); } while (0)
; #define PG8_LDA(dst, b, h) do { _Pragma("unroll") for (int m = 0; m < 4; ++m) _Pragma("unroll") for (int k = 0; k < 2; ++k) dst[m][k] = *(const PG8_LAS bf16x8*)(lds + PG8_SA(b, h) + aoff + m * 2048 + k * 1024); } while (0)
; #define PG8_LDB(dst, b, h) do { _Pragma("unroll") for (int n = 0; n < 2; ++n) _Pragma("unroll") for (int k = 0; k < 2; ++k) dst[n][k] = *(const PG8_LAS bf16x8*)(lds + PG8_SB(b, h) + boff + n * 2048 + k * 1024); } while (0)
; #define PG8_WAIT_V(n) asm volatile("s_waitcnt vmcnt(" #n ")" ::: "memory")
; #define PG8_WAIT_L(n) asm volatile("s_waitcnt lgkmcnt(" #n ")" ::: "memory")
; template <class Epi, class Sched, bool ALIGN_EPI = false>
; __device__ __forceinline__ void gemm_phase8(PG8_LAS unsigned char* lds, const Gemm g, const Sched& S, const Epi& E) {
;     ...
;         const bool has_next = S.next(ui + 1, nxt);
;         const size_t nko = (has_next && nxt.kp > 0) ? (size_t)nxt.kp * g.kpiece : 0;
;         const char* nA = has_next ? (const char*)g.A + (size_t)nxt.pm * tstepA + (size_t)nxt.pn * astep + nko : cA; const char* nB = has_next ? (const char*)g.Bt + (size_t)nxt.pn * tstepB + nko : cB;
;         const int nt = (cur.kp < 0 ? g.K : g.kpiece) / 128;
;         for (int t = 0; t < nt; t += 2) {
;             const bool last = (t == nt - 2);
;             const char* a1 = cA + (size_t)(t + 1) * kstep;
;             const char* a2 = last ? nA : cA + (size_t)(t + 2) * kstep; const char* b2 = last ? nB : cB + (size_t)(t + 2) * kstep;
;             const char* a3 = a2 + kstep; const char* b3 = b2 + kstep;
;             if (last && has_next) S.a_ready(nxt);
;             PG8_LDB(B0, 0, 0); PG8_LDB(B1, 0, 1); PG8_SCHED; PG8_LDA(At, 0, 0); PG8_STAGE(PG8_SA(1, 1), a1 + hstepA, voffA);
;             PG8_WAIT_V(8); PG8_WAIT_L(0); PG8_BAR; PG8_MMA(0, 0, At, B0); PG8_MMA(0, 1, At, B1); PG8_BAR; PG8_SCHED;
;             PG8_LDA(At, 0, 1); PG8_STAGE(PG8_SB(0, 0), b2, voffB); PG8_STAGE(PG8_SB(0, 1), b2 + hstepB, voffB); PG8_STAGE(PG8_SA(0, 0), a2, voffA);
;             PG8_WAIT_V(8); PG8_WAIT_L(0); PG8_BAR; PG8_MMA(1, 0, At, B0); PG8_MMA(1, 1, At, B1); PG8_BAR; PG8_SCHED;
.LBB0_1186:
	s_cmp_gt_i32 s0, 0
	s_cselect_b64 s[24:25], -1, 0
	s_and_b64 s[24:25], s[22:23], s[24:25]
	s_lshl_b64 s[26:27], s[0:1], 9
	s_and_b64 s[24:25], s[24:25], exec
	s_cselect_b32 s54, s27, 0
	s_cselect_b32 s55, s26, 0
	s_ashr_i32 s19, s18, 31
	s_lshl_b64 s[24:25], s[18:19], 19
	s_add_u32 s19, s33, s24
	s_addc_u32 s21, s60, s25
	s_add_u32 s24, s19, s55
	s_addc_u32 s25, s21, s54
	s_and_b64 s[26:27], s[22:23], exec
	s_cselect_b32 s19, s25, s57
	s_cselect_b32 s31, s24, s56
	s_ashr_i32 s21, s20, 31
	s_lshl_b64 s[26:27], s[20:21], 19
	s_add_u32 s21, s2, s26
	s_addc_u32 s27, s3, s27
	s_add_u32 s26, s21, s55
	s_addc_u32 s27, s27, s54
	s_and_b64 s[54:55], s[22:23], exec
	s_cselect_b32 s21, s27, s35
	s_cselect_b32 s75, s26, s34
	s_cmp_gt_i32 s30, -1
	s_cselect_b64 s[54:55], -1, 0
	s_cmp_lt_i32 s30, 0
	s_cselect_b32 s76, 16, 4
	s_add_i32 s77, s76, -2
	s_add_u32 s56, s56, 0x40080
	s_addc_u32 s57, s57, 0
	s_add_u32 s78, s34, 0x100
	s_mov_b32 s100, 1
	s_mov_b32 s58, 0
	s_addc_u32 s79, s35, 0
.LBB0_1187:
	ds_read_b128 v[18:21], v187
	ds_read_b128 v[26:29], v187 offset:2048
	ds_read_b128 v[22:25], v188
	ds_read_b128 v[30:33], v188 offset:2048
	ds_read_b128 v[2:5], v189
	ds_read_b128 v[10:13], v189 offset:2048
	ds_read_b128 v[6:9], v190
	ds_read_b128 v[14:17], v190 offset:2048
	s_add_i32 s80, s58, 2
	s_add_u32 s34, s56, 0xfffc0080
	s_addc_u32 s35, s57, -1
	s_cmp_eq_u32 s77, s58
	s_cselect_b32 s58, s31, s34
	s_cselect_b32 s59, s19, s35
	s_cselect_b32 s35, s21, s79
	s_cselect_b32 s34, s75, s78
	v_lshl_add_u64 v[218:219], s[56:57], 0, v[170:171]
	s_add_i32 m0, s29, 0xc000
	ds_read_b128 v[174:177], v191
	ds_read_b128 v[194:197], v191 offset:2048
	ds_read_b128 v[178:181], v192
	ds_read_b128 v[198:201], v192 offset:2048
	ds_read_b128 v[202:205], v191 offset:4096
	ds_read_b128 v[210:213], v191 offset:6144
	ds_read_b128 v[206:209], v192 offset:4096
	ds_read_b128 v[214:217], v192 offset:6144
	global_load_lds_dwordx4 v[218:219], off
	v_lshl_add_u64 v[218:219], s[56:57], 0, v[172:173]
	s_add_i32 m0, s29, 0xe000
	s_nop 0
	global_load_lds_dwordx4 v[218:219], off
	s_waitcnt vmcnt(8)
	s_waitcnt lgkmcnt(0)
	s_barrier
	s_setprio 1
	s_waitcnt lgkmcnt(0)
	s_cmp_eq_u32 s100, 1
	s_cbranch_scc1 .Lcy3_0f
	v_mfma_scale_f32_16x16x128_f8f6f4 v[158:161], v[18:25], v[174:181], v[158:161], v1, v182 op_sel_hi:[0,0,0]
	v_mfma_scale_f32_16x16x128_f8f6f4 v[154:157], v[26:33], v[174:181], v[154:157], v1, v182 op_sel_hi:[0,0,0]
	v_mfma_scale_f32_16x16x128_f8f6f4 v[150:153], v[18:25], v[194:201], v[150:153], v1, v182 op_sel_hi:[0,0,0]
	v_mfma_scale_f32_16x16x128_f8f6f4 v[138:141], v[26:33], v[194:201], v[138:141], v1, v182 op_sel_hi:[0,0,0]
	v_mfma_scale_f32_16x16x128_f8f6f4 v[130:133], v[18:25], v[202:209], v[130:133], v1, v182 op_sel_hi:[0,0,0]
	v_mfma_scale_f32_16x16x128_f8f6f4 v[122:125], v[26:33], v[202:209], v[122:125], v1, v182 op_sel_hi:[0,0,0]
	v_mfma_scale_f32_16x16x128_f8f6f4 v[118:121], v[18:25], v[210:217], v[118:121], v1, v182 op_sel_hi:[0,0,0]
	v_mfma_scale_f32_16x16x128_f8f6f4 v[106:109], v[26:33], v[210:217], v[106:109], v1, v182 op_sel_hi:[0,0,0]
	s_setprio 0
	s_setprio 1
	v_mfma_scale_f32_16x16x128_f8f6f4 v[146:149], v[2:9], v[174:181], v[146:149], v1, v182 op_sel_hi:[0,0,0]
	v_mfma_scale_f32_16x16x128_f8f6f4 v[142:145], v[10:17], v[174:181], v[142:145], v1, v182 op_sel_hi:[0,0,0]
	v_mfma_scale_f32_16x16x128_f8f6f4 v[134:137], v[2:9], v[194:201], v[134:137], v1, v182 op_sel_hi:[0,0,0]
	v_mfma_scale_f32_16x16x128_f8f6f4 v[126:129], v[10:17], v[194:201], v[126:129], v1, v182 op_sel_hi:[0,0,0]
	v_mfma_scale_f32_16x16x128_f8f6f4 v[114:117], v[2:9], v[202:209], v[114:117], v1, v182 op_sel_hi:[0,0,0]
	v_mfma_scale_f32_16x16x128_f8f6f4 v[110:113], v[10:17], v[202:209], v[110:113], v1, v182 op_sel_hi:[0,0,0]
	v_mfma_scale_f32_16x16x128_f8f6f4 v[102:105], v[2:9], v[210:217], v[102:105], v1, v182 op_sel_hi:[0,0,0]
	v_mfma_scale_f32_16x16x128_f8f6f4 v[98:101], v[10:17], v[210:217], v[98:101], v1, v182 op_sel_hi:[0,0,0]
.Lcy3_0j:
	s_setprio 0
	s_barrier
	s_add_i32 s81, s71, s61
	v_lshl_add_u64 v[174:175], s[34:35], 0, v[164:165]
	s_mov_b32 m0, s81
	ds_read_b128 v[194:197], v191 offset:16384
	ds_read_b128 v[202:205], v191 offset:18432
	ds_read_b128 v[198:201], v192 offset:16384
	ds_read_b128 v[206:209], v192 offset:18432
	ds_read_b128 v[210:213], v191 offset:20480
	ds_read_b128 v[218:221], v191 offset:22528
	ds_read_b128 v[214:217], v192 offset:20480
	ds_read_b128 v[222:225], v192 offset:22528
	global_load_lds_dwordx4 v[174:175], off
	s_add_i32 m0, s81, 0x2000
	s_add_u32 s82, s34, 0x40000
	v_lshl_add_u64 v[176:177], s[34:35], 0, v[168:169]
	s_addc_u32 s83, s35, 0
	s_add_i32 s81, s72, s61
	global_load_lds_dwordx4 v[176:177], off
	v_lshl_add_u64 v[178:179], s[82:83], 0, v[164:165]
	s_mov_b32 m0, s81
	v_lshl_add_u64 v[180:181], s[58:59], 0, v[166:167]
	global_load_lds_dwordx4 v[178:179], off
	v_lshl_add_u64 v[178:179], s[82:83], 0, v[168:169]
	s_add_i32 m0, s81, 0x2000
	s_nop 0
	global_load_lds_dwordx4 v[178:179], off
	v_lshl_add_u64 v[178:179], s[58:59], 0, v[162:163]
	s_mov_b32 m0, s29
	s_nop 0
	global_load_lds_dwordx4 v[178:179], off
	s_mov_b32 m0, s53
	s_nop 0
	global_load_lds_dwordx4 v[180:181], off
	s_waitcnt vmcnt(8)
	s_waitcnt lgkmcnt(0)
	s_barrier
	s_setprio 1
	s_waitcnt lgkmcnt(0)
	s_cmp_eq_u32 s100, 1
	s_cbranch_scc1 .Lcy3_1f
	v_mfma_scale_f32_16x16x128_f8f6f4 v[94:97], v[18:25], v[194:201], v[94:97], v1, v182 op_sel_hi:[0,0,0]
	v_mfma_scale_f32_16x16x128_f8f6f4 v[90:93], v[26:33], v[194:201], v[90:93], v1, v182 op_sel_hi:[0,0,0]
	v_mfma_scale_f32_16x16x128_f8f6f4 v[82:85], v[18:25], v[202:209], v[82:85], v1, v182 op_sel_hi:[0,0,0]
	v_mfma_scale_f32_16x16x128_f8f6f4 v[74:77], v[26:33], v[202:209], v[74:77], v1, v182 op_sel_hi:[0,0,0]
	v_mfma_scale_f32_16x16x128_f8f6f4 v[66:69], v[18:25], v[210:217], v[66:69], v1, v182 op_sel_hi:[0,0,0]
	v_mfma_scale_f32_16x16x128_f8f6f4 v[58:61], v[26:33], v[210:217], v[58:61], v1, v182 op_sel_hi:[0,0,0]
	v_mfma_scale_f32_16x16x128_f8f6f4 v[50:53], v[18:25], v[218:225], v[50:53], v1, v182 op_sel_hi:[0,0,0]
	v_mfma_scale_f32_16x16x128_f8f6f4 v[42:45], v[26:33], v[218:225], v[42:45], v1, v182 op_sel_hi:[0,0,0]
	s_setprio 0
	s_setprio 1
	v_mfma_scale_f32_16x16x128_f8f6f4 v[86:89], v[2:9], v[194:201], v[86:89], v1, v182 op_sel_hi:[0,0,0]
	v_mfma_scale_f32_16x16x128_f8f6f4 v[78:81], v[10:17], v[194:201], v[78:81], v1, v182 op_sel_hi:[0,0,0]
	v_mfma_scale_f32_16x16x128_f8f6f4 v[70:73], v[2:9], v[202:209], v[70:73], v1, v182 op_sel_hi:[0,0,0]
	v_mfma_scale_f32_16x16x128_f8f6f4 v[62:65], v[10:17], v[202:209], v[62:65], v1, v182 op_sel_hi:[0,0,0]
	v_mfma_scale_f32_16x16x128_f8f6f4 v[54:57], v[2:9], v[210:217], v[54:57], v1, v182 op_sel_hi:[0,0,0]
	v_mfma_scale_f32_16x16x128_f8f6f4 v[46:49], v[10:17], v[210:217], v[46:49], v1, v182 op_sel_hi:[0,0,0]
	v_mfma_scale_f32_16x16x128_f8f6f4 v[38:41], v[2:9], v[218:225], v[38:41], v1, v182 op_sel_hi:[0,0,0]
	v_mfma_scale_f32_16x16x128_f8f6f4 v[34:37], v[10:17], v[218:225], v[34:37], v1, v182 op_sel_hi:[0,0,0]
; #define PG8_STAGE(bufoff, gbase, voff) do { _Pragma("unroll") for (int _i = 0; _i < 2; ++_i) \
;         __builtin_amdgcn_global_load_lds((const unsigned*)((const char*)(gbase) + (voff)[_i]), (PG8_LAS unsigned*)(lds + (bufoff) + ldsw + _i * 8192), 16, 0, 0); } while (0)
; #define PG8_LDA(dst, b, h) do { _Pragma("unroll") for (int m = 0; m < 4; ++m) _Pragma("unroll") for (int k = 0; k < 2; ++k) dst[m][k] = *(const PG8_LAS bf16x8*)(lds + PG8_SA(b, h) + aoff + m * 2048 + k * 1024); } while (0)
; #define PG8_LDB(dst, b, h) do { _Pragma("unroll") for (int n = 0; n < 2; ++n) _Pragma("unroll") for (int k = 0; k < 2; ++k) dst[n][k] = *(const PG8_LAS bf16x8*)(lds + PG8_SB(b, h) + boff + n * 2048 + k * 1024); } while (0)
; #define PG8_MMA(ai, bj, At, Bt) do { __builtin_amdgcn_s_setprio(1); _Pragma("unroll") for (int m = 0; m < 4; ++m) _Pragma("unroll") for (int n = 0; n < 2; ++n) _Pragma("unroll") for (int k = 0; k < 2; ++k) \
;         acc[ai][bj][m][n] = __builtin_amdgcn_mfma_f32_16x16x32_bf16(Bt[n][k], At[m][k], acc[ai][bj][m][n], 0, 0, 0); __builtin_amdgcn_s_setprio(0); } while (0)
; #define PG8_WAIT_V(n) asm volatile("s_waitcnt vmcnt(" #n ")" ::: "memory")
; #define PG8_WAIT_L(n) asm volatile("s_waitcnt lgkmcnt(" #n ")" ::: "memory")
; #define PG8_BAR __builtin_amdgcn_s_barrier()
; #define PG8_SCHED __builtin_amdgcn_sched_barrier(0)
; #define PG8_STAGE(bufoff, gbase, voff) do { _Pragma("unroll") for (int _i = 0; _i < 2; ++_i) \
;         __builtin_amdgcn_global_load_lds((const unsigned*)((const char*)(gbase) + (voff)[_i]), (PG8_LAS unsigned*)(lds + (bufoff) + ldsw + _i * 8192), 16, 0, 0); } while (0)
; #define PG8_BAR __builtin_amdgcn_s_barrier()
; template <class Epi, class Sched, bool ALIGN_EPI = false>
; __device__ __forceinline__ void gemm_phase8(PG8_LAS unsigned char* lds, const Gemm g, const Sched& S, const Epi& E) {
;     ...
;             PG8_LDB(B0, 1, 0); PG8_LDB(B1, 1, 1); PG8_SCHED; PG8_LDA(At, 1, 0); PG8_STAGE(PG8_SA(0, 1), a2 + hstepA, voffA);
;             PG8_WAIT_V(8); PG8_WAIT_L(0); PG8_BAR; PG8_MMA(0, 0, At, B0); PG8_MMA(0, 1, At, B1); PG8_BAR; PG8_SCHED;
;             PG8_LDA(At, 1, 1); PG8_STAGE(PG8_SB(1, 0), b3, voffB); PG8_STAGE(PG8_SB(1, 1), b3 + hstepB, voffB); PG8_STAGE(PG8_SA(1, 0), a3, voffA);
;             PG8_WAIT_V(8); PG8_WAIT_L(0); PG8_BAR; PG8_MMA(1, 0, At, B0); PG8_MMA(1, 1, At, B1); PG8_BAR; PG8_SCHED;
;         }
.Lcy3_1j:
	s_setprio 0
	s_barrier
	s_add_i32 s81, 0, 0x18000
	s_add_i32 s82, 0, 0x1c000
	v_add_u32_e32 v6, s81, v184
	v_add_u32_e32 v14, s81, v185
	v_add_u32_e32 v22, s82, v184
	v_add_u32_e32 v30, s82, v185
	ds_read_b128 v[2:5], v6
	ds_read_b128 v[10:13], v6 offset:2048
	ds_read_b128 v[6:9], v14
	ds_read_b128 v[14:17], v14 offset:2048
	ds_read_b128 v[18:21], v22
	ds_read_b128 v[26:29], v22 offset:2048
	ds_read_b128 v[22:25], v30
	ds_read_b128 v[30:33], v30 offset:2048
	s_add_u32 s58, s58, 0x40000
	s_addc_u32 s59, s59, 0
	s_mov_b32 m0, s62
	v_lshl_add_u64 v[226:227], s[58:59], 0, v[162:163]
	ds_read_b128 v[194:197], v191 offset:32768
	ds_read_b128 v[202:205], v191 offset:34816
	ds_read_b128 v[198:201], v192 offset:32768
	ds_read_b128 v[206:209], v192 offset:34816
	ds_read_b128 v[210:213], v191 offset:36864
	ds_read_b128 v[218:221], v191 offset:38912
	ds_read_b128 v[214:217], v192 offset:36864
	ds_read_b128 v[222:225], v192 offset:38912
	global_load_lds_dwordx4 v[226:227], off
	v_lshl_add_u64 v[226:227], s[58:59], 0, v[166:167]
	s_mov_b32 m0, s63
	s_nop 0
	global_load_lds_dwordx4 v[226:227], off
	s_waitcnt vmcnt(8)
	s_waitcnt lgkmcnt(0)
	s_barrier
	s_setprio 1
	s_waitcnt lgkmcnt(0)
	v_mfma_scale_f32_16x16x128_f8f6f4 v[158:161], v[2:9], v[194:201], v[158:161], v1, v182 op_sel_hi:[0,0,0]
	v_mfma_scale_f32_16x16x128_f8f6f4 v[154:157], v[10:17], v[194:201], v[154:157], v1, v182 op_sel_hi:[0,0,0]
	v_mfma_scale_f32_16x16x128_f8f6f4 v[150:153], v[2:9], v[202:209], v[150:153], v1, v182 op_sel_hi:[0,0,0]
	v_mfma_scale_f32_16x16x128_f8f6f4 v[138:141], v[10:17], v[202:209], v[138:141], v1, v182 op_sel_hi:[0,0,0]
	v_mfma_scale_f32_16x16x128_f8f6f4 v[130:133], v[2:9], v[210:217], v[130:133], v1, v182 op_sel_hi:[0,0,0]
	v_mfma_scale_f32_16x16x128_f8f6f4 v[122:125], v[10:17], v[210:217], v[122:125], v1, v182 op_sel_hi:[0,0,0]
	v_mfma_scale_f32_16x16x128_f8f6f4 v[118:121], v[2:9], v[218:225], v[118:121], v1, v182 op_sel_hi:[0,0,0]
	v_mfma_scale_f32_16x16x128_f8f6f4 v[106:109], v[10:17], v[218:225], v[106:109], v1, v182 op_sel_hi:[0,0,0]
	s_setprio 0
	s_setprio 1
	v_mfma_scale_f32_16x16x128_f8f6f4 v[146:149], v[18:25], v[194:201], v[146:149], v1, v182 op_sel_hi:[0,0,0]
	v_mfma_scale_f32_16x16x128_f8f6f4 v[142:145], v[26:33], v[194:201], v[142:145], v1, v182 op_sel_hi:[0,0,0]
	v_mfma_scale_f32_16x16x128_f8f6f4 v[134:137], v[18:25], v[202:209], v[134:137], v1, v182 op_sel_hi:[0,0,0]
	v_mfma_scale_f32_16x16x128_f8f6f4 v[126:129], v[26:33], v[202:209], v[126:129], v1, v182 op_sel_hi:[0,0,0]
	v_mfma_scale_f32_16x16x128_f8f6f4 v[114:117], v[18:25], v[210:217], v[114:117], v1, v182 op_sel_hi:[0,0,0]
	v_mfma_scale_f32_16x16x128_f8f6f4 v[110:113], v[26:33], v[210:217], v[110:113], v1, v182 op_sel_hi:[0,0,0]
	v_mfma_scale_f32_16x16x128_f8f6f4 v[102:105], v[18:25], v[218:225], v[102:105], v1, v182 op_sel_hi:[0,0,0]
	v_mfma_scale_f32_16x16x128_f8f6f4 v[98:101], v[26:33], v[218:225], v[98:101], v1, v182 op_sel_hi:[0,0,0]
	s_setprio 0
	s_barrier
	s_add_i32 s58, s81, s61
	v_lshl_add_u64 v[174:175], v[174:175], 0, s[10:11]
	s_mov_b32 m0, s58
	ds_read_b128 v[194:197], v191 offset:49152
	ds_read_b128 v[202:205], v191 offset:51200
	ds_read_b128 v[198:201], v192 offset:49152
	ds_read_b128 v[206:209], v192 offset:51200
	ds_read_b128 v[210:213], v191 offset:53248
	ds_read_b128 v[218:221], v191 offset:55296
	ds_read_b128 v[214:217], v192 offset:53248
	ds_read_b128 v[222:225], v192 offset:55296
	global_load_lds_dwordx4 v[174:175], off
	s_add_i32 m0, s58, 0x2000
	s_add_u32 s34, s34, 0x40080
	v_lshl_add_u64 v[174:175], v[176:177], 0, s[10:11]
	s_addc_u32 s35, s35, 0
	s_add_i32 s58, s82, s61
	global_load_lds_dwordx4 v[174:175], off
	v_lshl_add_u64 v[174:175], s[34:35], 0, v[164:165]
	s_mov_b32 m0, s58
	s_nop 0
	global_load_lds_dwordx4 v[174:175], off
	v_lshl_add_u64 v[174:175], s[34:35], 0, v[168:169]
	s_add_i32 m0, s58, 0x2000
	s_nop 0
	global_load_lds_dwordx4 v[174:175], off
	v_lshl_add_u64 v[174:175], v[178:179], 0, s[10:11]
	s_mov_b32 m0, s69
	s_nop 0
	global_load_lds_dwordx4 v[174:175], off
	v_lshl_add_u64 v[174:175], v[180:181], 0, s[10:11]
	s_mov_b32 m0, s70
	s_nop 0
	global_load_lds_dwordx4 v[174:175], off
	s_waitcnt vmcnt(8)
	s_waitcnt lgkmcnt(0)
	s_barrier
	s_setprio 1
	s_waitcnt lgkmcnt(0)
	v_mfma_scale_f32_16x16x128_f8f6f4 v[94:97], v[2:9], v[194:201], v[94:97], v1, v182 op_sel_hi:[0,0,0]
	v_mfma_scale_f32_16x16x128_f8f6f4 v[90:93], v[10:17], v[194:201], v[90:93], v1, v182 op_sel_hi:[0,0,0]
	v_mfma_scale_f32_16x16x128_f8f6f4 v[82:85], v[2:9], v[202:209], v[82:85], v1, v182 op_sel_hi:[0,0,0]
	v_mfma_scale_f32_16x16x128_f8f6f4 v[74:77], v[10:17], v[202:209], v[74:77], v1, v182 op_sel_hi:[0,0,0]
	v_mfma_scale_f32_16x16x128_f8f6f4 v[66:69], v[2:9], v[210:217], v[66:69], v1, v182 op_sel_hi:[0,0,0]
	v_mfma_scale_f32_16x16x128_f8f6f4 v[58:61], v[10:17], v[210:217], v[58:61], v1, v182 op_sel_hi:[0,0,0]
	v_mfma_scale_f32_16x16x128_f8f6f4 v[50:53], v[2:9], v[218:225], v[50:53], v1, v182 op_sel_hi:[0,0,0]
	v_mfma_scale_f32_16x16x128_f8f6f4 v[42:45], v[10:17], v[218:225], v[42:45], v1, v182 op_sel_hi:[0,0,0]
	s_setprio 0
	s_setprio 1
	v_mfma_scale_f32_16x16x128_f8f6f4 v[86:89], v[18:25], v[194:201], v[86:89], v1, v182 op_sel_hi:[0,0,0]
	v_mfma_scale_f32_16x16x128_f8f6f4 v[78:81], v[26:33], v[194:201], v[78:81], v1, v182 op_sel_hi:[0,0,0]
	v_mfma_scale_f32_16x16x128_f8f6f4 v[70:73], v[18:25], v[202:209], v[70:73], v1, v182 op_sel_hi:[0,0,0]
	v_mfma_scale_f32_16x16x128_f8f6f4 v[62:65], v[26:33], v[202:209], v[62:65], v1, v182 op_sel_hi:[0,0,0]
	v_mfma_scale_f32_16x16x128_f8f6f4 v[54:57], v[18:25], v[210:217], v[54:57], v1, v182 op_sel_hi:[0,0,0]
	v_mfma_scale_f32_16x16x128_f8f6f4 v[46:49], v[26:33], v[210:217], v[46:49], v1, v182 op_sel_hi:[0,0,0]
	v_mfma_scale_f32_16x16x128_f8f6f4 v[38:41], v[18:25], v[218:225], v[38:41], v1, v182 op_sel_hi:[0,0,0]
	v_mfma_scale_f32_16x16x128_f8f6f4 v[34:37], v[26:33], v[218:225], v[34:37], v1, v182 op_sel_hi:[0,0,0]
	s_setprio 0
	s_barrier
	s_add_u32 s56, s56, 0x100
	s_addc_u32 s57, s57, 0
	s_add_u32 s78, s78, 0x100
	s_addc_u32 s79, s79, 0
	s_cmp_ge_u32 s80, s76
	s_mov_b32 s58, s80
	s_cbranch_scc0 .LBB0_1187
	s_and_b64 vcc, exec, s[12:13]
	s_cbranch_vccz .LBB0_1190
	s_barrier

; #define PG8_STAGE(bufoff, gbase, voff) do { _Pragma("unroll") for (int _i = 0; _i < 2; ++_i) \
;         __builtin_amdgcn_global_load_lds((const unsigned*)((const char*)(gbase) + (voff)[_i]), (PG8_LAS unsigned*)(lds + (bufoff) + ldsw + _i * 8192), 16, 0, 0); } while (0)
; #define PG8_LDA(dst, b, h) do { _Pragma("unroll") for (int m = 0; m < 4; ++m) _Pragma("unroll") for (int k = 0; k < 2; ++k) dst[m][k] = *(const PG8_LAS bf16x8*)(lds + PG8_SA(b, h) + aoff + m * 2048 + k * 1024); } while (0)
; #define PG8_LDB(dst, b, h) do { _Pragma("unroll") for (int n = 0; n < 2; ++n) _Pragma("unroll") for (int k = 0; k < 2; ++k) dst[n][k] = *(const PG8_LAS bf16x8*)(lds + PG8_SB(b, h) + boff + n * 2048 + k * 1024); } while (0)
; #define PG8_MMA(ai, bj, At, Bt) do { __builtin_amdgcn_s_setprio(1); _Pragma("unroll") for (int m = 0; m < 4; ++m) _Pragma("unroll") for (int n = 0; n < 2; ++n) _Pragma("unroll") for (int k = 0; k < 2; ++k) \
;         acc[ai][bj][m][n] = __builtin_amdgcn_mfma_f32_16x16x32_bf16(Bt[n][k], At[m][k], acc[ai][bj][m][n], 0, 0, 0); __builtin_amdgcn_s_setprio(0); } while (0)
; #define PG8_WAIT_V(n) asm volatile("s_waitcnt vmcnt(" #n ")" ::: "memory")
; #define PG8_WAIT_L(n) asm volatile("s_waitcnt lgkmcnt(" #n ")" ::: "memory")
; #define PG8_BAR __builtin_amdgcn_s_barrier()
; #define PG8_SCHED __builtin_amdgcn_sched_barrier(0)
; #define PG8_STAGE(bufoff, gbase, voff) do { _Pragma("unroll") for (int _i = 0; _i < 2; ++_i) \
;         __builtin_amdgcn_global_load_lds((const unsigned*)((const char*)(gbase) + (voff)[_i]), (PG8_LAS unsigned*)(lds + (bufoff) + ldsw + _i * 8192), 16, 0, 0); } while (0)
; #define PG8_WAIT_V(n) asm volatile("s_waitcnt vmcnt(" #n ")" ::: "memory")
; template <class Epi, class Sched, bool ALIGN_EPI = false>
; __device__ __forceinline__ void gemm_phase8(PG8_LAS unsigned char* lds, const Gemm g, const Sched& S, const Epi& E) {
;     ...
;             PG8_LDB(B0, 0, 0); PG8_LDB(B1, 0, 1); PG8_SCHED; PG8_LDA(At, 0, 0); PG8_STAGE(PG8_SA(1, 1), a1 + hstepA, voffA);
;             PG8_WAIT_V(8); PG8_WAIT_L(0); PG8_BAR; PG8_MMA(0, 0, At, B0); PG8_MMA(0, 1, At, B1); PG8_BAR; PG8_SCHED;
;             PG8_LDA(At, 0, 1); PG8_STAGE(PG8_SB(0, 0), b2, voffB); PG8_STAGE(PG8_SB(0, 1), b2 + hstepB, voffB); PG8_STAGE(PG8_SA(0, 0), a2, voffA);
;             PG8_WAIT_V(8); PG8_WAIT_L(0); PG8_BAR; PG8_MMA(1, 0, At, B0); PG8_MMA(1, 1, At, B1); PG8_BAR; PG8_SCHED;
.Lcy3_0f:
	v_mfma_scale_f32_16x16x128_f8f6f4 v[158:161], v[18:25], v[174:181], 0, v1, v182 op_sel_hi:[0,0,0]
	v_mfma_scale_f32_16x16x128_f8f6f4 v[154:157], v[26:33], v[174:181], 0, v1, v182 op_sel_hi:[0,0,0]
	v_mfma_scale_f32_16x16x128_f8f6f4 v[150:153], v[18:25], v[194:201], 0, v1, v182 op_sel_hi:[0,0,0]
	v_mfma_scale_f32_16x16x128_f8f6f4 v[138:141], v[26:33], v[194:201], 0, v1, v182 op_sel_hi:[0,0,0]
	v_mfma_scale_f32_16x16x128_f8f6f4 v[130:133], v[18:25], v[202:209], 0, v1, v182 op_sel_hi:[0,0,0]
	v_mfma_scale_f32_16x16x128_f8f6f4 v[122:125], v[26:33], v[202:209], 0, v1, v182 op_sel_hi:[0,0,0]
	v_mfma_scale_f32_16x16x128_f8f6f4 v[118:121], v[18:25], v[210:217], 0, v1, v182 op_sel_hi:[0,0,0]
	v_mfma_scale_f32_16x16x128_f8f6f4 v[106:109], v[26:33], v[210:217], 0, v1, v182 op_sel_hi:[0,0,0]
	s_setprio 0
	s_setprio 1
	v_mfma_scale_f32_16x16x128_f8f6f4 v[146:149], v[2:9], v[174:181], 0, v1, v182 op_sel_hi:[0,0,0]
	v_mfma_scale_f32_16x16x128_f8f6f4 v[142:145], v[10:17], v[174:181], 0, v1, v182 op_sel_hi:[0,0,0]
	v_mfma_scale_f32_16x16x128_f8f6f4 v[134:137], v[2:9], v[194:201], 0, v1, v182 op_sel_hi:[0,0,0]
	v_mfma_scale_f32_16x16x128_f8f6f4 v[126:129], v[10:17], v[194:201], 0, v1, v182 op_sel_hi:[0,0,0]
	v_mfma_scale_f32_16x16x128_f8f6f4 v[114:117], v[2:9], v[202:209], 0, v1, v182 op_sel_hi:[0,0,0]
	v_mfma_scale_f32_16x16x128_f8f6f4 v[110:113], v[10:17], v[202:209], 0, v1, v182 op_sel_hi:[0,0,0]
	v_mfma_scale_f32_16x16x128_f8f6f4 v[102:105], v[2:9], v[210:217], 0, v1, v182 op_sel_hi:[0,0,0]
	v_mfma_scale_f32_16x16x128_f8f6f4 v[98:101], v[10:17], v[210:217], 0, v1, v182 op_sel_hi:[0,0,0]
	s_branch .Lcy3_0j
.Lcy3_1f:
	v_mfma_scale_f32_16x16x128_f8f6f4 v[94:97], v[18:25], v[194:201], 0, v1, v182 op_sel_hi:[0,0,0]
	v_mfma_scale_f32_16x16x128_f8f6f4 v[90:93], v[26:33], v[194:201], 0, v1, v182 op_sel_hi:[0,0,0]
	v_mfma_scale_f32_16x16x128_f8f6f4 v[82:85], v[18:25], v[202:209], 0, v1, v182 op_sel_hi:[0,0,0]
	v_mfma_scale_f32_16x16x128_f8f6f4 v[74:77], v[26:33], v[202:209], 0, v1, v182 op_sel_hi:[0,0,0]
	v_mfma_scale_f32_16x16x128_f8f6f4 v[66:69], v[18:25], v[210:217], 0, v1, v182 op_sel_hi:[0,0,0]
	v_mfma_scale_f32_16x16x128_f8f6f4 v[58:61], v[26:33], v[210:217], 0, v1, v182 op_sel_hi:[0,0,0]
	v_mfma_scale_f32_16x16x128_f8f6f4 v[50:53], v[18:25], v[218:225], 0, v1, v182 op_sel_hi:[0,0,0]
	v_mfma_scale_f32_16x16x128_f8f6f4 v[42:45], v[26:33], v[218:225], 0, v1, v182 op_sel_hi:[0,0,0]
	s_setprio 0
	s_setprio 1
	v_mfma_scale_f32_16x16x128_f8f6f4 v[86:89], v[2:9], v[194:201], 0, v1, v182 op_sel_hi:[0,0,0]
	v_mfma_scale_f32_16x16x128_f8f6f4 v[78:81], v[10:17], v[194:201], 0, v1, v182 op_sel_hi:[0,0,0]
	v_mfma_scale_f32_16x16x128_f8f6f4 v[70:73], v[2:9], v[202:209], 0, v1, v182 op_sel_hi:[0,0,0]
	v_mfma_scale_f32_16x16x128_f8f6f4 v[62:65], v[10:17], v[202:209], 0, v1, v182 op_sel_hi:[0,0,0]
	v_mfma_scale_f32_16x16x128_f8f6f4 v[54:57], v[2:9], v[210:217], 0, v1, v182 op_sel_hi:[0,0,0]
	v_mfma_scale_f32_16x16x128_f8f6f4 v[46:49], v[10:17], v[210:217], 0, v1, v182 op_sel_hi:[0,0,0]
	v_mfma_scale_f32_16x16x128_f8f6f4 v[38:41], v[2:9], v[218:225], 0, v1, v182 op_sel_hi:[0,0,0]
	v_mfma_scale_f32_16x16x128_f8f6f4 v[34:37], v[10:17], v[218:225], 0, v1, v182 op_sel_hi:[0,0,0]
	s_mov_b32 s100, 0
	s_branch .Lcy3_1j

; #define PG8_STAGE(bufoff, gbase, voff) do { _Pragma("unroll") for (int _i = 0; _i < 2; ++_i) \
;         __builtin_amdgcn_global_load_lds((const unsigned*)((const char*)(gbase) + (voff)[_i]), (PG8_LAS unsigned*)(lds + (bufoff) + ldsw + _i * 8192), 16, 0, 0); } while (0)
; #define PG8_LDA(dst, b, h) do { _Pragma("unroll") for (int m = 0; m < 4; ++m) _Pragma("unroll") for (int k = 0; k < 2; ++k) dst[m][k] = *(const PG8_LAS bf16x8*)(lds + PG8_SA(b, h) + aoff + m * 2048 + k * 1024); } while (0)
; #define PG8_LDB(dst, b, h) do { _Pragma("unroll") for (int n = 0; n < 2; ++n) _Pragma("unroll") for (int k = 0; k < 2; ++k) dst[n][k] = *(const PG8_LAS bf16x8*)(lds + PG8_SB(b, h) + boff + n * 2048 + k * 1024); } while (0)
; #define PG8_WAIT_V(n) asm volatile("s_waitcnt vmcnt(" #n ")" ::: "memory")
; #define PG8_WAIT_L(n) asm volatile("s_waitcnt lgkmcnt(" #n ")" ::: "memory")
; #define PG8_BAR __builtin_amdgcn_s_barrier()
; #define PG8_SCHED __builtin_amdgcn_sched_barrier(0)
; template <class Epi, class Sched, bool ALIGN_EPI = false>
; __device__ __forceinline__ void gemm_phase8(PG8_LAS unsigned char* lds, const Gemm g, const Sched& S, const Epi& E) {
;     ...
;         for (int t = 0; t < nt; t += 2) {
;             const bool last = (t == nt - 2);
;             const char* a1 = cA + (size_t)(t + 1) * kstep;
;             const char* a2 = last ? nA : cA + (size_t)(t + 2) * kstep; const char* b2 = last ? nB : cB + (size_t)(t + 2) * kstep;
;             const char* a3 = a2 + kstep; const char* b3 = b2 + kstep;
;             if (last && has_next) S.a_ready(nxt);
;             PG8_LDB(B0, 0, 0); PG8_LDB(B1, 0, 1); PG8_SCHED; PG8_LDA(At, 0, 0); PG8_STAGE(PG8_SA(1, 1), a1 + hstepA, voffA);
;             PG8_WAIT_V(8); PG8_WAIT_L(0); PG8_BAR; PG8_MMA(0, 0, At, B0); PG8_MMA(0, 1, At, B1); PG8_BAR; PG8_SCHED;
;             PG8_LDA(At, 0, 1); PG8_STAGE(PG8_SB(0, 0), b2, voffB); PG8_STAGE(PG8_SB(0, 1), b2 + hstepB, voffB); PG8_STAGE(PG8_SA(0, 0), a2, voffA);
;             PG8_WAIT_V(8); PG8_WAIT_L(0); PG8_BAR; PG8_MMA(1, 0, At, B0); PG8_MMA(1, 1, At, B1); PG8_BAR; PG8_SCHED;
;     ...
; #pragma unroll
;         for (int a = 0; a < 2; ++a)
; #pragma unroll
;             for (int b = 0; b < 2; ++b)
; #pragma unroll
;                 for (int m = 0; m < 4; ++m)
; #pragma unroll
;                     for (int n = 0; n < 2; ++n) acc[a][b][m][n] = (f32x4){0.f, 0.f, 0.f, 0.f};
.LBB0_1421:
	s_ashr_i32 s13, s12, 31
	s_lshl_b64 s[14:15], s[12:13], 19
	s_add_u32 s14, s26, s14
	s_addc_u32 s15, s27, s15
	s_and_b64 s[16:17], s[2:3], exec
	s_cselect_b32 s13, s15, s21
	s_cselect_b32 s45, s14, s20
	s_ashr_i32 s11, s10, 31
	s_lshl_b64 s[16:17], s[10:11], 19
	s_add_u32 s16, s28, s16
	s_addc_u32 s17, s29, s17
	s_and_b64 s[24:25], s[2:3], exec
	s_cselect_b32 s11, s17, s23
	s_cselect_b32 s52, s16, s22
	s_add_u32 s20, s20, 0x40080
	s_addc_u32 s21, s21, 0
	s_add_u32 s53, s22, 0x100
	s_mov_b32 s100, 1
	s_addc_u32 s54, s23, 0
	s_mov_b32 s55, -2
.LBB0_1422:
	ds_read_b128 v[18:21], v191
	ds_read_b128 v[26:29], v191 offset:2048
	ds_read_b128 v[22:25], v192
	ds_read_b128 v[30:33], v192 offset:2048
	ds_read_b128 v[2:5], v193
	ds_read_b128 v[10:13], v193 offset:2048
	ds_read_b128 v[6:9], v194
	ds_read_b128 v[14:17], v194 offset:2048
	s_add_u32 s22, s20, 0xfffc0080
	s_addc_u32 s23, s21, -1
	s_cmp_eq_u32 s55, 12
	s_cselect_b32 s25, s13, s23
	s_cselect_b32 s24, s45, s22
	s_cselect_b32 s23, s11, s54
	s_cselect_b32 s22, s52, s53
	v_lshl_add_u64 v[222:223], s[20:21], 0, v[170:171]
	s_add_i32 m0, s19, 0xc000
	ds_read_b128 v[178:181], v195
	ds_read_b128 v[198:201], v195 offset:2048
	ds_read_b128 v[182:185], v196
	ds_read_b128 v[202:205], v196 offset:2048
	ds_read_b128 v[206:209], v195 offset:4096
	ds_read_b128 v[214:217], v195 offset:6144
	ds_read_b128 v[210:213], v196 offset:4096
	ds_read_b128 v[218:221], v196 offset:6144
	global_load_lds_dwordx4 v[222:223], off
	v_lshl_add_u64 v[222:223], s[20:21], 0, v[172:173]
	s_add_i32 m0, s19, 0xe000
	s_nop 0
	global_load_lds_dwordx4 v[222:223], off
	s_waitcnt vmcnt(8)
	s_waitcnt lgkmcnt(0)
	s_barrier
	s_setprio 1
	s_waitcnt lgkmcnt(0)
	s_cmp_eq_u32 s100, 1
	s_cbranch_scc1 .Lcy4_0f
	v_mfma_scale_f32_16x16x128_f8f6f4 v[158:161], v[18:25], v[178:185], v[158:161], v1, v186 op_sel_hi:[0,0,0]
	v_mfma_scale_f32_16x16x128_f8f6f4 v[150:153], v[26:33], v[178:185], v[150:153], v1, v186 op_sel_hi:[0,0,0]
	v_mfma_scale_f32_16x16x128_f8f6f4 v[142:145], v[18:25], v[198:205], v[142:145], v1, v186 op_sel_hi:[0,0,0]
	v_mfma_scale_f32_16x16x128_f8f6f4 v[134:137], v[26:33], v[198:205], v[134:137], v1, v186 op_sel_hi:[0,0,0]
	v_mfma_scale_f32_16x16x128_f8f6f4 v[126:129], v[18:25], v[206:213], v[126:129], v1, v186 op_sel_hi:[0,0,0]
	v_mfma_scale_f32_16x16x128_f8f6f4 v[118:121], v[26:33], v[206:213], v[118:121], v1, v186 op_sel_hi:[0,0,0]
	v_mfma_scale_f32_16x16x128_f8f6f4 v[110:113], v[18:25], v[214:221], v[110:113], v1, v186 op_sel_hi:[0,0,0]
	v_mfma_scale_f32_16x16x128_f8f6f4 v[102:105], v[26:33], v[214:221], v[102:105], v1, v186 op_sel_hi:[0,0,0]
	s_setprio 0
	s_setprio 1
	v_mfma_scale_f32_16x16x128_f8f6f4 v[154:157], v[2:9], v[178:185], v[154:157], v1, v186 op_sel_hi:[0,0,0]
	v_mfma_scale_f32_16x16x128_f8f6f4 v[146:149], v[10:17], v[178:185], v[146:149], v1, v186 op_sel_hi:[0,0,0]
	v_mfma_scale_f32_16x16x128_f8f6f4 v[138:141], v[2:9], v[198:205], v[138:141], v1, v186 op_sel_hi:[0,0,0]
	v_mfma_scale_f32_16x16x128_f8f6f4 v[130:133], v[10:17], v[198:205], v[130:133], v1, v186 op_sel_hi:[0,0,0]
	v_mfma_scale_f32_16x16x128_f8f6f4 v[122:125], v[2:9], v[206:213], v[122:125], v1, v186 op_sel_hi:[0,0,0]
	v_mfma_scale_f32_16x16x128_f8f6f4 v[114:117], v[10:17], v[206:213], v[114:117], v1, v186 op_sel_hi:[0,0,0]
	v_mfma_scale_f32_16x16x128_f8f6f4 v[106:109], v[2:9], v[214:221], v[106:109], v1, v186 op_sel_hi:[0,0,0]
	v_mfma_scale_f32_16x16x128_f8f6f4 v[98:101], v[10:17], v[214:221], v[98:101], v1, v186 op_sel_hi:[0,0,0]
.Lcy4_0j:
	s_setprio 0
	s_barrier
	s_add_i32 s56, s41, s30
	v_lshl_add_u64 v[178:179], s[22:23], 0, v[164:165]
	s_mov_b32 m0, s56
	ds_read_b128 v[198:201], v195 offset:16384
	ds_read_b128 v[206:209], v195 offset:18432
	ds_read_b128 v[202:205], v196 offset:16384
	ds_read_b128 v[210:213], v196 offset:18432
	ds_read_b128 v[214:217], v195 offset:20480
	ds_read_b128 v[222:225], v195 offset:22528
	ds_read_b128 v[218:221], v196 offset:20480
	ds_read_b128 v[226:229], v196 offset:22528
	global_load_lds_dwordx4 v[178:179], off
	s_add_i32 m0, s56, 0x2000
	s_add_u32 s56, s22, 0x40000
	v_lshl_add_u64 v[180:181], s[22:23], 0, v[168:169]
	s_addc_u32 s57, s23, 0
	s_add_i32 s58, s42, s30
	global_load_lds_dwordx4 v[180:181], off
	v_lshl_add_u64 v[182:183], s[56:57], 0, v[164:165]
	s_mov_b32 m0, s58
	v_lshl_add_u64 v[184:185], s[24:25], 0, v[166:167]
	global_load_lds_dwordx4 v[182:183], off
	v_lshl_add_u64 v[182:183], s[56:57], 0, v[168:169]
	s_add_i32 m0, s58, 0x2000
	s_nop 0
	global_load_lds_dwordx4 v[182:183], off
	v_lshl_add_u64 v[182:183], s[24:25], 0, v[162:163]
	s_mov_b32 m0, s19
	s_nop 0
	global_load_lds_dwordx4 v[182:183], off
	s_mov_b32 m0, s34
	s_nop 0
	global_load_lds_dwordx4 v[184:185], off
	s_waitcnt vmcnt(8)
	s_waitcnt lgkmcnt(0)
	s_barrier
	s_setprio 1
	s_waitcnt lgkmcnt(0)
	s_cmp_eq_u32 s100, 1
	s_cbranch_scc1 .Lcy4_1f
	v_mfma_scale_f32_16x16x128_f8f6f4 v[94:97], v[18:25], v[198:205], v[94:97], v1, v186 op_sel_hi:[0,0,0]
	v_mfma_scale_f32_16x16x128_f8f6f4 v[86:89], v[26:33], v[198:205], v[86:89], v1, v186 op_sel_hi:[0,0,0]
	v_mfma_scale_f32_16x16x128_f8f6f4 v[78:81], v[18:25], v[206:213], v[78:81], v1, v186 op_sel_hi:[0,0,0]
	v_mfma_scale_f32_16x16x128_f8f6f4 v[70:73], v[26:33], v[206:213], v[70:73], v1, v186 op_sel_hi:[0,0,0]
	v_mfma_scale_f32_16x16x128_f8f6f4 v[62:65], v[18:25], v[214:221], v[62:65], v1, v186 op_sel_hi:[0,0,0]
	v_mfma_scale_f32_16x16x128_f8f6f4 v[54:57], v[26:33], v[214:221], v[54:57], v1, v186 op_sel_hi:[0,0,0]
	v_mfma_scale_f32_16x16x128_f8f6f4 v[46:49], v[18:25], v[222:229], v[46:49], v1, v186 op_sel_hi:[0,0,0]
	v_mfma_scale_f32_16x16x128_f8f6f4 v[38:41], v[26:33], v[222:229], v[38:41], v1, v186 op_sel_hi:[0,0,0]
	s_setprio 0
	s_setprio 1
	v_mfma_scale_f32_16x16x128_f8f6f4 v[90:93], v[2:9], v[198:205], v[90:93], v1, v186 op_sel_hi:[0,0,0]
	v_mfma_scale_f32_16x16x128_f8f6f4 v[82:85], v[10:17], v[198:205], v[82:85], v1, v186 op_sel_hi:[0,0,0]
	v_mfma_scale_f32_16x16x128_f8f6f4 v[74:77], v[2:9], v[206:213], v[74:77], v1, v186 op_sel_hi:[0,0,0]
	v_mfma_scale_f32_16x16x128_f8f6f4 v[66:69], v[10:17], v[206:213], v[66:69], v1, v186 op_sel_hi:[0,0,0]
	v_mfma_scale_f32_16x16x128_f8f6f4 v[58:61], v[2:9], v[214:221], v[58:61], v1, v186 op_sel_hi:[0,0,0]
	v_mfma_scale_f32_16x16x128_f8f6f4 v[50:53], v[10:17], v[214:221], v[50:53], v1, v186 op_sel_hi:[0,0,0]
	v_mfma_scale_f32_16x16x128_f8f6f4 v[42:45], v[2:9], v[222:229], v[42:45], v1, v186 op_sel_hi:[0,0,0]
	v_mfma_scale_f32_16x16x128_f8f6f4 v[34:37], v[10:17], v[222:229], v[34:37], v1, v186 op_sel_hi:[0,0,0]
; #define PG8_STAGE(bufoff, gbase, voff) do { _Pragma("unroll") for (int _i = 0; _i < 2; ++_i) \
;         __builtin_amdgcn_global_load_lds((const unsigned*)((const char*)(gbase) + (voff)[_i]), (PG8_LAS unsigned*)(lds + (bufoff) + ldsw + _i * 8192), 16, 0, 0); } while (0)
; #define PG8_LDA(dst, b, h) do { _Pragma("unroll") for (int m = 0; m < 4; ++m) _Pragma("unroll") for (int k = 0; k < 2; ++k) dst[m][k] = *(const PG8_LAS bf16x8*)(lds + PG8_SA(b, h) + aoff + m * 2048 + k * 1024); } while (0)
; #define PG8_LDB(dst, b, h) do { _Pragma("unroll") for (int n = 0; n < 2; ++n) _Pragma("unroll") for (int k = 0; k < 2; ++k) dst[n][k] = *(const PG8_LAS bf16x8*)(lds + PG8_SB(b, h) + boff + n * 2048 + k * 1024); } while (0)
; #define PG8_MMA(ai, bj, At, Bt) do { __builtin_amdgcn_s_setprio(1); _Pragma("unroll") for (int m = 0; m < 4; ++m) _Pragma("unroll") for (int n = 0; n < 2; ++n) _Pragma("unroll") for (int k = 0; k < 2; ++k) \
;         acc[ai][bj][m][n] = __builtin_amdgcn_mfma_f32_16x16x32_bf16(Bt[n][k], At[m][k], acc[ai][bj][m][n], 0, 0, 0); __builtin_amdgcn_s_setprio(0); } while (0)
; #define PG8_WAIT_V(n) asm volatile("s_waitcnt vmcnt(" #n ")" ::: "memory")
; #define PG8_WAIT_L(n) asm volatile("s_waitcnt lgkmcnt(" #n ")" ::: "memory")
; #define PG8_BAR __builtin_amdgcn_s_barrier()
; #define PG8_SCHED __builtin_amdgcn_sched_barrier(0)
; #define PG8_STAGE(bufoff, gbase, voff) do { _Pragma("unroll") for (int _i = 0; _i < 2; ++_i) \
;         __builtin_amdgcn_global_load_lds((const unsigned*)((const char*)(gbase) + (voff)[_i]), (PG8_LAS unsigned*)(lds + (bufoff) + ldsw + _i * 8192), 16, 0, 0); } while (0)
; #define PG8_BAR __builtin_amdgcn_s_barrier()
; template <class Epi, class Sched, bool ALIGN_EPI = false>
; __device__ __forceinline__ void gemm_phase8(PG8_LAS unsigned char* lds, const Gemm g, const Sched& S, const Epi& E) {
;     ...
;             PG8_LDB(B0, 1, 0); PG8_LDB(B1, 1, 1); PG8_SCHED; PG8_LDA(At, 1, 0); PG8_STAGE(PG8_SA(0, 1), a2 + hstepA, voffA);
;             PG8_WAIT_V(8); PG8_WAIT_L(0); PG8_BAR; PG8_MMA(0, 0, At, B0); PG8_MMA(0, 1, At, B1); PG8_BAR; PG8_SCHED;
;             PG8_LDA(At, 1, 1); PG8_STAGE(PG8_SB(1, 0), b3, voffB); PG8_STAGE(PG8_SB(1, 1), b3 + hstepB, voffB); PG8_STAGE(PG8_SA(1, 0), a3, voffA);
;             PG8_WAIT_V(8); PG8_WAIT_L(0); PG8_BAR; PG8_MMA(1, 0, At, B0); PG8_MMA(1, 1, At, B1); PG8_BAR; PG8_SCHED;
;         }
.Lcy4_1j:
	s_setprio 0
	s_barrier
	s_add_i32 s56, 0, 0x18000
	s_add_i32 s57, 0, 0x1c000
	v_add_u32_e32 v6, s56, v187
	v_add_u32_e32 v14, s56, v188
	v_add_u32_e32 v22, s57, v187
	v_add_u32_e32 v30, s57, v188
	ds_read_b128 v[2:5], v6
	ds_read_b128 v[10:13], v6 offset:2048
	ds_read_b128 v[6:9], v14
	ds_read_b128 v[14:17], v14 offset:2048
	ds_read_b128 v[18:21], v22
	ds_read_b128 v[26:29], v22 offset:2048
	ds_read_b128 v[22:25], v30
	ds_read_b128 v[30:33], v30 offset:2048
	s_add_u32 s24, s24, 0x40000
	s_addc_u32 s25, s25, 0
	s_mov_b32 m0, s35
	v_lshl_add_u64 v[230:231], s[24:25], 0, v[162:163]
	ds_read_b128 v[198:201], v195 offset:32768
	ds_read_b128 v[206:209], v195 offset:34816
	ds_read_b128 v[202:205], v196 offset:32768
	ds_read_b128 v[210:213], v196 offset:34816
	ds_read_b128 v[214:217], v195 offset:36864
	ds_read_b128 v[222:225], v195 offset:38912
	ds_read_b128 v[218:221], v196 offset:36864
	ds_read_b128 v[226:229], v196 offset:38912
	global_load_lds_dwordx4 v[230:231], off
	v_lshl_add_u64 v[230:231], s[24:25], 0, v[166:167]
	s_mov_b32 m0, s36
	s_nop 0
	global_load_lds_dwordx4 v[230:231], off
	s_waitcnt vmcnt(8)
	s_waitcnt lgkmcnt(0)
	s_barrier
	s_setprio 1
	s_waitcnt lgkmcnt(0)
	v_mfma_scale_f32_16x16x128_f8f6f4 v[158:161], v[2:9], v[198:205], v[158:161], v1, v186 op_sel_hi:[0,0,0]
	v_mfma_scale_f32_16x16x128_f8f6f4 v[150:153], v[10:17], v[198:205], v[150:153], v1, v186 op_sel_hi:[0,0,0]
	v_mfma_scale_f32_16x16x128_f8f6f4 v[142:145], v[2:9], v[206:213], v[142:145], v1, v186 op_sel_hi:[0,0,0]
	v_mfma_scale_f32_16x16x128_f8f6f4 v[134:137], v[10:17], v[206:213], v[134:137], v1, v186 op_sel_hi:[0,0,0]
	v_mfma_scale_f32_16x16x128_f8f6f4 v[126:129], v[2:9], v[214:221], v[126:129], v1, v186 op_sel_hi:[0,0,0]
	v_mfma_scale_f32_16x16x128_f8f6f4 v[118:121], v[10:17], v[214:221], v[118:121], v1, v186 op_sel_hi:[0,0,0]
	v_mfma_scale_f32_16x16x128_f8f6f4 v[110:113], v[2:9], v[222:229], v[110:113], v1, v186 op_sel_hi:[0,0,0]
	v_mfma_scale_f32_16x16x128_f8f6f4 v[102:105], v[10:17], v[222:229], v[102:105], v1, v186 op_sel_hi:[0,0,0]
	s_setprio 0
	s_setprio 1
	v_mfma_scale_f32_16x16x128_f8f6f4 v[154:157], v[18:25], v[198:205], v[154:157], v1, v186 op_sel_hi:[0,0,0]
	v_mfma_scale_f32_16x16x128_f8f6f4 v[146:149], v[26:33], v[198:205], v[146:149], v1, v186 op_sel_hi:[0,0,0]
	v_mfma_scale_f32_16x16x128_f8f6f4 v[138:141], v[18:25], v[206:213], v[138:141], v1, v186 op_sel_hi:[0,0,0]
	v_mfma_scale_f32_16x16x128_f8f6f4 v[130:133], v[26:33], v[206:213], v[130:133], v1, v186 op_sel_hi:[0,0,0]
	v_mfma_scale_f32_16x16x128_f8f6f4 v[122:125], v[18:25], v[214:221], v[122:125], v1, v186 op_sel_hi:[0,0,0]
	v_mfma_scale_f32_16x16x128_f8f6f4 v[114:117], v[26:33], v[214:221], v[114:117], v1, v186 op_sel_hi:[0,0,0]
	v_mfma_scale_f32_16x16x128_f8f6f4 v[106:109], v[18:25], v[222:229], v[106:109], v1, v186 op_sel_hi:[0,0,0]
	v_mfma_scale_f32_16x16x128_f8f6f4 v[98:101], v[26:33], v[222:229], v[98:101], v1, v186 op_sel_hi:[0,0,0]
	s_setprio 0
	s_barrier
	s_add_i32 s24, s56, s30
	v_lshl_add_u64 v[178:179], v[178:179], 0, s[6:7]
	s_mov_b32 m0, s24
	ds_read_b128 v[198:201], v195 offset:49152
	ds_read_b128 v[206:209], v195 offset:51200
	ds_read_b128 v[202:205], v196 offset:49152
	ds_read_b128 v[210:213], v196 offset:51200
	ds_read_b128 v[214:217], v195 offset:53248
	ds_read_b128 v[222:225], v195 offset:55296
	ds_read_b128 v[218:221], v196 offset:53248
	ds_read_b128 v[226:229], v196 offset:55296
	global_load_lds_dwordx4 v[178:179], off
	s_add_i32 m0, s24, 0x2000
	s_add_u32 s22, s22, 0x40080
	v_lshl_add_u64 v[178:179], v[180:181], 0, s[6:7]
	s_addc_u32 s23, s23, 0
	s_add_i32 s24, s57, s30
	global_load_lds_dwordx4 v[178:179], off
	v_lshl_add_u64 v[178:179], s[22:23], 0, v[164:165]
	s_mov_b32 m0, s24
	s_nop 0
	global_load_lds_dwordx4 v[178:179], off
	v_lshl_add_u64 v[178:179], s[22:23], 0, v[168:169]
	s_add_i32 m0, s24, 0x2000
	s_nop 0
	global_load_lds_dwordx4 v[178:179], off
	v_lshl_add_u64 v[178:179], v[182:183], 0, s[6:7]
	s_mov_b32 m0, s39
	s_nop 0
	global_load_lds_dwordx4 v[178:179], off
	v_lshl_add_u64 v[178:179], v[184:185], 0, s[6:7]
	s_mov_b32 m0, s40
	s_nop 0
	global_load_lds_dwordx4 v[178:179], off
	s_waitcnt vmcnt(8)
	s_waitcnt lgkmcnt(0)
	s_barrier
	s_setprio 1
	s_waitcnt lgkmcnt(0)
	v_mfma_scale_f32_16x16x128_f8f6f4 v[94:97], v[2:9], v[198:205], v[94:97], v1, v186 op_sel_hi:[0,0,0]
	v_mfma_scale_f32_16x16x128_f8f6f4 v[86:89], v[10:17], v[198:205], v[86:89], v1, v186 op_sel_hi:[0,0,0]
	v_mfma_scale_f32_16x16x128_f8f6f4 v[78:81], v[2:9], v[206:213], v[78:81], v1, v186 op_sel_hi:[0,0,0]
	v_mfma_scale_f32_16x16x128_f8f6f4 v[70:73], v[10:17], v[206:213], v[70:73], v1, v186 op_sel_hi:[0,0,0]
	v_mfma_scale_f32_16x16x128_f8f6f4 v[62:65], v[2:9], v[214:221], v[62:65], v1, v186 op_sel_hi:[0,0,0]
	v_mfma_scale_f32_16x16x128_f8f6f4 v[54:57], v[10:17], v[214:221], v[54:57], v1, v186 op_sel_hi:[0,0,0]
	v_mfma_scale_f32_16x16x128_f8f6f4 v[46:49], v[2:9], v[222:229], v[46:49], v1, v186 op_sel_hi:[0,0,0]
	v_mfma_scale_f32_16x16x128_f8f6f4 v[38:41], v[10:17], v[222:229], v[38:41], v1, v186 op_sel_hi:[0,0,0]
	s_setprio 0
	s_setprio 1
	v_mfma_scale_f32_16x16x128_f8f6f4 v[90:93], v[18:25], v[198:205], v[90:93], v1, v186 op_sel_hi:[0,0,0]
	v_mfma_scale_f32_16x16x128_f8f6f4 v[82:85], v[26:33], v[198:205], v[82:85], v1, v186 op_sel_hi:[0,0,0]
	v_mfma_scale_f32_16x16x128_f8f6f4 v[74:77], v[18:25], v[206:213], v[74:77], v1, v186 op_sel_hi:[0,0,0]
	v_mfma_scale_f32_16x16x128_f8f6f4 v[66:69], v[26:33], v[206:213], v[66:69], v1, v186 op_sel_hi:[0,0,0]
	v_mfma_scale_f32_16x16x128_f8f6f4 v[58:61], v[18:25], v[214:221], v[58:61], v1, v186 op_sel_hi:[0,0,0]
	v_mfma_scale_f32_16x16x128_f8f6f4 v[50:53], v[26:33], v[214:221], v[50:53], v1, v186 op_sel_hi:[0,0,0]
	v_mfma_scale_f32_16x16x128_f8f6f4 v[42:45], v[18:25], v[222:229], v[42:45], v1, v186 op_sel_hi:[0,0,0]
	v_mfma_scale_f32_16x16x128_f8f6f4 v[34:37], v[26:33], v[222:229], v[34:37], v1, v186 op_sel_hi:[0,0,0]
	s_setprio 0
	s_barrier
	s_add_i32 s55, s55, 2
	s_add_u32 s20, s20, 0x100
	s_addc_u32 s21, s21, 0
	s_add_u32 s53, s53, 0x100
	s_addc_u32 s54, s54, 0
	s_cmp_gt_u32 s55, 13
	s_cbranch_scc0 .LBB0_1422
	s_and_b64 vcc, exec, s[8:9]
	s_cbranch_vccz .LBB0_1425
	s_barrier

; #define PG8_STAGE(bufoff, gbase, voff) do { _Pragma("unroll") for (int _i = 0; _i < 2; ++_i) \
;         __builtin_amdgcn_global_load_lds((const unsigned*)((const char*)(gbase) + (voff)[_i]), (PG8_LAS unsigned*)(lds + (bufoff) + ldsw + _i * 8192), 16, 0, 0); } while (0)
; #define PG8_LDA(dst, b, h) do { _Pragma("unroll") for (int m = 0; m < 4; ++m) _Pragma("unroll") for (int k = 0; k < 2; ++k) dst[m][k] = *(const PG8_LAS bf16x8*)(lds + PG8_SA(b, h) + aoff + m * 2048 + k * 1024); } while (0)
; #define PG8_LDB(dst, b, h) do { _Pragma("unroll") for (int n = 0; n < 2; ++n) _Pragma("unroll") for (int k = 0; k < 2; ++k) dst[n][k] = *(const PG8_LAS bf16x8*)(lds + PG8_SB(b, h) + boff + n * 2048 + k * 1024); } while (0)
; #define PG8_WAIT_V(n) asm volatile("s_waitcnt vmcnt(" #n ")" ::: "memory")
; #define PG8_WAIT_L(n) asm volatile("s_waitcnt lgkmcnt(" #n ")" ::: "memory")
; #define PG8_BAR __builtin_amdgcn_s_barrier()
; #define PG8_SCHED __builtin_amdgcn_sched_barrier(0)
; template <class Epi, class Sched, bool ALIGN_EPI = false>
; __device__ __forceinline__ void gemm_phase8(PG8_LAS unsigned char* lds, const Gemm g, const Sched& S, const Epi& E) {
;     ...
;         for (int t = 0; t < nt; t += 2) {
;             const bool last = (t == nt - 2);
;             const char* a1 = cA + (size_t)(t + 1) * kstep;
;             const char* a2 = last ? nA : cA + (size_t)(t + 2) * kstep; const char* b2 = last ? nB : cB + (size_t)(t + 2) * kstep;
;             const char* a3 = a2 + kstep; const char* b3 = b2 + kstep;
;             if (last && has_next) S.a_ready(nxt);
;             PG8_LDB(B0, 0, 0); PG8_LDB(B1, 0, 1); PG8_SCHED; PG8_LDA(At, 0, 0); PG8_STAGE(PG8_SA(1, 1), a1 + hstepA, voffA);
;             PG8_WAIT_V(8); PG8_WAIT_L(0); PG8_BAR; PG8_MMA(0, 0, At, B0); PG8_MMA(0, 1, At, B1); PG8_BAR; PG8_SCHED;
;             PG8_LDA(At, 0, 1); PG8_STAGE(PG8_SB(0, 0), b2, voffB); PG8_STAGE(PG8_SB(0, 1), b2 + hstepB, voffB); PG8_STAGE(PG8_SA(0, 0), a2, voffA);
;             PG8_WAIT_V(8); PG8_WAIT_L(0); PG8_BAR; PG8_MMA(1, 0, At, B0); PG8_MMA(1, 1, At, B1); PG8_BAR; PG8_SCHED;
;     ...
; #pragma unroll
;         for (int a = 0; a < 2; ++a)
; #pragma unroll
;             for (int b = 0; b < 2; ++b)
; #pragma unroll
;                 for (int m = 0; m < 4; ++m)
; #pragma unroll
;                     for (int n = 0; n < 2; ++n) acc[a][b][m][n] = (f32x4){0.f, 0.f, 0.f, 0.f};
.LBB0_1510:
	s_cmp_gt_i32 s30, -1
	s_cselect_b64 s[36:37], -1, 0
	s_cmp_lt_i32 s30, 0
	s_cselect_b32 s31, 44, 4
	s_add_i32 s79, s31, -2
	s_add_u32 s38, s38, 0xb0080
	s_addc_u32 s39, s39, 0
	s_add_u32 s80, s34, 0x100
	s_mov_b32 s100, 1
	s_mov_b32 s40, 0
	s_addc_u32 s81, s35, 0
.LBB0_1511:
	ds_read_b128 v[18:21], v187
	ds_read_b128 v[26:29], v187 offset:2048
	ds_read_b128 v[22:25], v188
	ds_read_b128 v[30:33], v188 offset:2048
	ds_read_b128 v[2:5], v189
	ds_read_b128 v[10:13], v189 offset:2048
	ds_read_b128 v[6:9], v190
	ds_read_b128 v[14:17], v190 offset:2048
	s_add_i32 s82, s40, 2
	s_add_u32 s34, s38, 0xfff50080
	s_addc_u32 s35, s39, -1
	s_cmp_eq_u32 s79, s40
	s_cselect_b32 s40, s26, s34
	s_cselect_b32 s41, s27, s35
	s_cselect_b32 s35, s29, s81
	s_cselect_b32 s34, s28, s80
	v_lshl_add_u64 v[218:219], s[38:39], 0, v[170:171]
	s_add_i32 m0, s52, 0xc000
	ds_read_b128 v[174:177], v191
	ds_read_b128 v[194:197], v191 offset:2048
	ds_read_b128 v[178:181], v192
	ds_read_b128 v[198:201], v192 offset:2048
	ds_read_b128 v[202:205], v191 offset:4096
	ds_read_b128 v[210:213], v191 offset:6144
	ds_read_b128 v[206:209], v192 offset:4096
	ds_read_b128 v[214:217], v192 offset:6144
	global_load_lds_dwordx4 v[218:219], off
	v_lshl_add_u64 v[218:219], s[38:39], 0, v[172:173]
	s_add_i32 m0, s52, 0xe000
	s_nop 0
	global_load_lds_dwordx4 v[218:219], off
	s_waitcnt vmcnt(8)
	s_waitcnt lgkmcnt(0)
	s_barrier
	s_setprio 1
	s_waitcnt lgkmcnt(0)
	s_cmp_eq_u32 s100, 1
	s_cbranch_scc1 .Lcy5_0f
	v_mfma_scale_f32_16x16x128_f8f6f4 v[158:161], v[18:25], v[174:181], v[158:161], v1, v182 op_sel_hi:[0,0,0]
	v_mfma_scale_f32_16x16x128_f8f6f4 v[154:157], v[26:33], v[174:181], v[154:157], v1, v182 op_sel_hi:[0,0,0]
	v_mfma_scale_f32_16x16x128_f8f6f4 v[150:153], v[18:25], v[194:201], v[150:153], v1, v182 op_sel_hi:[0,0,0]
	v_mfma_scale_f32_16x16x128_f8f6f4 v[138:141], v[26:33], v[194:201], v[138:141], v1, v182 op_sel_hi:[0,0,0]
	v_mfma_scale_f32_16x16x128_f8f6f4 v[130:133], v[18:25], v[202:209], v[130:133], v1, v182 op_sel_hi:[0,0,0]
	v_mfma_scale_f32_16x16x128_f8f6f4 v[122:125], v[26:33], v[202:209], v[122:125], v1, v182 op_sel_hi:[0,0,0]
	v_mfma_scale_f32_16x16x128_f8f6f4 v[118:121], v[18:25], v[210:217], v[118:121], v1, v182 op_sel_hi:[0,0,0]
	v_mfma_scale_f32_16x16x128_f8f6f4 v[106:109], v[26:33], v[210:217], v[106:109], v1, v182 op_sel_hi:[0,0,0]
	s_setprio 0
	s_setprio 1
	v_mfma_scale_f32_16x16x128_f8f6f4 v[146:149], v[2:9], v[174:181], v[146:149], v1, v182 op_sel_hi:[0,0,0]
	v_mfma_scale_f32_16x16x128_f8f6f4 v[142:145], v[10:17], v[174:181], v[142:145], v1, v182 op_sel_hi:[0,0,0]
	v_mfma_scale_f32_16x16x128_f8f6f4 v[134:137], v[2:9], v[194:201], v[134:137], v1, v182 op_sel_hi:[0,0,0]
	v_mfma_scale_f32_16x16x128_f8f6f4 v[126:129], v[10:17], v[194:201], v[126:129], v1, v182 op_sel_hi:[0,0,0]
	v_mfma_scale_f32_16x16x128_f8f6f4 v[114:117], v[2:9], v[202:209], v[114:117], v1, v182 op_sel_hi:[0,0,0]
	v_mfma_scale_f32_16x16x128_f8f6f4 v[110:113], v[10:17], v[202:209], v[110:113], v1, v182 op_sel_hi:[0,0,0]
	v_mfma_scale_f32_16x16x128_f8f6f4 v[102:105], v[2:9], v[210:217], v[102:105], v1, v182 op_sel_hi:[0,0,0]
	v_mfma_scale_f32_16x16x128_f8f6f4 v[98:101], v[10:17], v[210:217], v[98:101], v1, v182 op_sel_hi:[0,0,0]
.Lcy5_0j:
	s_setprio 0
	s_barrier
	s_add_i32 s83, s63, s45
	v_lshl_add_u64 v[174:175], s[34:35], 0, v[164:165]
	s_mov_b32 m0, s83
	ds_read_b128 v[194:197], v191 offset:16384
	ds_read_b128 v[202:205], v191 offset:18432
	ds_read_b128 v[198:201], v192 offset:16384
	ds_read_b128 v[206:209], v192 offset:18432
	ds_read_b128 v[210:213], v191 offset:20480
	ds_read_b128 v[218:221], v191 offset:22528
	ds_read_b128 v[214:217], v192 offset:20480
	ds_read_b128 v[222:225], v192 offset:22528
	global_load_lds_dwordx4 v[174:175], off
	s_add_i32 m0, s83, 0x2000
	s_add_u32 s84, s34, 0xb0000
	v_lshl_add_u64 v[176:177], s[34:35], 0, v[168:169]
	s_addc_u32 s85, s35, 0
	s_add_i32 s83, s64, s45
	global_load_lds_dwordx4 v[176:177], off
	v_lshl_add_u64 v[178:179], s[84:85], 0, v[164:165]
	s_mov_b32 m0, s83
	v_lshl_add_u64 v[180:181], s[40:41], 0, v[166:167]
	global_load_lds_dwordx4 v[178:179], off
	v_lshl_add_u64 v[178:179], s[84:85], 0, v[168:169]
	s_add_i32 m0, s83, 0x2000
	s_nop 0
	global_load_lds_dwordx4 v[178:179], off
	v_lshl_add_u64 v[178:179], s[40:41], 0, v[162:163]
	s_mov_b32 m0, s52
	s_nop 0
	global_load_lds_dwordx4 v[178:179], off
	s_mov_b32 m0, s53
	s_nop 0
	global_load_lds_dwordx4 v[180:181], off
	s_waitcnt vmcnt(8)
	s_waitcnt lgkmcnt(0)
	s_barrier
	s_setprio 1
	s_waitcnt lgkmcnt(0)
	s_cmp_eq_u32 s100, 1
	s_cbranch_scc1 .Lcy5_1f
	v_mfma_scale_f32_16x16x128_f8f6f4 v[94:97], v[18:25], v[194:201], v[94:97], v1, v182 op_sel_hi:[0,0,0]
	v_mfma_scale_f32_16x16x128_f8f6f4 v[90:93], v[26:33], v[194:201], v[90:93], v1, v182 op_sel_hi:[0,0,0]
	v_mfma_scale_f32_16x16x128_f8f6f4 v[82:85], v[18:25], v[202:209], v[82:85], v1, v182 op_sel_hi:[0,0,0]
	v_mfma_scale_f32_16x16x128_f8f6f4 v[74:77], v[26:33], v[202:209], v[74:77], v1, v182 op_sel_hi:[0,0,0]
	v_mfma_scale_f32_16x16x128_f8f6f4 v[66:69], v[18:25], v[210:217], v[66:69], v1, v182 op_sel_hi:[0,0,0]
	v_mfma_scale_f32_16x16x128_f8f6f4 v[58:61], v[26:33], v[210:217], v[58:61], v1, v182 op_sel_hi:[0,0,0]
	v_mfma_scale_f32_16x16x128_f8f6f4 v[50:53], v[18:25], v[218:225], v[50:53], v1, v182 op_sel_hi:[0,0,0]
	v_mfma_scale_f32_16x16x128_f8f6f4 v[42:45], v[26:33], v[218:225], v[42:45], v1, v182 op_sel_hi:[0,0,0]
	s_setprio 0
	s_setprio 1
	v_mfma_scale_f32_16x16x128_f8f6f4 v[86:89], v[2:9], v[194:201], v[86:89], v1, v182 op_sel_hi:[0,0,0]
	v_mfma_scale_f32_16x16x128_f8f6f4 v[78:81], v[10:17], v[194:201], v[78:81], v1, v182 op_sel_hi:[0,0,0]
	v_mfma_scale_f32_16x16x128_f8f6f4 v[70:73], v[2:9], v[202:209], v[70:73], v1, v182 op_sel_hi:[0,0,0]
	v_mfma_scale_f32_16x16x128_f8f6f4 v[62:65], v[10:17], v[202:209], v[62:65], v1, v182 op_sel_hi:[0,0,0]
	v_mfma_scale_f32_16x16x128_f8f6f4 v[54:57], v[2:9], v[210:217], v[54:57], v1, v182 op_sel_hi:[0,0,0]
	v_mfma_scale_f32_16x16x128_f8f6f4 v[46:49], v[10:17], v[210:217], v[46:49], v1, v182 op_sel_hi:[0,0,0]
	v_mfma_scale_f32_16x16x128_f8f6f4 v[38:41], v[2:9], v[218:225], v[38:41], v1, v182 op_sel_hi:[0,0,0]
	v_mfma_scale_f32_16x16x128_f8f6f4 v[34:37], v[10:17], v[218:225], v[34:37], v1, v182 op_sel_hi:[0,0,0]
; #define PG8_STAGE(bufoff, gbase, voff) do { _Pragma("unroll") for (int _i = 0; _i < 2; ++_i) \
;         __builtin_amdgcn_global_load_lds((const unsigned*)((const char*)(gbase) + (voff)[_i]), (PG8_LAS unsigned*)(lds + (bufoff) + ldsw + _i * 8192), 16, 0, 0); } while (0)
; #define PG8_LDA(dst, b, h) do { _Pragma("unroll") for (int m = 0; m < 4; ++m) _Pragma("unroll") for (int k = 0; k < 2; ++k) dst[m][k] = *(const PG8_LAS bf16x8*)(lds + PG8_SA(b, h) + aoff + m * 2048 + k * 1024); } while (0)
; #define PG8_LDB(dst, b, h) do { _Pragma("unroll") for (int n = 0; n < 2; ++n) _Pragma("unroll") for (int k = 0; k < 2; ++k) dst[n][k] = *(const PG8_LAS bf16x8*)(lds + PG8_SB(b, h) + boff + n * 2048 + k * 1024); } while (0)
; #define PG8_MMA(ai, bj, At, Bt) do { __builtin_amdgcn_s_setprio(1); _Pragma("unroll") for (int m = 0; m < 4; ++m) _Pragma("unroll") for (int n = 0; n < 2; ++n) _Pragma("unroll") for (int k = 0; k < 2; ++k) \
;         acc[ai][bj][m][n] = __builtin_amdgcn_mfma_f32_16x16x32_bf16(Bt[n][k], At[m][k], acc[ai][bj][m][n], 0, 0, 0); __builtin_amdgcn_s_setprio(0); } while (0)
; #define PG8_WAIT_V(n) asm volatile("s_waitcnt vmcnt(" #n ")" ::: "memory")
; #define PG8_WAIT_L(n) asm volatile("s_waitcnt lgkmcnt(" #n ")" ::: "memory")
; #define PG8_BAR __builtin_amdgcn_s_barrier()
; #define PG8_SCHED __builtin_amdgcn_sched_barrier(0)
; #define PG8_STAGE(bufoff, gbase, voff) do { _Pragma("unroll") for (int _i = 0; _i < 2; ++_i) \
;         __builtin_amdgcn_global_load_lds((const unsigned*)((const char*)(gbase) + (voff)[_i]), (PG8_LAS unsigned*)(lds + (bufoff) + ldsw + _i * 8192), 16, 0, 0); } while (0)
; #define PG8_BAR __builtin_amdgcn_s_barrier()
; template <class Epi, class Sched, bool ALIGN_EPI = false>
; __device__ __forceinline__ void gemm_phase8(PG8_LAS unsigned char* lds, const Gemm g, const Sched& S, const Epi& E) {
;     ...
;             PG8_LDB(B0, 1, 0); PG8_LDB(B1, 1, 1); PG8_SCHED; PG8_LDA(At, 1, 0); PG8_STAGE(PG8_SA(0, 1), a2 + hstepA, voffA);
;             PG8_WAIT_V(8); PG8_WAIT_L(0); PG8_BAR; PG8_MMA(0, 0, At, B0); PG8_MMA(0, 1, At, B1); PG8_BAR; PG8_SCHED;
;             PG8_LDA(At, 1, 1); PG8_STAGE(PG8_SB(1, 0), b3, voffB); PG8_STAGE(PG8_SB(1, 1), b3 + hstepB, voffB); PG8_STAGE(PG8_SA(1, 0), a3, voffA);
;             PG8_WAIT_V(8); PG8_WAIT_L(0); PG8_BAR; PG8_MMA(1, 0, At, B0); PG8_MMA(1, 1, At, B1); PG8_BAR; PG8_SCHED;
;         }
.Lcy5_1j:
	s_setprio 0
	s_barrier
	s_add_i32 s83, 0, 0x18000
	s_add_i32 s84, 0, 0x1c000
	v_add_u32_e32 v6, s83, v184
	v_add_u32_e32 v14, s83, v185
	v_add_u32_e32 v22, s84, v184
	v_add_u32_e32 v30, s84, v185
	ds_read_b128 v[2:5], v6
	ds_read_b128 v[10:13], v6 offset:2048
	ds_read_b128 v[6:9], v14
	ds_read_b128 v[14:17], v14 offset:2048
	ds_read_b128 v[18:21], v22
	ds_read_b128 v[26:29], v22 offset:2048
	ds_read_b128 v[22:25], v30
	ds_read_b128 v[30:33], v30 offset:2048
	s_add_u32 s40, s40, 0xb0000
	s_addc_u32 s41, s41, 0
	s_mov_b32 m0, s54
	v_lshl_add_u64 v[226:227], s[40:41], 0, v[162:163]
	ds_read_b128 v[194:197], v191 offset:32768
	ds_read_b128 v[202:205], v191 offset:34816
	ds_read_b128 v[198:201], v192 offset:32768
	ds_read_b128 v[206:209], v192 offset:34816
	ds_read_b128 v[210:213], v191 offset:36864
	ds_read_b128 v[218:221], v191 offset:38912
	ds_read_b128 v[214:217], v192 offset:36864
	ds_read_b128 v[222:225], v192 offset:38912
	global_load_lds_dwordx4 v[226:227], off
	v_lshl_add_u64 v[226:227], s[40:41], 0, v[166:167]
	s_mov_b32 m0, s55
	s_nop 0
	global_load_lds_dwordx4 v[226:227], off
	s_waitcnt vmcnt(8)
	s_waitcnt lgkmcnt(0)
	s_barrier
	s_setprio 1
	s_waitcnt lgkmcnt(0)
	v_mfma_scale_f32_16x16x128_f8f6f4 v[158:161], v[2:9], v[194:201], v[158:161], v1, v182 op_sel_hi:[0,0,0]
	v_mfma_scale_f32_16x16x128_f8f6f4 v[154:157], v[10:17], v[194:201], v[154:157], v1, v182 op_sel_hi:[0,0,0]
	v_mfma_scale_f32_16x16x128_f8f6f4 v[150:153], v[2:9], v[202:209], v[150:153], v1, v182 op_sel_hi:[0,0,0]
	v_mfma_scale_f32_16x16x128_f8f6f4 v[138:141], v[10:17], v[202:209], v[138:141], v1, v182 op_sel_hi:[0,0,0]
	v_mfma_scale_f32_16x16x128_f8f6f4 v[130:133], v[2:9], v[210:217], v[130:133], v1, v182 op_sel_hi:[0,0,0]
	v_mfma_scale_f32_16x16x128_f8f6f4 v[122:125], v[10:17], v[210:217], v[122:125], v1, v182 op_sel_hi:[0,0,0]
	v_mfma_scale_f32_16x16x128_f8f6f4 v[118:121], v[2:9], v[218:225], v[118:121], v1, v182 op_sel_hi:[0,0,0]
	v_mfma_scale_f32_16x16x128_f8f6f4 v[106:109], v[10:17], v[218:225], v[106:109], v1, v182 op_sel_hi:[0,0,0]
	s_setprio 0
	s_setprio 1
	v_mfma_scale_f32_16x16x128_f8f6f4 v[146:149], v[18:25], v[194:201], v[146:149], v1, v182 op_sel_hi:[0,0,0]
	v_mfma_scale_f32_16x16x128_f8f6f4 v[142:145], v[26:33], v[194:201], v[142:145], v1, v182 op_sel_hi:[0,0,0]
	v_mfma_scale_f32_16x16x128_f8f6f4 v[134:137], v[18:25], v[202:209], v[134:137], v1, v182 op_sel_hi:[0,0,0]
	v_mfma_scale_f32_16x16x128_f8f6f4 v[126:129], v[26:33], v[202:209], v[126:129], v1, v182 op_sel_hi:[0,0,0]
	v_mfma_scale_f32_16x16x128_f8f6f4 v[114:117], v[18:25], v[210:217], v[114:117], v1, v182 op_sel_hi:[0,0,0]
	v_mfma_scale_f32_16x16x128_f8f6f4 v[110:113], v[26:33], v[210:217], v[110:113], v1, v182 op_sel_hi:[0,0,0]
	v_mfma_scale_f32_16x16x128_f8f6f4 v[102:105], v[18:25], v[218:225], v[102:105], v1, v182 op_sel_hi:[0,0,0]
	v_mfma_scale_f32_16x16x128_f8f6f4 v[98:101], v[26:33], v[218:225], v[98:101], v1, v182 op_sel_hi:[0,0,0]
	s_setprio 0
	s_barrier
	s_add_i32 s40, s83, s45
	v_lshl_add_u64 v[174:175], v[174:175], 0, s[12:13]
	s_mov_b32 m0, s40
	ds_read_b128 v[194:197], v191 offset:49152
	ds_read_b128 v[202:205], v191 offset:51200
	ds_read_b128 v[198:201], v192 offset:49152
	ds_read_b128 v[206:209], v192 offset:51200
	ds_read_b128 v[210:213], v191 offset:53248
	ds_read_b128 v[218:221], v191 offset:55296
	ds_read_b128 v[214:217], v192 offset:53248
	ds_read_b128 v[222:225], v192 offset:55296
	global_load_lds_dwordx4 v[174:175], off
	s_add_i32 m0, s40, 0x2000
	s_add_u32 s34, s34, 0xb0080
	v_lshl_add_u64 v[174:175], v[176:177], 0, s[12:13]
	s_addc_u32 s35, s35, 0
	s_add_i32 s40, s84, s45
	global_load_lds_dwordx4 v[174:175], off
	v_lshl_add_u64 v[174:175], s[34:35], 0, v[164:165]
	s_mov_b32 m0, s40
	s_nop 0
	global_load_lds_dwordx4 v[174:175], off
	v_lshl_add_u64 v[174:175], s[34:35], 0, v[168:169]
	s_add_i32 m0, s40, 0x2000
	s_nop 0
	global_load_lds_dwordx4 v[174:175], off
	v_lshl_add_u64 v[174:175], v[178:179], 0, s[12:13]
	s_mov_b32 m0, s61
	s_nop 0
	global_load_lds_dwordx4 v[174:175], off
	v_lshl_add_u64 v[174:175], v[180:181], 0, s[12:13]
	s_mov_b32 m0, s62
	s_nop 0
	global_load_lds_dwordx4 v[174:175], off
	s_waitcnt vmcnt(8)
	s_waitcnt lgkmcnt(0)
	s_barrier
	s_setprio 1
	s_waitcnt lgkmcnt(0)
	v_mfma_scale_f32_16x16x128_f8f6f4 v[94:97], v[2:9], v[194:201], v[94:97], v1, v182 op_sel_hi:[0,0,0]
	v_mfma_scale_f32_16x16x128_f8f6f4 v[90:93], v[10:17], v[194:201], v[90:93], v1, v182 op_sel_hi:[0,0,0]
	v_mfma_scale_f32_16x16x128_f8f6f4 v[82:85], v[2:9], v[202:209], v[82:85], v1, v182 op_sel_hi:[0,0,0]
	v_mfma_scale_f32_16x16x128_f8f6f4 v[74:77], v[10:17], v[202:209], v[74:77], v1, v182 op_sel_hi:[0,0,0]
	v_mfma_scale_f32_16x16x128_f8f6f4 v[66:69], v[2:9], v[210:217], v[66:69], v1, v182 op_sel_hi:[0,0,0]
	v_mfma_scale_f32_16x16x128_f8f6f4 v[58:61], v[10:17], v[210:217], v[58:61], v1, v182 op_sel_hi:[0,0,0]
	v_mfma_scale_f32_16x16x128_f8f6f4 v[50:53], v[2:9], v[218:225], v[50:53], v1, v182 op_sel_hi:[0,0,0]
	v_mfma_scale_f32_16x16x128_f8f6f4 v[42:45], v[10:17], v[218:225], v[42:45], v1, v182 op_sel_hi:[0,0,0]
	s_setprio 0
	s_setprio 1
	v_mfma_scale_f32_16x16x128_f8f6f4 v[86:89], v[18:25], v[194:201], v[86:89], v1, v182 op_sel_hi:[0,0,0]
	v_mfma_scale_f32_16x16x128_f8f6f4 v[78:81], v[26:33], v[194:201], v[78:81], v1, v182 op_sel_hi:[0,0,0]
	v_mfma_scale_f32_16x16x128_f8f6f4 v[70:73], v[18:25], v[202:209], v[70:73], v1, v182 op_sel_hi:[0,0,0]
	v_mfma_scale_f32_16x16x128_f8f6f4 v[62:65], v[26:33], v[202:209], v[62:65], v1, v182 op_sel_hi:[0,0,0]
	v_mfma_scale_f32_16x16x128_f8f6f4 v[54:57], v[18:25], v[210:217], v[54:57], v1, v182 op_sel_hi:[0,0,0]
	v_mfma_scale_f32_16x16x128_f8f6f4 v[46:49], v[26:33], v[210:217], v[46:49], v1, v182 op_sel_hi:[0,0,0]
	v_mfma_scale_f32_16x16x128_f8f6f4 v[38:41], v[18:25], v[218:225], v[38:41], v1, v182 op_sel_hi:[0,0,0]
	v_mfma_scale_f32_16x16x128_f8f6f4 v[34:37], v[26:33], v[218:225], v[34:37], v1, v182 op_sel_hi:[0,0,0]
	s_setprio 0
	s_barrier
	s_add_u32 s38, s38, 0x100
	s_addc_u32 s39, s39, 0
	s_add_u32 s80, s80, 0x100
	s_addc_u32 s81, s81, 0
	s_cmp_ge_u32 s82, s31
	s_mov_b32 s40, s82
	s_cbranch_scc0 .LBB0_1511
	s_and_b64 vcc, exec, s[14:15]
	s_cbranch_vccz .LBB0_1514
	s_barrier
